# GEMM K-loops: 8 of 16 LDS-DMAs per iteration in saddr form (64-bit VALU address adds removed), on the attention LDS-DMA version
# baseline (speedup 1.0000x reference)
; #define PG8_STAGE(bufoff, gbase, voff) do { _Pragma("unroll") for (int _i = 0; _i < 2; ++_i) \
;         __builtin_amdgcn_global_load_lds((const unsigned*)((const char*)(gbase) + (voff)[_i]), (PG8_LAS unsigned*)(lds + (bufoff) + ldsw + _i * 8192), 16, 0, 0); } while (0)
; #define PG8_LDA(dst, b, h) do { _Pragma("unroll") for (int m = 0; m < 4; ++m) _Pragma("unroll") for (int k = 0; k < 2; ++k) dst[m][k] = *(const PG8_LAS bf16x8*)(lds + PG8_SA(b, h) + aoff + m * 2048 + k * 1024); } while (0)
; #define PG8_LDB(dst, b, h) do { _Pragma("unroll") for (int n = 0; n < 2; ++n) _Pragma("unroll") for (int k = 0; k < 2; ++k) dst[n][k] = *(const PG8_LAS bf16x8*)(lds + PG8_SB(b, h) + boff + n * 2048 + k * 1024); } while (0)
; #define PG8_MMA(ai, bj, At, Bt) do { __builtin_amdgcn_s_setprio(1); _Pragma("unroll") for (int m = 0; m < 4; ++m) _Pragma("unroll") for (int n = 0; n < 2; ++n) _Pragma("unroll") for (int k = 0; k < 2; ++k) \
;         acc[ai][bj][m][n] = __builtin_amdgcn_mfma_f32_16x16x32_bf16(Bt[n][k], At[m][k], acc[ai][bj][m][n], 0, 0, 0); __builtin_amdgcn_s_setprio(0); } while (0)
; #define PG8_WAIT_V(n) asm volatile("s_waitcnt vmcnt(" #n ")" ::: "memory")
; #define PG8_WAIT_L(n) asm volatile("s_waitcnt lgkmcnt(" #n ")" ::: "memory")
; #define PG8_BAR __builtin_amdgcn_s_barrier()
; #define PG8_SCHED __builtin_amdgcn_sched_barrier(0)
; template <class Epi, class Sched, bool ALIGN_EPI = false, bool SP2 = false>
; __device__ __forceinline__ void gemm_phase(PG8_LAS unsigned char* lds, const Gemm g, const Sched& S, const Epi& E) {
;     ...
;             PG8_LDB(B0, 0, 0); PG8_LDB(B1, 0, 1); PG8_SCHED; PG8_LDA(At, 0, 0); PG8_STAGE(PG8_SA(1, 1), a1 + hstep, voffA);
;             PG8_WAIT_V(8); PG8_WAIT_L(0); PG8_BAR; PG8_MMA(0, 0, At, B0); PG8_MMA(0, 1, At, B1); PG8_BAR; PG8_SCHED;
;             PG8_LDA(At, 0, 1); PG8_STAGE(PG8_SB(0, 0), b2, voffB); PG8_STAGE(PG8_SB(0, 1), b2 + hstep, voffB); PG8_STAGE(PG8_SA(0, 0), a2, voffA);
;             PG8_WAIT_V(8); PG8_WAIT_L(0); PG8_BAR; PG8_MMA(1, 0, At, B0); PG8_MMA(1, 1, At, B1); PG8_BAR; PG8_SCHED;
.LBB0_96:
	ds_read_b128 v[128:131], v178
	ds_read_b128 v[132:135], v178 offset:1024
	ds_read_b128 v[136:139], v178 offset:2048
	ds_read_b128 v[140:143], v178 offset:3072
	ds_read_b128 v[166:169], v179
	ds_read_b128 v[170:173], v179 offset:1024
	ds_read_b128 v[190:193], v179 offset:2048
	ds_read_b128 v[194:197], v179 offset:3072
	s_add_u32 s36, s80, 0xfffc0080
	s_addc_u32 s37, s81, -1
	s_cmp_eq_u32 s35, 12
	s_cselect_b32 s87, s8, s37
	s_cselect_b32 s86, s55, s36
	s_cselect_b32 s83, s49, s34
	s_cselect_b32 s82, vcc_lo, vcc_hi
	s_add_i32 m0, s93, 0xc000
	ds_read_b128 v[198:201], v181
	ds_read_b128 v[202:205], v181 offset:1024
	ds_read_b128 v[206:209], v181 offset:2048
	ds_read_b128 v[210:213], v181 offset:3072
	ds_read_b128 v[214:217], v181 offset:4096
	ds_read_b128 v[218:221], v181 offset:5120
	ds_read_b128 v[222:225], v181 offset:6144
	ds_read_b128 v[226:229], v181 offset:7168
	global_load_lds_dwordx4 v158, s[80:81]
	s_add_i32 m0, s93, 0xe000
	s_nop 0
	global_load_lds_dwordx4 v160, s[80:81]
	s_waitcnt vmcnt(8)
	s_waitcnt lgkmcnt(0)
	s_barrier
	s_setprio 1
	s_waitcnt lgkmcnt(0)
	v_mfma_f32_16x16x32_bf16 v[124:127], v[128:131], v[198:201], v[124:127]
	v_mfma_f32_16x16x32_bf16 v[120:123], v[136:139], v[198:201], v[120:123]
	v_mfma_f32_16x16x32_bf16 v[108:111], v[128:131], v[206:209], v[108:111]
	v_mfma_f32_16x16x32_bf16 v[104:107], v[136:139], v[206:209], v[104:107]
	v_mfma_f32_16x16x32_bf16 v[92:95], v[128:131], v[214:217], v[92:95]
	v_mfma_f32_16x16x32_bf16 v[88:91], v[136:139], v[214:217], v[88:91]
	v_mfma_f32_16x16x32_bf16 v[76:79], v[128:131], v[222:225], v[76:79]
	v_mfma_f32_16x16x32_bf16 v[72:75], v[136:139], v[222:225], v[72:75]
	v_mfma_f32_16x16x32_bf16 v[124:127], v[132:135], v[202:205], v[124:127]
	v_mfma_f32_16x16x32_bf16 v[120:123], v[140:143], v[202:205], v[120:123]
	v_mfma_f32_16x16x32_bf16 v[108:111], v[132:135], v[210:213], v[108:111]
	v_mfma_f32_16x16x32_bf16 v[104:107], v[140:143], v[210:213], v[104:107]
	v_mfma_f32_16x16x32_bf16 v[92:95], v[132:135], v[218:221], v[92:95]
	v_mfma_f32_16x16x32_bf16 v[88:91], v[140:143], v[218:221], v[88:91]
	v_mfma_f32_16x16x32_bf16 v[76:79], v[132:135], v[226:229], v[76:79]
	v_mfma_f32_16x16x32_bf16 v[72:75], v[140:143], v[226:229], v[72:75]
	s_setprio 0
	s_setprio 1
	v_mfma_f32_16x16x32_bf16 v[116:119], v[166:169], v[198:201], v[116:119]
	v_mfma_f32_16x16x32_bf16 v[112:115], v[190:193], v[198:201], v[112:115]
	v_mfma_f32_16x16x32_bf16 v[100:103], v[166:169], v[206:209], v[100:103]
	v_mfma_f32_16x16x32_bf16 v[96:99], v[190:193], v[206:209], v[96:99]
	v_mfma_f32_16x16x32_bf16 v[84:87], v[166:169], v[214:217], v[84:87]
	v_mfma_f32_16x16x32_bf16 v[80:83], v[190:193], v[214:217], v[80:83]
	v_mfma_f32_16x16x32_bf16 v[68:71], v[166:169], v[222:225], v[68:71]
	v_mfma_f32_16x16x32_bf16 v[64:67], v[190:193], v[222:225], v[64:67]
	v_mfma_f32_16x16x32_bf16 v[116:119], v[170:173], v[202:205], v[116:119]
	v_mfma_f32_16x16x32_bf16 v[112:115], v[194:197], v[202:205], v[112:115]
	v_mfma_f32_16x16x32_bf16 v[100:103], v[170:173], v[210:213], v[100:103]
	v_mfma_f32_16x16x32_bf16 v[96:99], v[194:197], v[210:213], v[96:99]
	v_mfma_f32_16x16x32_bf16 v[84:87], v[170:173], v[218:221], v[84:87]
	v_mfma_f32_16x16x32_bf16 v[80:83], v[194:197], v[218:221], v[80:83]
	v_mfma_f32_16x16x32_bf16 v[68:71], v[170:173], v[226:229], v[68:71]
	v_mfma_f32_16x16x32_bf16 v[64:67], v[194:197], v[226:229], v[64:67]
	s_setprio 0
	s_barrier
	s_add_i32 s36, s23, s90
	v_lshl_add_u64 v[174:175], s[82:83], 0, v[148:149]
	s_mov_b32 m0, s36
	ds_read_b128 v[198:201], v181 offset:16384
	ds_read_b128 v[202:205], v181 offset:17408
	ds_read_b128 v[206:209], v181 offset:18432
	ds_read_b128 v[210:213], v181 offset:19456
	ds_read_b128 v[214:217], v181 offset:20480
	ds_read_b128 v[218:221], v181 offset:21504
	ds_read_b128 v[222:225], v181 offset:22528
	ds_read_b128 v[226:229], v181 offset:23552
	global_load_lds_dwordx4 v[174:175], off
	s_add_i32 m0, s36, 0x2000
	s_add_u32 s36, s82, 0x40000
	v_lshl_add_u64 v[186:187], s[82:83], 0, v[144:145]
	s_addc_u32 s37, s83, 0
	s_add_i32 s20, s41, s90
	global_load_lds_dwordx4 v[186:187], off
	s_mov_b32 m0, s20
	v_lshl_add_u64 v[232:233], s[86:87], 0, v[146:147]
	global_load_lds_dwordx4 v148, s[36:37]
	s_add_i32 m0, s20, 0x2000
	s_nop 0
	global_load_lds_dwordx4 v144, s[36:37]
	v_lshl_add_u64 v[230:231], s[86:87], 0, v[150:151]
	s_mov_b32 m0, s93
	s_nop 0
	global_load_lds_dwordx4 v[230:231], off
	s_mov_b32 m0, s94
	s_nop 0
	global_load_lds_dwordx4 v[232:233], off
	s_waitcnt vmcnt(8)
	s_waitcnt lgkmcnt(0)
	s_barrier
; #define PG8_STAGE(bufoff, gbase, voff) do { _Pragma("unroll") for (int _i = 0; _i < 2; ++_i) \
;         __builtin_amdgcn_global_load_lds((const unsigned*)((const char*)(gbase) + (voff)[_i]), (PG8_LAS unsigned*)(lds + (bufoff) + ldsw + _i * 8192), 16, 0, 0); } while (0)
; #define PG8_LDA(dst, b, h) do { _Pragma("unroll") for (int m = 0; m < 4; ++m) _Pragma("unroll") for (int k = 0; k < 2; ++k) dst[m][k] = *(const PG8_LAS bf16x8*)(lds + PG8_SA(b, h) + aoff + m * 2048 + k * 1024); } while (0)
; #define PG8_LDB(dst, b, h) do { _Pragma("unroll") for (int n = 0; n < 2; ++n) _Pragma("unroll") for (int k = 0; k < 2; ++k) dst[n][k] = *(const PG8_LAS bf16x8*)(lds + PG8_SB(b, h) + boff + n * 2048 + k * 1024); } while (0)
; #define PG8_MMA(ai, bj, At, Bt) do { __builtin_amdgcn_s_setprio(1); _Pragma("unroll") for (int m = 0; m < 4; ++m) _Pragma("unroll") for (int n = 0; n < 2; ++n) _Pragma("unroll") for (int k = 0; k < 2; ++k) \
;         acc[ai][bj][m][n] = __builtin_amdgcn_mfma_f32_16x16x32_bf16(Bt[n][k], At[m][k], acc[ai][bj][m][n], 0, 0, 0); __builtin_amdgcn_s_setprio(0); } while (0)
; #define PG8_WAIT_V(n) asm volatile("s_waitcnt vmcnt(" #n ")" ::: "memory")
; #define PG8_WAIT_L(n) asm volatile("s_waitcnt lgkmcnt(" #n ")" ::: "memory")
; #define PG8_BAR __builtin_amdgcn_s_barrier()
; #define PG8_SCHED __builtin_amdgcn_sched_barrier(0)
; template <class Epi, class Sched, bool ALIGN_EPI = false, bool SP2 = false>
; __device__ __forceinline__ void gemm_phase(PG8_LAS unsigned char* lds, const Gemm g, const Sched& S, const Epi& E) {
;     ...
;             PG8_WAIT_V(8); PG8_WAIT_L(0); PG8_BAR; PG8_MMA(1, 0, At, B0); PG8_MMA(1, 1, At, B1); PG8_BAR; PG8_SCHED;
;             PG8_LDB(B0, 1, 0); PG8_LDB(B1, 1, 1); PG8_SCHED; PG8_LDA(At, 1, 0); PG8_STAGE(PG8_SA(0, 1), a2 + hstep, voffA);
;             PG8_WAIT_V(8); PG8_WAIT_L(0); PG8_BAR; PG8_MMA(0, 0, At, B0); PG8_MMA(0, 1, At, B1); PG8_BAR; PG8_SCHED;
	s_setprio 1
	s_waitcnt lgkmcnt(0)
	v_mfma_f32_16x16x32_bf16 v[60:63], v[128:131], v[198:201], v[60:63]
	v_mfma_f32_16x16x32_bf16 v[56:59], v[136:139], v[198:201], v[56:59]
	v_mfma_f32_16x16x32_bf16 v[44:47], v[128:131], v[206:209], v[44:47]
	v_mfma_f32_16x16x32_bf16 v[40:43], v[136:139], v[206:209], v[40:43]
	v_mfma_f32_16x16x32_bf16 v[28:31], v[128:131], v[214:217], v[28:31]
	v_mfma_f32_16x16x32_bf16 v[24:27], v[136:139], v[214:217], v[24:27]
	v_mfma_f32_16x16x32_bf16 v[12:15], v[128:131], v[222:225], v[12:15]
	v_mfma_f32_16x16x32_bf16 v[8:11], v[136:139], v[222:225], v[8:11]
	v_mfma_f32_16x16x32_bf16 v[60:63], v[132:135], v[202:205], v[60:63]
	v_mfma_f32_16x16x32_bf16 v[56:59], v[140:143], v[202:205], v[56:59]
	v_mfma_f32_16x16x32_bf16 v[44:47], v[132:135], v[210:213], v[44:47]
	v_mfma_f32_16x16x32_bf16 v[40:43], v[140:143], v[210:213], v[40:43]
	v_mfma_f32_16x16x32_bf16 v[28:31], v[132:135], v[218:221], v[28:31]
	v_mfma_f32_16x16x32_bf16 v[24:27], v[140:143], v[218:221], v[24:27]
	v_mfma_f32_16x16x32_bf16 v[12:15], v[132:135], v[226:229], v[12:15]
	v_mfma_f32_16x16x32_bf16 v[8:11], v[140:143], v[226:229], v[8:11]
	s_setprio 0
	s_setprio 1
	v_mfma_f32_16x16x32_bf16 v[52:55], v[166:169], v[198:201], v[52:55]
	v_mfma_f32_16x16x32_bf16 v[48:51], v[190:193], v[198:201], v[48:51]
	v_mfma_f32_16x16x32_bf16 v[36:39], v[166:169], v[206:209], v[36:39]
	v_mfma_f32_16x16x32_bf16 v[32:35], v[190:193], v[206:209], v[32:35]
	v_mfma_f32_16x16x32_bf16 v[20:23], v[166:169], v[214:217], v[20:23]
	v_mfma_f32_16x16x32_bf16 v[16:19], v[190:193], v[214:217], v[16:19]
	v_mfma_f32_16x16x32_bf16 v[4:7], v[166:169], v[222:225], v[4:7]
	v_mfma_f32_16x16x32_bf16 v[0:3], v[190:193], v[222:225], v[0:3]
	v_mfma_f32_16x16x32_bf16 v[52:55], v[170:173], v[202:205], v[52:55]
	v_mfma_f32_16x16x32_bf16 v[48:51], v[194:197], v[202:205], v[48:51]
	v_mfma_f32_16x16x32_bf16 v[36:39], v[170:173], v[210:213], v[36:39]
	v_mfma_f32_16x16x32_bf16 v[32:35], v[194:197], v[210:213], v[32:35]
	v_mfma_f32_16x16x32_bf16 v[20:23], v[170:173], v[218:221], v[20:23]
	v_mfma_f32_16x16x32_bf16 v[16:19], v[194:197], v[218:221], v[16:19]
	v_mfma_f32_16x16x32_bf16 v[4:7], v[170:173], v[226:229], v[4:7]
	v_mfma_f32_16x16x32_bf16 v[0:3], v[194:197], v[226:229], v[0:3]
	s_setprio 0
	s_barrier
	s_add_i32 s20, 0, 0x18000
	s_add_i32 s21, 0, 0x1c000
	v_add_u32_e32 v140, s20, v176
	v_add_u32_e32 v152, s21, v176
	ds_read_b128 v[128:131], v140
	ds_read_b128 v[132:135], v140 offset:1024
	ds_read_b128 v[136:139], v140 offset:2048
	ds_read_b128 v[140:143], v140 offset:3072
	ds_read_b128 v[166:169], v152
	ds_read_b128 v[170:173], v152 offset:1024
	ds_read_b128 v[190:193], v152 offset:2048
	ds_read_b128 v[194:197], v152 offset:3072
	s_add_u32 s36, s86, 0x40000
	s_addc_u32 s37, s87, 0
	s_mov_b32 m0, s95
	ds_read_b128 v[198:201], v181 offset:32768
	ds_read_b128 v[202:205], v181 offset:33792
	ds_read_b128 v[206:209], v181 offset:34816
	ds_read_b128 v[210:213], v181 offset:35840
	ds_read_b128 v[214:217], v181 offset:36864
	ds_read_b128 v[218:221], v181 offset:37888
	ds_read_b128 v[222:225], v181 offset:38912
	ds_read_b128 v[226:229], v181 offset:39936
	global_load_lds_dwordx4 v150, s[36:37]
	s_mov_b32 m0, s97
	s_nop 0
	global_load_lds_dwordx4 v146, s[36:37]
	s_waitcnt vmcnt(8)
	s_waitcnt lgkmcnt(0)
	s_barrier
	s_setprio 1
	s_waitcnt lgkmcnt(0)
	v_mfma_f32_16x16x32_bf16 v[124:127], v[128:131], v[198:201], v[124:127]
	v_mfma_f32_16x16x32_bf16 v[120:123], v[136:139], v[198:201], v[120:123]
	v_mfma_f32_16x16x32_bf16 v[108:111], v[128:131], v[206:209], v[108:111]
	v_mfma_f32_16x16x32_bf16 v[104:107], v[136:139], v[206:209], v[104:107]
	v_mfma_f32_16x16x32_bf16 v[92:95], v[128:131], v[214:217], v[92:95]
	v_mfma_f32_16x16x32_bf16 v[88:91], v[136:139], v[214:217], v[88:91]
	v_mfma_f32_16x16x32_bf16 v[76:79], v[128:131], v[222:225], v[76:79]
	v_mfma_f32_16x16x32_bf16 v[72:75], v[136:139], v[222:225], v[72:75]
	v_mfma_f32_16x16x32_bf16 v[124:127], v[132:135], v[202:205], v[124:127]
	v_mfma_f32_16x16x32_bf16 v[120:123], v[140:143], v[202:205], v[120:123]
	v_mfma_f32_16x16x32_bf16 v[108:111], v[132:135], v[210:213], v[108:111]
	v_mfma_f32_16x16x32_bf16 v[104:107], v[140:143], v[210:213], v[104:107]
	v_mfma_f32_16x16x32_bf16 v[92:95], v[132:135], v[218:221], v[92:95]
	v_mfma_f32_16x16x32_bf16 v[88:91], v[140:143], v[218:221], v[88:91]
	v_mfma_f32_16x16x32_bf16 v[76:79], v[132:135], v[226:229], v[76:79]
	v_mfma_f32_16x16x32_bf16 v[72:75], v[140:143], v[226:229], v[72:75]
	s_setprio 0
	s_setprio 1
	v_mfma_f32_16x16x32_bf16 v[116:119], v[166:169], v[198:201], v[116:119]
	v_mfma_f32_16x16x32_bf16 v[112:115], v[190:193], v[198:201], v[112:115]
	v_mfma_f32_16x16x32_bf16 v[100:103], v[166:169], v[206:209], v[100:103]
	v_mfma_f32_16x16x32_bf16 v[96:99], v[190:193], v[206:209], v[96:99]
	v_mfma_f32_16x16x32_bf16 v[84:87], v[166:169], v[214:217], v[84:87]
	v_mfma_f32_16x16x32_bf16 v[80:83], v[190:193], v[214:217], v[80:83]
	v_mfma_f32_16x16x32_bf16 v[68:71], v[166:169], v[222:225], v[68:71]
	v_mfma_f32_16x16x32_bf16 v[64:67], v[190:193], v[222:225], v[64:67]
	v_mfma_f32_16x16x32_bf16 v[116:119], v[170:173], v[202:205], v[116:119]
	v_mfma_f32_16x16x32_bf16 v[112:115], v[194:197], v[202:205], v[112:115]
	v_mfma_f32_16x16x32_bf16 v[100:103], v[170:173], v[210:213], v[100:103]
	v_mfma_f32_16x16x32_bf16 v[96:99], v[194:197], v[210:213], v[96:99]
	v_mfma_f32_16x16x32_bf16 v[84:87], v[170:173], v[218:221], v[84:87]
	v_mfma_f32_16x16x32_bf16 v[80:83], v[194:197], v[218:221], v[80:83]
	v_mfma_f32_16x16x32_bf16 v[68:71], v[170:173], v[226:229], v[68:71]
	v_mfma_f32_16x16x32_bf16 v[64:67], v[194:197], v[226:229], v[64:67]
	s_setprio 0
	s_barrier
; #define PG8_STAGE(bufoff, gbase, voff) do { _Pragma("unroll") for (int _i = 0; _i < 2; ++_i) \
;         __builtin_amdgcn_global_load_lds((const unsigned*)((const char*)(gbase) + (voff)[_i]), (PG8_LAS unsigned*)(lds + (bufoff) + ldsw + _i * 8192), 16, 0, 0); } while (0)
; #define PG8_LDA(dst, b, h) do { _Pragma("unroll") for (int m = 0; m < 4; ++m) _Pragma("unroll") for (int k = 0; k < 2; ++k) dst[m][k] = *(const PG8_LAS bf16x8*)(lds + PG8_SA(b, h) + aoff + m * 2048 + k * 1024); } while (0)
; #define PG8_MMA(ai, bj, At, Bt) do { __builtin_amdgcn_s_setprio(1); _Pragma("unroll") for (int m = 0; m < 4; ++m) _Pragma("unroll") for (int n = 0; n < 2; ++n) _Pragma("unroll") for (int k = 0; k < 2; ++k) \
;         acc[ai][bj][m][n] = __builtin_amdgcn_mfma_f32_16x16x32_bf16(Bt[n][k], At[m][k], acc[ai][bj][m][n], 0, 0, 0); __builtin_amdgcn_s_setprio(0); } while (0)
; #define PG8_WAIT_V(n) asm volatile("s_waitcnt vmcnt(" #n ")" ::: "memory")
; #define PG8_WAIT_L(n) asm volatile("s_waitcnt lgkmcnt(" #n ")" ::: "memory")
; #define PG8_BAR __builtin_amdgcn_s_barrier()
; #define PG8_SCHED __builtin_amdgcn_sched_barrier(0)
; template <class Epi, class Sched, bool ALIGN_EPI = false, bool SP2 = false>
; __device__ __forceinline__ void gemm_phase(PG8_LAS unsigned char* lds, const Gemm g, const Sched& S, const Epi& E) {
;     ...
;         for (int t = 0; t < nt; t += 2) {
;             const bool last = (t == nt - 2);
;             const char* a1 = cA + (size_t)(t + 1) * kstep;
;             const char* a2 = last ? nA : cA + (size_t)(t + 2) * kstep; const char* b2 = last ? nB : cB + (size_t)(t + 2) * kstep;
;             const char* a3 = a2 + kstep; const char* b3 = b2 + kstep;
;     ...
;             PG8_LDA(At, 1, 1); PG8_STAGE(PG8_SB(1, 0), b3, voffB); PG8_STAGE(PG8_SB(1, 1), b3 + hstep, voffB); PG8_STAGE(PG8_SA(1, 0), a3, voffA);
;             PG8_WAIT_V(8); PG8_WAIT_L(0); PG8_BAR; PG8_MMA(1, 0, At, B0); PG8_MMA(1, 1, At, B1); PG8_BAR; PG8_SCHED;
	s_add_i32 s20, s20, s90
	v_lshl_add_u64 v[174:175], v[174:175], 0, s[26:27]
	s_mov_b32 m0, s20
	ds_read_b128 v[198:201], v181 offset:49152
	ds_read_b128 v[202:205], v181 offset:50176
	ds_read_b128 v[206:209], v181 offset:51200
	ds_read_b128 v[210:213], v181 offset:52224
	ds_read_b128 v[214:217], v181 offset:53248
	ds_read_b128 v[218:221], v181 offset:54272
	ds_read_b128 v[222:225], v181 offset:55296
	ds_read_b128 v[226:229], v181 offset:56320
	global_load_lds_dwordx4 v[174:175], off
	s_add_i32 m0, s20, 0x2000
	s_add_u32 s36, s82, 0x40080
	v_lshl_add_u64 v[174:175], v[186:187], 0, s[26:27]
	s_addc_u32 s37, s83, 0
	s_add_i32 s20, s21, s90
	global_load_lds_dwordx4 v[174:175], off
	s_mov_b32 m0, s20
	s_nop 0
	global_load_lds_dwordx4 v148, s[36:37]
	s_add_i32 m0, s20, 0x2000
	s_nop 0
	global_load_lds_dwordx4 v144, s[36:37]
	v_lshl_add_u64 v[174:175], v[230:231], 0, s[26:27]
	s_mov_b32 m0, s42
	s_nop 0
	global_load_lds_dwordx4 v[174:175], off
	v_lshl_add_u64 v[174:175], v[232:233], 0, s[26:27]
	s_mov_b32 m0, s43
	s_nop 0
	global_load_lds_dwordx4 v[174:175], off
	s_waitcnt vmcnt(8)
	s_waitcnt lgkmcnt(0)
	s_barrier
	s_setprio 1
	s_waitcnt lgkmcnt(0)
	v_mfma_f32_16x16x32_bf16 v[60:63], v[128:131], v[198:201], v[60:63]
	v_mfma_f32_16x16x32_bf16 v[56:59], v[136:139], v[198:201], v[56:59]
	v_mfma_f32_16x16x32_bf16 v[44:47], v[128:131], v[206:209], v[44:47]
	v_mfma_f32_16x16x32_bf16 v[40:43], v[136:139], v[206:209], v[40:43]
	v_mfma_f32_16x16x32_bf16 v[28:31], v[128:131], v[214:217], v[28:31]
	v_mfma_f32_16x16x32_bf16 v[24:27], v[136:139], v[214:217], v[24:27]
	v_mfma_f32_16x16x32_bf16 v[12:15], v[128:131], v[222:225], v[12:15]
	v_mfma_f32_16x16x32_bf16 v[8:11], v[136:139], v[222:225], v[8:11]
	v_mfma_f32_16x16x32_bf16 v[60:63], v[132:135], v[202:205], v[60:63]
	v_mfma_f32_16x16x32_bf16 v[56:59], v[140:143], v[202:205], v[56:59]
	v_mfma_f32_16x16x32_bf16 v[44:47], v[132:135], v[210:213], v[44:47]
	v_mfma_f32_16x16x32_bf16 v[40:43], v[140:143], v[210:213], v[40:43]
	v_mfma_f32_16x16x32_bf16 v[28:31], v[132:135], v[218:221], v[28:31]
	v_mfma_f32_16x16x32_bf16 v[24:27], v[140:143], v[218:221], v[24:27]
	v_mfma_f32_16x16x32_bf16 v[12:15], v[132:135], v[226:229], v[12:15]
	v_mfma_f32_16x16x32_bf16 v[8:11], v[140:143], v[226:229], v[8:11]
	s_setprio 0
	s_setprio 1
	v_mfma_f32_16x16x32_bf16 v[52:55], v[166:169], v[198:201], v[52:55]
	v_mfma_f32_16x16x32_bf16 v[48:51], v[190:193], v[198:201], v[48:51]
	v_mfma_f32_16x16x32_bf16 v[36:39], v[166:169], v[206:209], v[36:39]
	v_mfma_f32_16x16x32_bf16 v[32:35], v[190:193], v[206:209], v[32:35]
	v_mfma_f32_16x16x32_bf16 v[20:23], v[166:169], v[214:217], v[20:23]
	v_mfma_f32_16x16x32_bf16 v[16:19], v[190:193], v[214:217], v[16:19]
	v_mfma_f32_16x16x32_bf16 v[4:7], v[166:169], v[222:225], v[4:7]
	v_mfma_f32_16x16x32_bf16 v[0:3], v[190:193], v[222:225], v[0:3]
	v_mfma_f32_16x16x32_bf16 v[52:55], v[170:173], v[202:205], v[52:55]
	v_mfma_f32_16x16x32_bf16 v[48:51], v[194:197], v[202:205], v[48:51]
	v_mfma_f32_16x16x32_bf16 v[36:39], v[170:173], v[210:213], v[36:39]
	v_mfma_f32_16x16x32_bf16 v[32:35], v[194:197], v[210:213], v[32:35]
	v_mfma_f32_16x16x32_bf16 v[20:23], v[170:173], v[218:221], v[20:23]
	v_mfma_f32_16x16x32_bf16 v[16:19], v[194:197], v[218:221], v[16:19]
	v_mfma_f32_16x16x32_bf16 v[4:7], v[170:173], v[226:229], v[4:7]
	v_mfma_f32_16x16x32_bf16 v[0:3], v[194:197], v[226:229], v[0:3]
	s_setprio 0
	s_barrier
	s_add_i32 s35, s35, 2
	s_add_u32 s80, s80, 0x100
	s_addc_u32 s81, s81, 0
	s_add_u32 vcc_hi, vcc_hi, 0x100
	s_addc_u32 s34, s34, 0
	s_cmp_gt_u32 s35, 13
	s_cbranch_scc0 .LBB0_96
	s_and_b64 vcc, exec, s[28:29]
	s_cbranch_vccz .LBB0_99
	s_barrier

; #define PG8_STAGE(bufoff, gbase, voff) do { _Pragma("unroll") for (int _i = 0; _i < 2; ++_i) \
;         __builtin_amdgcn_global_load_lds((const unsigned*)((const char*)(gbase) + (voff)[_i]), (PG8_LAS unsigned*)(lds + (bufoff) + ldsw + _i * 8192), 16, 0, 0); } while (0)
; #define PG8_LDA(dst, b, h) do { _Pragma("unroll") for (int m = 0; m < 4; ++m) _Pragma("unroll") for (int k = 0; k < 2; ++k) dst[m][k] = *(const PG8_LAS bf16x8*)(lds + PG8_SA(b, h) + aoff + m * 2048 + k * 1024); } while (0)
; #define PG8_LDB(dst, b, h) do { _Pragma("unroll") for (int n = 0; n < 2; ++n) _Pragma("unroll") for (int k = 0; k < 2; ++k) dst[n][k] = *(const PG8_LAS bf16x8*)(lds + PG8_SB(b, h) + boff + n * 2048 + k * 1024); } while (0)
; #define PG8_MMA(ai, bj, At, Bt) do { __builtin_amdgcn_s_setprio(1); _Pragma("unroll") for (int m = 0; m < 4; ++m) _Pragma("unroll") for (int n = 0; n < 2; ++n) _Pragma("unroll") for (int k = 0; k < 2; ++k) \
;         acc[ai][bj][m][n] = __builtin_amdgcn_mfma_f32_16x16x32_bf16(Bt[n][k], At[m][k], acc[ai][bj][m][n], 0, 0, 0); __builtin_amdgcn_s_setprio(0); } while (0)
; #define PG8_WAIT_V(n) asm volatile("s_waitcnt vmcnt(" #n ")" ::: "memory")
; #define PG8_WAIT_L(n) asm volatile("s_waitcnt lgkmcnt(" #n ")" ::: "memory")
; #define PG8_BAR __builtin_amdgcn_s_barrier()
; #define PG8_SCHED __builtin_amdgcn_sched_barrier(0)
; template <class Epi, class Sched, bool ALIGN_EPI = false, bool SP2 = false>
; __device__ __forceinline__ void gemm_phase(PG8_LAS unsigned char* lds, const Gemm g, const Sched& S, const Epi& E) {
;     ...
;             PG8_LDB(B0, 0, 0); PG8_LDB(B1, 0, 1); PG8_SCHED; PG8_LDA(At, 0, 0); PG8_STAGE(PG8_SA(1, 1), a1 + hstep, voffA);
;             PG8_WAIT_V(8); PG8_WAIT_L(0); PG8_BAR; PG8_MMA(0, 0, At, B0); PG8_MMA(0, 1, At, B1); PG8_BAR; PG8_SCHED;
;             PG8_LDA(At, 0, 1); PG8_STAGE(PG8_SB(0, 0), b2, voffB); PG8_STAGE(PG8_SB(0, 1), b2 + hstep, voffB); PG8_STAGE(PG8_SA(0, 0), a2, voffA);
;             PG8_WAIT_V(8); PG8_WAIT_L(0); PG8_BAR; PG8_MMA(1, 0, At, B0); PG8_MMA(1, 1, At, B1); PG8_BAR; PG8_SCHED;
.LBB0_150:
	s_add_u32 s24, s22, 0xfffc0080
	s_addc_u32 s25, s23, -1
	s_waitcnt lgkmcnt(0)
	s_add_i32 s54, 0, 0x10000
	v_add_u32_e32 v147, s54, v152
	ds_read_b128 v[156:159], v147
	ds_read_b128 v[160:163], v147 offset:1024
	ds_read_b128 v[164:167], v147 offset:2048
	ds_read_b128 v[168:171], v147 offset:3072
	ds_read_b128 v[172:175], v154
	ds_read_b128 v[176:179], v154 offset:1024
	ds_read_b128 v[182:185], v154 offset:2048
	ds_read_b128 v[190:193], v154 offset:3072
	s_cmp_eq_u32 s49, 12
	s_cselect_b32 s27, s17, s25
	s_cselect_b32 s26, s45, s24
	s_cselect_b32 s25, s15, s48
	s_cselect_b32 s24, s46, s47
	s_add_i32 m0, s13, 0xc000
	ds_read_b128 v[194:197], v155
	ds_read_b128 v[198:201], v155 offset:1024
	ds_read_b128 v[202:205], v155 offset:2048
	ds_read_b128 v[206:209], v155 offset:3072
	ds_read_b128 v[210:213], v155 offset:4096
	ds_read_b128 v[214:217], v155 offset:5120
	ds_read_b128 v[218:221], v155 offset:6144
	ds_read_b128 v[222:225], v155 offset:7168
	global_load_lds_dwordx4 v138, s[22:23]
	s_add_i32 m0, s13, 0xe000
	s_nop 0
	global_load_lds_dwordx4 v140, s[22:23]
	s_waitcnt vmcnt(8)
	s_waitcnt lgkmcnt(0)
	s_barrier
	s_setprio 1
	s_waitcnt lgkmcnt(0)
	v_mfma_f32_16x16x32_bf16 v[124:127], v[156:159], v[194:197], v[124:127]
	v_mfma_f32_16x16x32_bf16 v[120:123], v[164:167], v[194:197], v[120:123]
	v_mfma_f32_16x16x32_bf16 v[116:119], v[156:159], v[202:205], v[116:119]
	v_mfma_f32_16x16x32_bf16 v[112:115], v[164:167], v[202:205], v[112:115]
	v_mfma_f32_16x16x32_bf16 v[100:103], v[156:159], v[210:213], v[100:103]
	v_mfma_f32_16x16x32_bf16 v[96:99], v[164:167], v[210:213], v[96:99]
	v_mfma_f32_16x16x32_bf16 v[84:87], v[156:159], v[218:221], v[84:87]
	v_mfma_f32_16x16x32_bf16 v[80:83], v[164:167], v[218:221], v[80:83]
	v_mfma_f32_16x16x32_bf16 v[124:127], v[160:163], v[198:201], v[124:127]
	v_mfma_f32_16x16x32_bf16 v[120:123], v[168:171], v[198:201], v[120:123]
	v_mfma_f32_16x16x32_bf16 v[116:119], v[160:163], v[206:209], v[116:119]
	v_mfma_f32_16x16x32_bf16 v[112:115], v[168:171], v[206:209], v[112:115]
	v_mfma_f32_16x16x32_bf16 v[100:103], v[160:163], v[214:217], v[100:103]
	v_mfma_f32_16x16x32_bf16 v[96:99], v[168:171], v[214:217], v[96:99]
	v_mfma_f32_16x16x32_bf16 v[84:87], v[160:163], v[222:225], v[84:87]
	v_mfma_f32_16x16x32_bf16 v[80:83], v[168:171], v[222:225], v[80:83]
	s_setprio 0
	s_setprio 1
	v_mfma_f32_16x16x32_bf16 v[108:111], v[172:175], v[194:197], v[108:111]
	v_mfma_f32_16x16x32_bf16 v[104:107], v[182:185], v[194:197], v[104:107]
	v_mfma_f32_16x16x32_bf16 v[92:95], v[172:175], v[202:205], v[92:95]
	v_mfma_f32_16x16x32_bf16 v[88:91], v[182:185], v[202:205], v[88:91]
	v_mfma_f32_16x16x32_bf16 v[76:79], v[172:175], v[210:213], v[76:79]
	v_mfma_f32_16x16x32_bf16 v[72:75], v[182:185], v[210:213], v[72:75]
	v_mfma_f32_16x16x32_bf16 v[68:71], v[172:175], v[218:221], v[68:71]
	v_mfma_f32_16x16x32_bf16 v[64:67], v[182:185], v[218:221], v[64:67]
	v_mfma_f32_16x16x32_bf16 v[108:111], v[176:179], v[198:201], v[108:111]
	v_mfma_f32_16x16x32_bf16 v[104:107], v[190:193], v[198:201], v[104:107]
	v_mfma_f32_16x16x32_bf16 v[92:95], v[176:179], v[206:209], v[92:95]
	v_mfma_f32_16x16x32_bf16 v[88:91], v[190:193], v[206:209], v[88:91]
	v_mfma_f32_16x16x32_bf16 v[76:79], v[176:179], v[214:217], v[76:79]
	v_mfma_f32_16x16x32_bf16 v[72:75], v[190:193], v[214:217], v[72:75]
	v_mfma_f32_16x16x32_bf16 v[68:71], v[176:179], v[222:225], v[68:71]
	v_mfma_f32_16x16x32_bf16 v[64:67], v[190:193], v[222:225], v[64:67]
	s_setprio 0
	s_barrier
	s_add_i32 s54, s54, s31
	v_lshl_add_u64 v[186:187], s[24:25], 0, v[130:131]
	s_mov_b32 m0, s54
	ds_read_b128 v[194:197], v155 offset:16384
	ds_read_b128 v[198:201], v155 offset:17408
	ds_read_b128 v[202:205], v155 offset:18432
	ds_read_b128 v[206:209], v155 offset:19456
	ds_read_b128 v[210:213], v155 offset:20480
	ds_read_b128 v[214:217], v155 offset:21504
	ds_read_b128 v[218:221], v155 offset:22528
	ds_read_b128 v[222:225], v155 offset:23552
	global_load_lds_dwordx4 v[186:187], off
	s_add_i32 m0, s54, 0x2000
	s_add_u32 s54, s24, 0x40000
	v_lshl_add_u64 v[226:227], s[24:25], 0, v[134:135]
	s_addc_u32 s55, s25, 0
	s_add_i32 s76, s43, s31
	global_load_lds_dwordx4 v[226:227], off
	s_mov_b32 m0, s76
	v_lshl_add_u64 v[230:231], s[26:27], 0, v[132:133]
	global_load_lds_dwordx4 v130, s[54:55]
	s_add_i32 m0, s76, 0x2000
	s_nop 0
	global_load_lds_dwordx4 v134, s[54:55]
	v_lshl_add_u64 v[228:229], s[26:27], 0, v[128:129]
	s_mov_b32 m0, s13
	s_nop 0
	global_load_lds_dwordx4 v[228:229], off
	s_mov_b32 m0, s34
	s_nop 0
	global_load_lds_dwordx4 v[230:231], off
	s_waitcnt vmcnt(8)
	s_waitcnt lgkmcnt(0)
	s_barrier
; #define PG8_STAGE(bufoff, gbase, voff) do { _Pragma("unroll") for (int _i = 0; _i < 2; ++_i) \
;         __builtin_amdgcn_global_load_lds((const unsigned*)((const char*)(gbase) + (voff)[_i]), (PG8_LAS unsigned*)(lds + (bufoff) + ldsw + _i * 8192), 16, 0, 0); } while (0)
; #define PG8_LDA(dst, b, h) do { _Pragma("unroll") for (int m = 0; m < 4; ++m) _Pragma("unroll") for (int k = 0; k < 2; ++k) dst[m][k] = *(const PG8_LAS bf16x8*)(lds + PG8_SA(b, h) + aoff + m * 2048 + k * 1024); } while (0)
; #define PG8_LDB(dst, b, h) do { _Pragma("unroll") for (int n = 0; n < 2; ++n) _Pragma("unroll") for (int k = 0; k < 2; ++k) dst[n][k] = *(const PG8_LAS bf16x8*)(lds + PG8_SB(b, h) + boff + n * 2048 + k * 1024); } while (0)
; #define PG8_MMA(ai, bj, At, Bt) do { __builtin_amdgcn_s_setprio(1); _Pragma("unroll") for (int m = 0; m < 4; ++m) _Pragma("unroll") for (int n = 0; n < 2; ++n) _Pragma("unroll") for (int k = 0; k < 2; ++k) \
;         acc[ai][bj][m][n] = __builtin_amdgcn_mfma_f32_16x16x32_bf16(Bt[n][k], At[m][k], acc[ai][bj][m][n], 0, 0, 0); __builtin_amdgcn_s_setprio(0); } while (0)
; #define PG8_WAIT_V(n) asm volatile("s_waitcnt vmcnt(" #n ")" ::: "memory")
; #define PG8_WAIT_L(n) asm volatile("s_waitcnt lgkmcnt(" #n ")" ::: "memory")
; #define PG8_BAR __builtin_amdgcn_s_barrier()
; #define PG8_SCHED __builtin_amdgcn_sched_barrier(0)
; template <class Epi, class Sched, bool ALIGN_EPI = false, bool SP2 = false>
; __device__ __forceinline__ void gemm_phase(PG8_LAS unsigned char* lds, const Gemm g, const Sched& S, const Epi& E) {
;     ...
;             PG8_WAIT_V(8); PG8_WAIT_L(0); PG8_BAR; PG8_MMA(1, 0, At, B0); PG8_MMA(1, 1, At, B1); PG8_BAR; PG8_SCHED;
;             PG8_LDB(B0, 1, 0); PG8_LDB(B1, 1, 1); PG8_SCHED; PG8_LDA(At, 1, 0); PG8_STAGE(PG8_SA(0, 1), a2 + hstep, voffA);
;             PG8_WAIT_V(8); PG8_WAIT_L(0); PG8_BAR; PG8_MMA(0, 0, At, B0); PG8_MMA(0, 1, At, B1); PG8_BAR; PG8_SCHED;
	s_setprio 1
	s_waitcnt lgkmcnt(0)
	v_mfma_f32_16x16x32_bf16 v[60:63], v[156:159], v[194:197], v[60:63]
	v_mfma_f32_16x16x32_bf16 v[56:59], v[164:167], v[194:197], v[56:59]
	v_mfma_f32_16x16x32_bf16 v[52:55], v[156:159], v[202:205], v[52:55]
	v_mfma_f32_16x16x32_bf16 v[48:51], v[164:167], v[202:205], v[48:51]
	v_mfma_f32_16x16x32_bf16 v[36:39], v[156:159], v[210:213], v[36:39]
	v_mfma_f32_16x16x32_bf16 v[32:35], v[164:167], v[210:213], v[32:35]
	v_mfma_f32_16x16x32_bf16 v[20:23], v[156:159], v[218:221], v[20:23]
	v_mfma_f32_16x16x32_bf16 v[16:19], v[164:167], v[218:221], v[16:19]
	v_mfma_f32_16x16x32_bf16 v[60:63], v[160:163], v[198:201], v[60:63]
	v_mfma_f32_16x16x32_bf16 v[56:59], v[168:171], v[198:201], v[56:59]
	v_mfma_f32_16x16x32_bf16 v[52:55], v[160:163], v[206:209], v[52:55]
	v_mfma_f32_16x16x32_bf16 v[48:51], v[168:171], v[206:209], v[48:51]
	v_mfma_f32_16x16x32_bf16 v[36:39], v[160:163], v[214:217], v[36:39]
	v_mfma_f32_16x16x32_bf16 v[32:35], v[168:171], v[214:217], v[32:35]
	v_mfma_f32_16x16x32_bf16 v[20:23], v[160:163], v[222:225], v[20:23]
	v_mfma_f32_16x16x32_bf16 v[16:19], v[168:171], v[222:225], v[16:19]
	s_setprio 0
	s_setprio 1
	v_mfma_f32_16x16x32_bf16 v[44:47], v[172:175], v[194:197], v[44:47]
	v_mfma_f32_16x16x32_bf16 v[40:43], v[182:185], v[194:197], v[40:43]
	v_mfma_f32_16x16x32_bf16 v[28:31], v[172:175], v[202:205], v[28:31]
	v_mfma_f32_16x16x32_bf16 v[24:27], v[182:185], v[202:205], v[24:27]
	v_mfma_f32_16x16x32_bf16 v[12:15], v[172:175], v[210:213], v[12:15]
	v_mfma_f32_16x16x32_bf16 v[8:11], v[182:185], v[210:213], v[8:11]
	v_mfma_f32_16x16x32_bf16 v[4:7], v[172:175], v[218:221], v[4:7]
	v_mfma_f32_16x16x32_bf16 v[0:3], v[182:185], v[218:221], v[0:3]
	v_mfma_f32_16x16x32_bf16 v[44:47], v[176:179], v[198:201], v[44:47]
	v_mfma_f32_16x16x32_bf16 v[40:43], v[190:193], v[198:201], v[40:43]
	v_mfma_f32_16x16x32_bf16 v[28:31], v[176:179], v[206:209], v[28:31]
	v_mfma_f32_16x16x32_bf16 v[24:27], v[190:193], v[206:209], v[24:27]
	v_mfma_f32_16x16x32_bf16 v[12:15], v[176:179], v[214:217], v[12:15]
	v_mfma_f32_16x16x32_bf16 v[8:11], v[190:193], v[214:217], v[8:11]
	v_mfma_f32_16x16x32_bf16 v[4:7], v[176:179], v[222:225], v[4:7]
	v_mfma_f32_16x16x32_bf16 v[0:3], v[190:193], v[222:225], v[0:3]
	s_setprio 0
	s_barrier
	s_add_i32 s54, 0, 0x18000
	v_add_u32_e32 v147, s54, v152
	s_add_i32 s55, 0, 0x1c000
	ds_read_b128 v[156:159], v147
	ds_read_b128 v[160:163], v147 offset:1024
	ds_read_b128 v[164:167], v147 offset:2048
	ds_read_b128 v[168:171], v147 offset:3072
	v_add_u32_e32 v147, s55, v152
	ds_read_b128 v[172:175], v147
	ds_read_b128 v[176:179], v147 offset:1024
	ds_read_b128 v[182:185], v147 offset:2048
	ds_read_b128 v[190:193], v147 offset:3072
	s_add_u32 s26, s26, 0x40000
	s_addc_u32 s27, s27, 0
	s_mov_b32 m0, s35
	ds_read_b128 v[194:197], v155 offset:32768
	ds_read_b128 v[198:201], v155 offset:33792
	ds_read_b128 v[202:205], v155 offset:34816
	ds_read_b128 v[206:209], v155 offset:35840
	ds_read_b128 v[210:213], v155 offset:36864
	ds_read_b128 v[214:217], v155 offset:37888
	ds_read_b128 v[218:221], v155 offset:38912
	ds_read_b128 v[222:225], v155 offset:39936
	global_load_lds_dwordx4 v128, s[26:27]
	s_mov_b32 m0, s36
	s_nop 0
	global_load_lds_dwordx4 v132, s[26:27]
	s_waitcnt vmcnt(8)
	s_waitcnt lgkmcnt(0)
	s_barrier
	s_setprio 1
	s_waitcnt lgkmcnt(0)
	v_mfma_f32_16x16x32_bf16 v[124:127], v[156:159], v[194:197], v[124:127]
	v_mfma_f32_16x16x32_bf16 v[120:123], v[164:167], v[194:197], v[120:123]
	v_mfma_f32_16x16x32_bf16 v[116:119], v[156:159], v[202:205], v[116:119]
	v_mfma_f32_16x16x32_bf16 v[112:115], v[164:167], v[202:205], v[112:115]
	v_mfma_f32_16x16x32_bf16 v[100:103], v[156:159], v[210:213], v[100:103]
	v_mfma_f32_16x16x32_bf16 v[96:99], v[164:167], v[210:213], v[96:99]
	v_mfma_f32_16x16x32_bf16 v[84:87], v[156:159], v[218:221], v[84:87]
	v_mfma_f32_16x16x32_bf16 v[80:83], v[164:167], v[218:221], v[80:83]
	v_mfma_f32_16x16x32_bf16 v[124:127], v[160:163], v[198:201], v[124:127]
	v_mfma_f32_16x16x32_bf16 v[120:123], v[168:171], v[198:201], v[120:123]
	v_mfma_f32_16x16x32_bf16 v[116:119], v[160:163], v[206:209], v[116:119]
	v_mfma_f32_16x16x32_bf16 v[112:115], v[168:171], v[206:209], v[112:115]
	v_mfma_f32_16x16x32_bf16 v[100:103], v[160:163], v[214:217], v[100:103]
	v_mfma_f32_16x16x32_bf16 v[96:99], v[168:171], v[214:217], v[96:99]
	v_mfma_f32_16x16x32_bf16 v[84:87], v[160:163], v[222:225], v[84:87]
	v_mfma_f32_16x16x32_bf16 v[80:83], v[168:171], v[222:225], v[80:83]
	s_setprio 0
	s_setprio 1
	v_mfma_f32_16x16x32_bf16 v[108:111], v[172:175], v[194:197], v[108:111]
	v_mfma_f32_16x16x32_bf16 v[104:107], v[182:185], v[194:197], v[104:107]
	v_mfma_f32_16x16x32_bf16 v[92:95], v[172:175], v[202:205], v[92:95]
	v_mfma_f32_16x16x32_bf16 v[88:91], v[182:185], v[202:205], v[88:91]
	v_mfma_f32_16x16x32_bf16 v[76:79], v[172:175], v[210:213], v[76:79]
	v_mfma_f32_16x16x32_bf16 v[72:75], v[182:185], v[210:213], v[72:75]
	v_mfma_f32_16x16x32_bf16 v[68:71], v[172:175], v[218:221], v[68:71]
	v_mfma_f32_16x16x32_bf16 v[64:67], v[182:185], v[218:221], v[64:67]
	v_mfma_f32_16x16x32_bf16 v[108:111], v[176:179], v[198:201], v[108:111]
	v_mfma_f32_16x16x32_bf16 v[104:107], v[190:193], v[198:201], v[104:107]
	v_mfma_f32_16x16x32_bf16 v[92:95], v[176:179], v[206:209], v[92:95]
	v_mfma_f32_16x16x32_bf16 v[88:91], v[190:193], v[206:209], v[88:91]
	v_mfma_f32_16x16x32_bf16 v[76:79], v[176:179], v[214:217], v[76:79]
	v_mfma_f32_16x16x32_bf16 v[72:75], v[190:193], v[214:217], v[72:75]
	v_mfma_f32_16x16x32_bf16 v[68:71], v[176:179], v[222:225], v[68:71]
	v_mfma_f32_16x16x32_bf16 v[64:67], v[190:193], v[222:225], v[64:67]
	s_setprio 0
	s_barrier
; #define PG8_STAGE(bufoff, gbase, voff) do { _Pragma("unroll") for (int _i = 0; _i < 2; ++_i) \
;         __builtin_amdgcn_global_load_lds((const unsigned*)((const char*)(gbase) + (voff)[_i]), (PG8_LAS unsigned*)(lds + (bufoff) + ldsw + _i * 8192), 16, 0, 0); } while (0)
; #define PG8_LDA(dst, b, h) do { _Pragma("unroll") for (int m = 0; m < 4; ++m) _Pragma("unroll") for (int k = 0; k < 2; ++k) dst[m][k] = *(const PG8_LAS bf16x8*)(lds + PG8_SA(b, h) + aoff + m * 2048 + k * 1024); } while (0)
; #define PG8_MMA(ai, bj, At, Bt) do { __builtin_amdgcn_s_setprio(1); _Pragma("unroll") for (int m = 0; m < 4; ++m) _Pragma("unroll") for (int n = 0; n < 2; ++n) _Pragma("unroll") for (int k = 0; k < 2; ++k) \
;         acc[ai][bj][m][n] = __builtin_amdgcn_mfma_f32_16x16x32_bf16(Bt[n][k], At[m][k], acc[ai][bj][m][n], 0, 0, 0); __builtin_amdgcn_s_setprio(0); } while (0)
; #define PG8_WAIT_V(n) asm volatile("s_waitcnt vmcnt(" #n ")" ::: "memory")
; #define PG8_WAIT_L(n) asm volatile("s_waitcnt lgkmcnt(" #n ")" ::: "memory")
; #define PG8_BAR __builtin_amdgcn_s_barrier()
; #define PG8_SCHED __builtin_amdgcn_sched_barrier(0)
; template <class Epi, class Sched, bool ALIGN_EPI = false, bool SP2 = false>
; __device__ __forceinline__ void gemm_phase(PG8_LAS unsigned char* lds, const Gemm g, const Sched& S, const Epi& E) {
;     ...
;         for (int t = 0; t < nt; t += 2) {
;             const bool last = (t == nt - 2);
;             const char* a1 = cA + (size_t)(t + 1) * kstep;
;             const char* a2 = last ? nA : cA + (size_t)(t + 2) * kstep; const char* b2 = last ? nB : cB + (size_t)(t + 2) * kstep;
;             const char* a3 = a2 + kstep; const char* b3 = b2 + kstep;
;     ...
;             PG8_LDA(At, 1, 1); PG8_STAGE(PG8_SB(1, 0), b3, voffB); PG8_STAGE(PG8_SB(1, 1), b3 + hstep, voffB); PG8_STAGE(PG8_SA(1, 0), a3, voffA);
;             PG8_WAIT_V(8); PG8_WAIT_L(0); PG8_BAR; PG8_MMA(1, 0, At, B0); PG8_MMA(1, 1, At, B1); PG8_BAR; PG8_SCHED;
	s_add_i32 s26, s54, s31
	v_lshl_add_u64 v[186:187], v[186:187], 0, s[8:9]
	s_mov_b32 m0, s26
	ds_read_b128 v[194:197], v155 offset:49152
	ds_read_b128 v[198:201], v155 offset:50176
	ds_read_b128 v[202:205], v155 offset:51200
	ds_read_b128 v[206:209], v155 offset:52224
	ds_read_b128 v[210:213], v155 offset:53248
	ds_read_b128 v[214:217], v155 offset:54272
	ds_read_b128 v[218:221], v155 offset:55296
	ds_read_b128 v[222:225], v155 offset:56320
	global_load_lds_dwordx4 v[186:187], off
	s_add_i32 m0, s26, 0x2000
	s_add_u32 s24, s24, 0x40080
	v_lshl_add_u64 v[186:187], v[226:227], 0, s[8:9]
	s_addc_u32 s25, s25, 0
	s_add_i32 s26, s55, s31
	global_load_lds_dwordx4 v[186:187], off
	s_mov_b32 m0, s26
	s_nop 0
	global_load_lds_dwordx4 v130, s[24:25]
	s_add_i32 m0, s26, 0x2000
	s_nop 0
	global_load_lds_dwordx4 v134, s[24:25]
	v_lshl_add_u64 v[186:187], v[228:229], 0, s[8:9]
	s_mov_b32 m0, s39
	s_nop 0
	global_load_lds_dwordx4 v[186:187], off
	v_lshl_add_u64 v[186:187], v[230:231], 0, s[8:9]
	s_mov_b32 m0, s40
	s_nop 0
	global_load_lds_dwordx4 v[186:187], off
	s_waitcnt vmcnt(8)
	s_waitcnt lgkmcnt(0)
	s_barrier
	s_setprio 1
	s_waitcnt lgkmcnt(0)
	v_mfma_f32_16x16x32_bf16 v[60:63], v[156:159], v[194:197], v[60:63]
	v_mfma_f32_16x16x32_bf16 v[56:59], v[164:167], v[194:197], v[56:59]
	v_mfma_f32_16x16x32_bf16 v[52:55], v[156:159], v[202:205], v[52:55]
	v_mfma_f32_16x16x32_bf16 v[48:51], v[164:167], v[202:205], v[48:51]
	v_mfma_f32_16x16x32_bf16 v[36:39], v[156:159], v[210:213], v[36:39]
	v_mfma_f32_16x16x32_bf16 v[32:35], v[164:167], v[210:213], v[32:35]
	v_mfma_f32_16x16x32_bf16 v[20:23], v[156:159], v[218:221], v[20:23]
	v_mfma_f32_16x16x32_bf16 v[16:19], v[164:167], v[218:221], v[16:19]
	v_mfma_f32_16x16x32_bf16 v[60:63], v[160:163], v[198:201], v[60:63]
	v_mfma_f32_16x16x32_bf16 v[56:59], v[168:171], v[198:201], v[56:59]
	v_mfma_f32_16x16x32_bf16 v[52:55], v[160:163], v[206:209], v[52:55]
	v_mfma_f32_16x16x32_bf16 v[48:51], v[168:171], v[206:209], v[48:51]
	v_mfma_f32_16x16x32_bf16 v[36:39], v[160:163], v[214:217], v[36:39]
	v_mfma_f32_16x16x32_bf16 v[32:35], v[168:171], v[214:217], v[32:35]
	v_mfma_f32_16x16x32_bf16 v[20:23], v[160:163], v[222:225], v[20:23]
	v_mfma_f32_16x16x32_bf16 v[16:19], v[168:171], v[222:225], v[16:19]
	s_setprio 0
	s_setprio 1
	v_mfma_f32_16x16x32_bf16 v[44:47], v[172:175], v[194:197], v[44:47]
	v_mfma_f32_16x16x32_bf16 v[40:43], v[182:185], v[194:197], v[40:43]
	v_mfma_f32_16x16x32_bf16 v[28:31], v[172:175], v[202:205], v[28:31]
	v_mfma_f32_16x16x32_bf16 v[24:27], v[182:185], v[202:205], v[24:27]
	v_mfma_f32_16x16x32_bf16 v[12:15], v[172:175], v[210:213], v[12:15]
	v_mfma_f32_16x16x32_bf16 v[8:11], v[182:185], v[210:213], v[8:11]
	v_mfma_f32_16x16x32_bf16 v[4:7], v[172:175], v[218:221], v[4:7]
	v_mfma_f32_16x16x32_bf16 v[0:3], v[182:185], v[218:221], v[0:3]
	v_mfma_f32_16x16x32_bf16 v[44:47], v[176:179], v[198:201], v[44:47]
	v_mfma_f32_16x16x32_bf16 v[40:43], v[190:193], v[198:201], v[40:43]
	v_mfma_f32_16x16x32_bf16 v[28:31], v[176:179], v[206:209], v[28:31]
	v_mfma_f32_16x16x32_bf16 v[24:27], v[190:193], v[206:209], v[24:27]
	v_mfma_f32_16x16x32_bf16 v[12:15], v[176:179], v[214:217], v[12:15]
	v_mfma_f32_16x16x32_bf16 v[8:11], v[190:193], v[214:217], v[8:11]
	v_mfma_f32_16x16x32_bf16 v[4:7], v[176:179], v[222:225], v[4:7]
	v_mfma_f32_16x16x32_bf16 v[0:3], v[190:193], v[222:225], v[0:3]
	s_setprio 0
	s_barrier
	s_add_i32 s49, s49, 2
	s_add_u32 s22, s22, 0x100
	s_addc_u32 s23, s23, 0
	s_add_u32 s47, s47, 0x100
	s_addc_u32 s48, s48, 0
	s_cmp_gt_u32 s49, 13
	s_cbranch_scc0 .LBB0_150
	s_and_b64 vcc, exec, s[10:11]
	s_cbranch_vccz .LBB0_153
	s_barrier

; #define PG8_STAGE(bufoff, gbase, voff) do { _Pragma("unroll") for (int _i = 0; _i < 2; ++_i) \
;         __builtin_amdgcn_global_load_lds((const unsigned*)((const char*)(gbase) + (voff)[_i]), (PG8_LAS unsigned*)(lds + (bufoff) + ldsw + _i * 8192), 16, 0, 0); } while (0)
; #define PG8_LDA(dst, b, h) do { _Pragma("unroll") for (int m = 0; m < 4; ++m) _Pragma("unroll") for (int k = 0; k < 2; ++k) dst[m][k] = *(const PG8_LAS bf16x8*)(lds + PG8_SA(b, h) + aoff + m * 2048 + k * 1024); } while (0)
; #define PG8_LDB(dst, b, h) do { _Pragma("unroll") for (int n = 0; n < 2; ++n) _Pragma("unroll") for (int k = 0; k < 2; ++k) dst[n][k] = *(const PG8_LAS bf16x8*)(lds + PG8_SB(b, h) + boff + n * 2048 + k * 1024); } while (0)
; #define PG8_MMA(ai, bj, At, Bt) do { __builtin_amdgcn_s_setprio(1); _Pragma("unroll") for (int m = 0; m < 4; ++m) _Pragma("unroll") for (int n = 0; n < 2; ++n) _Pragma("unroll") for (int k = 0; k < 2; ++k) \
;         acc[ai][bj][m][n] = __builtin_amdgcn_mfma_f32_16x16x32_bf16(Bt[n][k], At[m][k], acc[ai][bj][m][n], 0, 0, 0); __builtin_amdgcn_s_setprio(0); } while (0)
; #define PG8_WAIT_V(n) asm volatile("s_waitcnt vmcnt(" #n ")" ::: "memory")
; #define PG8_WAIT_L(n) asm volatile("s_waitcnt lgkmcnt(" #n ")" ::: "memory")
; #define PG8_BAR __builtin_amdgcn_s_barrier()
; #define PG8_SCHED __builtin_amdgcn_sched_barrier(0)
; template <class Epi, class Sched, bool ALIGN_EPI = false, bool SP2 = false>
; __device__ __forceinline__ void gemm_phase(PG8_LAS unsigned char* lds, const Gemm g, const Sched& S, const Epi& E) {
;     ...
;             PG8_LDB(B0, 0, 0); PG8_LDB(B1, 0, 1); PG8_SCHED; PG8_LDA(At, 0, 0); PG8_STAGE(PG8_SA(1, 1), a1 + hstep, voffA);
;             PG8_WAIT_V(8); PG8_WAIT_L(0); PG8_BAR; PG8_MMA(0, 0, At, B0); PG8_MMA(0, 1, At, B1); PG8_BAR; PG8_SCHED;
;             PG8_LDA(At, 0, 1); PG8_STAGE(PG8_SB(0, 0), b2, voffB); PG8_STAGE(PG8_SB(0, 1), b2 + hstep, voffB); PG8_STAGE(PG8_SA(0, 0), a2, voffA);
;             PG8_WAIT_V(8); PG8_WAIT_L(0); PG8_BAR; PG8_MMA(1, 0, At, B0); PG8_MMA(1, 1, At, B1); PG8_BAR; PG8_SCHED;
;             PG8_LDB(B0, 1, 0); PG8_LDB(B1, 1, 1); PG8_SCHED; PG8_LDA(At, 1, 0); PG8_STAGE(PG8_SA(0, 1), a2 + hstep, voffA);
;             PG8_WAIT_V(8); PG8_WAIT_L(0); PG8_BAR; PG8_MMA(0, 0, At, B0); PG8_MMA(0, 1, At, B1); PG8_BAR; PG8_SCHED;
.LBB0_684:
	ds_read_b128 v[128:131], v174
	ds_read_b128 v[132:135], v174 offset:1024
	ds_read_b128 v[136:139], v174 offset:2048
	ds_read_b128 v[140:143], v174 offset:3072
	ds_read_b128 v[162:165], v175
	ds_read_b128 v[166:169], v175 offset:1024
	ds_read_b128 v[180:183], v175 offset:2048
	ds_read_b128 v[184:187], v175 offset:3072
	s_add_u32 s8, s0, 0xfffc0080
	s_addc_u32 s9, s1, -1
	s_cmp_eq_u32 vcc_lo, 12
	s_cselect_b32 s43, s3, s9
	s_cselect_b32 s42, s94, s8
	s_cselect_b32 s41, s5, s97
	s_cselect_b32 s40, s95, s96
	s_add_i32 m0, s47, 0xc000
	ds_read_b128 v[190:193], v176
	ds_read_b128 v[194:197], v176 offset:1024
	ds_read_b128 v[198:201], v176 offset:2048
	ds_read_b128 v[202:205], v176 offset:3072
	ds_read_b128 v[206:209], v176 offset:4096
	ds_read_b128 v[210:213], v176 offset:5120
	ds_read_b128 v[214:217], v176 offset:6144
	ds_read_b128 v[218:221], v176 offset:7168
	global_load_lds_dwordx4 v158, s[0:1]
	s_add_i32 m0, s47, 0xe000
	s_nop 0
	global_load_lds_dwordx4 v160, s[0:1]
	s_waitcnt vmcnt(8)
	s_waitcnt lgkmcnt(0)
	s_barrier
	s_setprio 1
	s_waitcnt lgkmcnt(0)
	v_mfma_f32_16x16x32_bf16 v[124:127], v[128:131], v[190:193], v[124:127]
	v_mfma_f32_16x16x32_bf16 v[120:123], v[136:139], v[190:193], v[120:123]
	v_mfma_f32_16x16x32_bf16 v[108:111], v[128:131], v[198:201], v[108:111]
	v_mfma_f32_16x16x32_bf16 v[104:107], v[136:139], v[198:201], v[104:107]
	v_mfma_f32_16x16x32_bf16 v[92:95], v[128:131], v[206:209], v[92:95]
	v_mfma_f32_16x16x32_bf16 v[88:91], v[136:139], v[206:209], v[88:91]
	v_mfma_f32_16x16x32_bf16 v[76:79], v[128:131], v[214:217], v[76:79]
	v_mfma_f32_16x16x32_bf16 v[72:75], v[136:139], v[214:217], v[72:75]
	v_mfma_f32_16x16x32_bf16 v[124:127], v[132:135], v[194:197], v[124:127]
	v_mfma_f32_16x16x32_bf16 v[120:123], v[140:143], v[194:197], v[120:123]
	v_mfma_f32_16x16x32_bf16 v[108:111], v[132:135], v[202:205], v[108:111]
	v_mfma_f32_16x16x32_bf16 v[104:107], v[140:143], v[202:205], v[104:107]
	v_mfma_f32_16x16x32_bf16 v[92:95], v[132:135], v[210:213], v[92:95]
	v_mfma_f32_16x16x32_bf16 v[88:91], v[140:143], v[210:213], v[88:91]
	v_mfma_f32_16x16x32_bf16 v[76:79], v[132:135], v[218:221], v[76:79]
	v_mfma_f32_16x16x32_bf16 v[72:75], v[140:143], v[218:221], v[72:75]
	s_setprio 0
	s_setprio 1
	v_mfma_f32_16x16x32_bf16 v[116:119], v[162:165], v[190:193], v[116:119]
	v_mfma_f32_16x16x32_bf16 v[112:115], v[180:183], v[190:193], v[112:115]
	v_mfma_f32_16x16x32_bf16 v[100:103], v[162:165], v[198:201], v[100:103]
	v_mfma_f32_16x16x32_bf16 v[96:99], v[180:183], v[198:201], v[96:99]
	v_mfma_f32_16x16x32_bf16 v[84:87], v[162:165], v[206:209], v[84:87]
	v_mfma_f32_16x16x32_bf16 v[80:83], v[180:183], v[206:209], v[80:83]
	v_mfma_f32_16x16x32_bf16 v[68:71], v[162:165], v[214:217], v[68:71]
	v_mfma_f32_16x16x32_bf16 v[64:67], v[180:183], v[214:217], v[64:67]
	v_mfma_f32_16x16x32_bf16 v[116:119], v[166:169], v[194:197], v[116:119]
	v_mfma_f32_16x16x32_bf16 v[112:115], v[184:187], v[194:197], v[112:115]
	v_mfma_f32_16x16x32_bf16 v[100:103], v[166:169], v[202:205], v[100:103]
	v_mfma_f32_16x16x32_bf16 v[96:99], v[184:187], v[202:205], v[96:99]
	v_mfma_f32_16x16x32_bf16 v[84:87], v[166:169], v[210:213], v[84:87]
	v_mfma_f32_16x16x32_bf16 v[80:83], v[184:187], v[210:213], v[80:83]
	v_mfma_f32_16x16x32_bf16 v[68:71], v[166:169], v[218:221], v[68:71]
	v_mfma_f32_16x16x32_bf16 v[64:67], v[184:187], v[218:221], v[64:67]
	s_setprio 0
	s_barrier
	s_add_i32 s8, s76, s46
	v_lshl_add_u64 v[170:171], s[40:41], 0, v[146:147]
	s_mov_b32 m0, s8
	ds_read_b128 v[190:193], v176 offset:16384
	ds_read_b128 v[194:197], v176 offset:17408
	ds_read_b128 v[198:201], v176 offset:18432
	ds_read_b128 v[202:205], v176 offset:19456
	ds_read_b128 v[206:209], v176 offset:20480
	ds_read_b128 v[210:213], v176 offset:21504
	ds_read_b128 v[214:217], v176 offset:22528
	ds_read_b128 v[218:221], v176 offset:23552
	global_load_lds_dwordx4 v[170:171], off
	s_add_i32 m0, s8, 0x2000
	s_add_u32 s8, s40, 0x40000
	v_lshl_add_u64 v[222:223], s[40:41], 0, v[150:151]
	s_addc_u32 s9, s41, 0
	s_add_i32 s54, s77, s46
	global_load_lds_dwordx4 v[222:223], off
	s_mov_b32 m0, s54
	v_lshl_add_u64 v[226:227], s[42:43], 0, v[148:149]
	global_load_lds_dwordx4 v146, s[8:9]
	s_add_i32 m0, s54, 0x2000
	s_nop 0
	global_load_lds_dwordx4 v150, s[8:9]
	v_lshl_add_u64 v[224:225], s[42:43], 0, v[144:145]
	s_mov_b32 m0, s47
	s_nop 0
	global_load_lds_dwordx4 v[224:225], off
	s_mov_b32 m0, s48
	s_nop 0
	global_load_lds_dwordx4 v[226:227], off
	s_waitcnt vmcnt(8)
	s_waitcnt lgkmcnt(0)
	s_barrier
	s_setprio 1
	s_waitcnt lgkmcnt(0)
	v_mfma_f32_16x16x32_bf16 v[60:63], v[128:131], v[190:193], v[60:63]
	v_mfma_f32_16x16x32_bf16 v[56:59], v[136:139], v[190:193], v[56:59]
	v_mfma_f32_16x16x32_bf16 v[44:47], v[128:131], v[198:201], v[44:47]
	v_mfma_f32_16x16x32_bf16 v[40:43], v[136:139], v[198:201], v[40:43]
	v_mfma_f32_16x16x32_bf16 v[28:31], v[128:131], v[206:209], v[28:31]
	v_mfma_f32_16x16x32_bf16 v[24:27], v[136:139], v[206:209], v[24:27]
	v_mfma_f32_16x16x32_bf16 v[12:15], v[128:131], v[214:217], v[12:15]
	v_mfma_f32_16x16x32_bf16 v[8:11], v[136:139], v[214:217], v[8:11]
	v_mfma_f32_16x16x32_bf16 v[60:63], v[132:135], v[194:197], v[60:63]
	v_mfma_f32_16x16x32_bf16 v[56:59], v[140:143], v[194:197], v[56:59]
	v_mfma_f32_16x16x32_bf16 v[44:47], v[132:135], v[202:205], v[44:47]
	v_mfma_f32_16x16x32_bf16 v[40:43], v[140:143], v[202:205], v[40:43]
	v_mfma_f32_16x16x32_bf16 v[28:31], v[132:135], v[210:213], v[28:31]
	v_mfma_f32_16x16x32_bf16 v[24:27], v[140:143], v[210:213], v[24:27]
	v_mfma_f32_16x16x32_bf16 v[12:15], v[132:135], v[218:221], v[12:15]
	v_mfma_f32_16x16x32_bf16 v[8:11], v[140:143], v[218:221], v[8:11]
	s_setprio 0
	s_setprio 1
	v_mfma_f32_16x16x32_bf16 v[52:55], v[162:165], v[190:193], v[52:55]
	v_mfma_f32_16x16x32_bf16 v[48:51], v[180:183], v[190:193], v[48:51]
	v_mfma_f32_16x16x32_bf16 v[36:39], v[162:165], v[198:201], v[36:39]
	v_mfma_f32_16x16x32_bf16 v[32:35], v[180:183], v[198:201], v[32:35]
	v_mfma_f32_16x16x32_bf16 v[20:23], v[162:165], v[206:209], v[20:23]
	v_mfma_f32_16x16x32_bf16 v[16:19], v[180:183], v[206:209], v[16:19]
	v_mfma_f32_16x16x32_bf16 v[4:7], v[162:165], v[214:217], v[4:7]
	v_mfma_f32_16x16x32_bf16 v[0:3], v[180:183], v[214:217], v[0:3]
	v_mfma_f32_16x16x32_bf16 v[52:55], v[166:169], v[194:197], v[52:55]
	v_mfma_f32_16x16x32_bf16 v[48:51], v[184:187], v[194:197], v[48:51]
	v_mfma_f32_16x16x32_bf16 v[36:39], v[166:169], v[202:205], v[36:39]
	v_mfma_f32_16x16x32_bf16 v[32:35], v[184:187], v[202:205], v[32:35]
	v_mfma_f32_16x16x32_bf16 v[20:23], v[166:169], v[210:213], v[20:23]
	v_mfma_f32_16x16x32_bf16 v[16:19], v[184:187], v[210:213], v[16:19]
	v_mfma_f32_16x16x32_bf16 v[4:7], v[166:169], v[218:221], v[4:7]
	v_mfma_f32_16x16x32_bf16 v[0:3], v[184:187], v[218:221], v[0:3]
	s_setprio 0
	s_barrier
; #define PG8_STAGE(bufoff, gbase, voff) do { _Pragma("unroll") for (int _i = 0; _i < 2; ++_i) \
;         __builtin_amdgcn_global_load_lds((const unsigned*)((const char*)(gbase) + (voff)[_i]), (PG8_LAS unsigned*)(lds + (bufoff) + ldsw + _i * 8192), 16, 0, 0); } while (0)
; #define PG8_LDA(dst, b, h) do { _Pragma("unroll") for (int m = 0; m < 4; ++m) _Pragma("unroll") for (int k = 0; k < 2; ++k) dst[m][k] = *(const PG8_LAS bf16x8*)(lds + PG8_SA(b, h) + aoff + m * 2048 + k * 1024); } while (0)
; #define PG8_LDB(dst, b, h) do { _Pragma("unroll") for (int n = 0; n < 2; ++n) _Pragma("unroll") for (int k = 0; k < 2; ++k) dst[n][k] = *(const PG8_LAS bf16x8*)(lds + PG8_SB(b, h) + boff + n * 2048 + k * 1024); } while (0)
; #define PG8_MMA(ai, bj, At, Bt) do { __builtin_amdgcn_s_setprio(1); _Pragma("unroll") for (int m = 0; m < 4; ++m) _Pragma("unroll") for (int n = 0; n < 2; ++n) _Pragma("unroll") for (int k = 0; k < 2; ++k) \
;         acc[ai][bj][m][n] = __builtin_amdgcn_mfma_f32_16x16x32_bf16(Bt[n][k], At[m][k], acc[ai][bj][m][n], 0, 0, 0); __builtin_amdgcn_s_setprio(0); } while (0)
; #define PG8_WAIT_V(n) asm volatile("s_waitcnt vmcnt(" #n ")" ::: "memory")
; #define PG8_WAIT_L(n) asm volatile("s_waitcnt lgkmcnt(" #n ")" ::: "memory")
; #define PG8_BAR __builtin_amdgcn_s_barrier()
; template <class Epi, class Sched, bool ALIGN_EPI = false, bool SP2 = false>
; __device__ __forceinline__ void gemm_phase(PG8_LAS unsigned char* lds, const Gemm g, const Sched& S, const Epi& E) {
;     ...
;         for (int t = 0; t < nt; t += 2) {
;             const bool last = (t == nt - 2);
;             const char* a1 = cA + (size_t)(t + 1) * kstep;
;             const char* a2 = last ? nA : cA + (size_t)(t + 2) * kstep; const char* b2 = last ? nB : cB + (size_t)(t + 2) * kstep;
;             const char* a3 = a2 + kstep; const char* b3 = b2 + kstep;
;     ...
;             PG8_LDB(B0, 1, 0); PG8_LDB(B1, 1, 1); PG8_SCHED; PG8_LDA(At, 1, 0); PG8_STAGE(PG8_SA(0, 1), a2 + hstep, voffA);
;             PG8_WAIT_V(8); PG8_WAIT_L(0); PG8_BAR; PG8_MMA(0, 0, At, B0); PG8_MMA(0, 1, At, B1); PG8_BAR; PG8_SCHED;
;             PG8_LDA(At, 1, 1); PG8_STAGE(PG8_SB(1, 0), b3, voffB); PG8_STAGE(PG8_SB(1, 1), b3 + hstep, voffB); PG8_STAGE(PG8_SA(1, 0), a3, voffA);
;             PG8_WAIT_V(8); PG8_WAIT_L(0); PG8_BAR; PG8_MMA(1, 0, At, B0); PG8_MMA(1, 1, At, B1); PG8_BAR; PG8_SCHED;
	s_add_i32 s54, 0, 0x18000
	s_add_i32 s55, 0, 0x1c000
	v_add_u32_e32 v140, s54, v172
	v_add_u32_e32 v152, s55, v172
	ds_read_b128 v[128:131], v140
	ds_read_b128 v[132:135], v140 offset:1024
	ds_read_b128 v[136:139], v140 offset:2048
	ds_read_b128 v[140:143], v140 offset:3072
	ds_read_b128 v[162:165], v152
	ds_read_b128 v[166:169], v152 offset:1024
	ds_read_b128 v[180:183], v152 offset:2048
	ds_read_b128 v[184:187], v152 offset:3072
	s_add_u32 s8, s42, 0x40000
	s_addc_u32 s9, s43, 0
	s_mov_b32 m0, s49
	ds_read_b128 v[190:193], v176 offset:32768
	ds_read_b128 v[194:197], v176 offset:33792
	ds_read_b128 v[198:201], v176 offset:34816
	ds_read_b128 v[202:205], v176 offset:35840
	ds_read_b128 v[206:209], v176 offset:36864
	ds_read_b128 v[210:213], v176 offset:37888
	ds_read_b128 v[214:217], v176 offset:38912
	ds_read_b128 v[218:221], v176 offset:39936
	global_load_lds_dwordx4 v144, s[8:9]
	s_mov_b32 m0, s51
	s_nop 0
	global_load_lds_dwordx4 v148, s[8:9]
	s_waitcnt vmcnt(8)
	s_waitcnt lgkmcnt(0)
	s_barrier
	s_setprio 1
	s_waitcnt lgkmcnt(0)
	v_mfma_f32_16x16x32_bf16 v[124:127], v[128:131], v[190:193], v[124:127]
	v_mfma_f32_16x16x32_bf16 v[120:123], v[136:139], v[190:193], v[120:123]
	v_mfma_f32_16x16x32_bf16 v[108:111], v[128:131], v[198:201], v[108:111]
	v_mfma_f32_16x16x32_bf16 v[104:107], v[136:139], v[198:201], v[104:107]
	v_mfma_f32_16x16x32_bf16 v[92:95], v[128:131], v[206:209], v[92:95]
	v_mfma_f32_16x16x32_bf16 v[88:91], v[136:139], v[206:209], v[88:91]
	v_mfma_f32_16x16x32_bf16 v[76:79], v[128:131], v[214:217], v[76:79]
	v_mfma_f32_16x16x32_bf16 v[72:75], v[136:139], v[214:217], v[72:75]
	v_mfma_f32_16x16x32_bf16 v[124:127], v[132:135], v[194:197], v[124:127]
	v_mfma_f32_16x16x32_bf16 v[120:123], v[140:143], v[194:197], v[120:123]
	v_mfma_f32_16x16x32_bf16 v[108:111], v[132:135], v[202:205], v[108:111]
	v_mfma_f32_16x16x32_bf16 v[104:107], v[140:143], v[202:205], v[104:107]
	v_mfma_f32_16x16x32_bf16 v[92:95], v[132:135], v[210:213], v[92:95]
	v_mfma_f32_16x16x32_bf16 v[88:91], v[140:143], v[210:213], v[88:91]
	v_mfma_f32_16x16x32_bf16 v[76:79], v[132:135], v[218:221], v[76:79]
	v_mfma_f32_16x16x32_bf16 v[72:75], v[140:143], v[218:221], v[72:75]
	s_setprio 0
	s_setprio 1
	v_mfma_f32_16x16x32_bf16 v[116:119], v[162:165], v[190:193], v[116:119]
	v_mfma_f32_16x16x32_bf16 v[112:115], v[180:183], v[190:193], v[112:115]
	v_mfma_f32_16x16x32_bf16 v[100:103], v[162:165], v[198:201], v[100:103]
	v_mfma_f32_16x16x32_bf16 v[96:99], v[180:183], v[198:201], v[96:99]
	v_mfma_f32_16x16x32_bf16 v[84:87], v[162:165], v[206:209], v[84:87]
	v_mfma_f32_16x16x32_bf16 v[80:83], v[180:183], v[206:209], v[80:83]
	v_mfma_f32_16x16x32_bf16 v[68:71], v[162:165], v[214:217], v[68:71]
	v_mfma_f32_16x16x32_bf16 v[64:67], v[180:183], v[214:217], v[64:67]
	v_mfma_f32_16x16x32_bf16 v[116:119], v[166:169], v[194:197], v[116:119]
	v_mfma_f32_16x16x32_bf16 v[112:115], v[184:187], v[194:197], v[112:115]
	v_mfma_f32_16x16x32_bf16 v[100:103], v[166:169], v[202:205], v[100:103]
	v_mfma_f32_16x16x32_bf16 v[96:99], v[184:187], v[202:205], v[96:99]
	v_mfma_f32_16x16x32_bf16 v[84:87], v[166:169], v[210:213], v[84:87]
	v_mfma_f32_16x16x32_bf16 v[80:83], v[184:187], v[210:213], v[80:83]
	v_mfma_f32_16x16x32_bf16 v[68:71], v[166:169], v[218:221], v[68:71]
	v_mfma_f32_16x16x32_bf16 v[64:67], v[184:187], v[218:221], v[64:67]
	s_setprio 0
	s_barrier
	s_add_i32 s8, s54, s46
	v_lshl_add_u64 v[170:171], v[170:171], 0, s[14:15]
	s_mov_b32 m0, s8
	ds_read_b128 v[190:193], v176 offset:49152
	ds_read_b128 v[194:197], v176 offset:50176
	ds_read_b128 v[198:201], v176 offset:51200
	ds_read_b128 v[202:205], v176 offset:52224
	ds_read_b128 v[206:209], v176 offset:53248
	ds_read_b128 v[210:213], v176 offset:54272
	ds_read_b128 v[214:217], v176 offset:55296
	ds_read_b128 v[218:221], v176 offset:56320
	global_load_lds_dwordx4 v[170:171], off
	s_add_i32 m0, s8, 0x2000
	s_add_u32 s8, s40, 0x40080
	v_lshl_add_u64 v[170:171], v[222:223], 0, s[14:15]
	s_addc_u32 s9, s41, 0
	s_add_i32 s40, s55, s46
	global_load_lds_dwordx4 v[170:171], off
	s_mov_b32 m0, s40
	s_nop 0
	global_load_lds_dwordx4 v146, s[8:9]
	s_add_i32 m0, s40, 0x2000
	s_nop 0
	global_load_lds_dwordx4 v150, s[8:9]
	v_lshl_add_u64 v[170:171], v[224:225], 0, s[14:15]
	s_mov_b32 m0, s66
	s_nop 0
	global_load_lds_dwordx4 v[170:171], off
	v_lshl_add_u64 v[170:171], v[226:227], 0, s[14:15]
	s_mov_b32 m0, s67
	s_nop 0
	global_load_lds_dwordx4 v[170:171], off
	s_waitcnt vmcnt(8)
	s_waitcnt lgkmcnt(0)
	s_barrier
	s_setprio 1
	s_waitcnt lgkmcnt(0)
	v_mfma_f32_16x16x32_bf16 v[60:63], v[128:131], v[190:193], v[60:63]
	v_mfma_f32_16x16x32_bf16 v[56:59], v[136:139], v[190:193], v[56:59]
	v_mfma_f32_16x16x32_bf16 v[44:47], v[128:131], v[198:201], v[44:47]
	v_mfma_f32_16x16x32_bf16 v[40:43], v[136:139], v[198:201], v[40:43]
	v_mfma_f32_16x16x32_bf16 v[28:31], v[128:131], v[206:209], v[28:31]
	v_mfma_f32_16x16x32_bf16 v[24:27], v[136:139], v[206:209], v[24:27]
	v_mfma_f32_16x16x32_bf16 v[12:15], v[128:131], v[214:217], v[12:15]
	v_mfma_f32_16x16x32_bf16 v[8:11], v[136:139], v[214:217], v[8:11]
	v_mfma_f32_16x16x32_bf16 v[60:63], v[132:135], v[194:197], v[60:63]
	v_mfma_f32_16x16x32_bf16 v[56:59], v[140:143], v[194:197], v[56:59]
	v_mfma_f32_16x16x32_bf16 v[44:47], v[132:135], v[202:205], v[44:47]
	v_mfma_f32_16x16x32_bf16 v[40:43], v[140:143], v[202:205], v[40:43]
	v_mfma_f32_16x16x32_bf16 v[28:31], v[132:135], v[210:213], v[28:31]
	v_mfma_f32_16x16x32_bf16 v[24:27], v[140:143], v[210:213], v[24:27]
	v_mfma_f32_16x16x32_bf16 v[12:15], v[132:135], v[218:221], v[12:15]
	v_mfma_f32_16x16x32_bf16 v[8:11], v[140:143], v[218:221], v[8:11]
	s_setprio 0
	s_setprio 1
	v_mfma_f32_16x16x32_bf16 v[52:55], v[162:165], v[190:193], v[52:55]
	v_mfma_f32_16x16x32_bf16 v[48:51], v[180:183], v[190:193], v[48:51]
	v_mfma_f32_16x16x32_bf16 v[36:39], v[162:165], v[198:201], v[36:39]
	v_mfma_f32_16x16x32_bf16 v[32:35], v[180:183], v[198:201], v[32:35]
	v_mfma_f32_16x16x32_bf16 v[20:23], v[162:165], v[206:209], v[20:23]
	v_mfma_f32_16x16x32_bf16 v[16:19], v[180:183], v[206:209], v[16:19]
	v_mfma_f32_16x16x32_bf16 v[4:7], v[162:165], v[214:217], v[4:7]
	v_mfma_f32_16x16x32_bf16 v[0:3], v[180:183], v[214:217], v[0:3]
	v_mfma_f32_16x16x32_bf16 v[52:55], v[166:169], v[194:197], v[52:55]
	v_mfma_f32_16x16x32_bf16 v[48:51], v[184:187], v[194:197], v[48:51]
	v_mfma_f32_16x16x32_bf16 v[36:39], v[166:169], v[202:205], v[36:39]
	v_mfma_f32_16x16x32_bf16 v[32:35], v[184:187], v[202:205], v[32:35]
	v_mfma_f32_16x16x32_bf16 v[20:23], v[166:169], v[210:213], v[20:23]
	v_mfma_f32_16x16x32_bf16 v[16:19], v[184:187], v[210:213], v[16:19]
	v_mfma_f32_16x16x32_bf16 v[4:7], v[166:169], v[218:221], v[4:7]
	v_mfma_f32_16x16x32_bf16 v[0:3], v[184:187], v[218:221], v[0:3]
	s_setprio 0
	s_barrier
	s_add_i32 vcc_lo, vcc_lo, 2
	s_add_u32 s0, s0, 0x100
	s_addc_u32 s1, s1, 0
	s_add_u32 s96, s96, 0x100
	s_addc_u32 s97, s97, 0
	s_cmp_gt_u32 vcc_lo, 13
	s_cbranch_scc0 .LBB0_684
	s_and_b64 vcc, exec, s[18:19]
	s_cbranch_vccz .LBB0_687
	s_barrier

; #define PG8_STAGE(bufoff, gbase, voff) do { _Pragma("unroll") for (int _i = 0; _i < 2; ++_i) \
;         __builtin_amdgcn_global_load_lds((const unsigned*)((const char*)(gbase) + (voff)[_i]), (PG8_LAS unsigned*)(lds + (bufoff) + ldsw + _i * 8192), 16, 0, 0); } while (0)
; #define PG8_LDA(dst, b, h) do { _Pragma("unroll") for (int m = 0; m < 4; ++m) _Pragma("unroll") for (int k = 0; k < 2; ++k) dst[m][k] = *(const PG8_LAS bf16x8*)(lds + PG8_SA(b, h) + aoff + m * 2048 + k * 1024); } while (0)
; #define PG8_LDB(dst, b, h) do { _Pragma("unroll") for (int n = 0; n < 2; ++n) _Pragma("unroll") for (int k = 0; k < 2; ++k) dst[n][k] = *(const PG8_LAS bf16x8*)(lds + PG8_SB(b, h) + boff + n * 2048 + k * 1024); } while (0)
; #define PG8_MMA(ai, bj, At, Bt) do { __builtin_amdgcn_s_setprio(1); _Pragma("unroll") for (int m = 0; m < 4; ++m) _Pragma("unroll") for (int n = 0; n < 2; ++n) _Pragma("unroll") for (int k = 0; k < 2; ++k) \
;         acc[ai][bj][m][n] = __builtin_amdgcn_mfma_f32_16x16x32_bf16(Bt[n][k], At[m][k], acc[ai][bj][m][n], 0, 0, 0); __builtin_amdgcn_s_setprio(0); } while (0)
; #define PG8_WAIT_V(n) asm volatile("s_waitcnt vmcnt(" #n ")" ::: "memory")
; #define PG8_WAIT_L(n) asm volatile("s_waitcnt lgkmcnt(" #n ")" ::: "memory")
; #define PG8_BAR __builtin_amdgcn_s_barrier()
; #define PG8_SCHED __builtin_amdgcn_sched_barrier(0)
; template <class Epi, class Sched, bool ALIGN_EPI = false, bool SP2 = false>
; __device__ __forceinline__ void gemm_phase(PG8_LAS unsigned char* lds, const Gemm g, const Sched& S, const Epi& E) {
;     ...
;             PG8_LDB(B0, 0, 0); PG8_LDB(B1, 0, 1); PG8_SCHED; PG8_LDA(At, 0, 0); PG8_STAGE(PG8_SA(1, 1), a1 + hstep, voffA);
;             PG8_WAIT_V(8); PG8_WAIT_L(0); PG8_BAR; PG8_MMA(0, 0, At, B0); PG8_MMA(0, 1, At, B1); PG8_BAR; PG8_SCHED;
;             PG8_LDA(At, 0, 1); PG8_STAGE(PG8_SB(0, 0), b2, voffB); PG8_STAGE(PG8_SB(0, 1), b2 + hstep, voffB); PG8_STAGE(PG8_SA(0, 0), a2, voffA);
;             PG8_WAIT_V(8); PG8_WAIT_L(0); PG8_BAR; PG8_MMA(1, 0, At, B0); PG8_MMA(1, 1, At, B1); PG8_BAR; PG8_SCHED;
.LBB0_795:
	v_add_u32_e32 v162, s67, v186
	v_add_u32_e32 v178, s68, v186
	ds_read_b128 v[150:153], v162
	ds_read_b128 v[154:157], v162 offset:1024
	ds_read_b128 v[158:161], v162 offset:2048
	ds_read_b128 v[162:165], v162 offset:3072
	ds_read_b128 v[166:169], v178
	ds_read_b128 v[170:173], v178 offset:1024
	ds_read_b128 v[174:177], v178 offset:2048
	ds_read_b128 v[178:181], v178 offset:3072
	s_add_u32 s54, s46, 0xfff80080
	s_addc_u32 s55, s47, -1
	s_cmp_eq_u32 s82, 12
	s_cselect_b32 s57, s41, s55
	s_cselect_b32 s56, s78, s54
	s_cselect_b32 s55, s39, s81
	s_cselect_b32 s54, s79, s80
	s_add_i32 m0, s61, 0xc000
	ds_read_b128 v[182:185], v187
	ds_read_b128 v[190:193], v187 offset:1024
	ds_read_b128 v[194:197], v187 offset:2048
	ds_read_b128 v[198:201], v187 offset:3072
	ds_read_b128 v[202:205], v187 offset:4096
	ds_read_b128 v[206:209], v187 offset:5120
	ds_read_b128 v[210:213], v187 offset:6144
	ds_read_b128 v[214:217], v187 offset:7168
	global_load_lds_dwordx4 v142, s[46:47]
	s_add_i32 m0, s61, 0xe000
	s_nop 0
	global_load_lds_dwordx4 v144, s[46:47]
	s_waitcnt vmcnt(8)
	s_waitcnt lgkmcnt(0)
	s_barrier
	s_setprio 1
	s_waitcnt lgkmcnt(0)
	v_mfma_f32_16x16x32_bf16 v[124:127], v[150:153], v[182:185], v[124:127]
	v_mfma_f32_16x16x32_bf16 v[120:123], v[158:161], v[182:185], v[120:123]
	v_mfma_f32_16x16x32_bf16 v[116:119], v[150:153], v[194:197], v[116:119]
	v_mfma_f32_16x16x32_bf16 v[112:115], v[158:161], v[194:197], v[112:115]
	v_mfma_f32_16x16x32_bf16 v[108:111], v[150:153], v[202:205], v[108:111]
	v_mfma_f32_16x16x32_bf16 v[104:107], v[158:161], v[202:205], v[104:107]
	v_mfma_f32_16x16x32_bf16 v[100:103], v[150:153], v[210:213], v[100:103]
	v_mfma_f32_16x16x32_bf16 v[96:99], v[158:161], v[210:213], v[96:99]
	v_mfma_f32_16x16x32_bf16 v[124:127], v[154:157], v[190:193], v[124:127]
	v_mfma_f32_16x16x32_bf16 v[120:123], v[162:165], v[190:193], v[120:123]
	v_mfma_f32_16x16x32_bf16 v[116:119], v[154:157], v[198:201], v[116:119]
	v_mfma_f32_16x16x32_bf16 v[112:115], v[162:165], v[198:201], v[112:115]
	v_mfma_f32_16x16x32_bf16 v[108:111], v[154:157], v[206:209], v[108:111]
	v_mfma_f32_16x16x32_bf16 v[104:107], v[162:165], v[206:209], v[104:107]
	v_mfma_f32_16x16x32_bf16 v[100:103], v[154:157], v[214:217], v[100:103]
	v_mfma_f32_16x16x32_bf16 v[96:99], v[162:165], v[214:217], v[96:99]
	s_setprio 0
	s_setprio 1
	v_mfma_f32_16x16x32_bf16 v[92:95], v[166:169], v[182:185], v[92:95]
	v_mfma_f32_16x16x32_bf16 v[88:91], v[174:177], v[182:185], v[88:91]
	v_mfma_f32_16x16x32_bf16 v[84:87], v[166:169], v[194:197], v[84:87]
	v_mfma_f32_16x16x32_bf16 v[80:83], v[174:177], v[194:197], v[80:83]
	v_mfma_f32_16x16x32_bf16 v[76:79], v[166:169], v[202:205], v[76:79]
	v_mfma_f32_16x16x32_bf16 v[72:75], v[174:177], v[202:205], v[72:75]
	v_mfma_f32_16x16x32_bf16 v[68:71], v[166:169], v[210:213], v[68:71]
	v_mfma_f32_16x16x32_bf16 v[64:67], v[174:177], v[210:213], v[64:67]
	v_mfma_f32_16x16x32_bf16 v[92:95], v[170:173], v[190:193], v[92:95]
	v_mfma_f32_16x16x32_bf16 v[88:91], v[178:181], v[190:193], v[88:91]
	v_mfma_f32_16x16x32_bf16 v[84:87], v[170:173], v[198:201], v[84:87]
	v_mfma_f32_16x16x32_bf16 v[80:83], v[178:181], v[198:201], v[80:83]
	v_mfma_f32_16x16x32_bf16 v[76:79], v[170:173], v[206:209], v[76:79]
	v_mfma_f32_16x16x32_bf16 v[72:75], v[178:181], v[206:209], v[72:75]
	v_mfma_f32_16x16x32_bf16 v[68:71], v[170:173], v[214:217], v[68:71]
	v_mfma_f32_16x16x32_bf16 v[64:67], v[178:181], v[214:217], v[64:67]
	s_setprio 0
	s_barrier
	s_add_i32 s83, s67, s60
	v_lshl_add_u64 v[218:219], s[54:55], 0, v[130:131]
	s_mov_b32 m0, s83
	ds_read_b128 v[182:185], v187 offset:16384
	ds_read_b128 v[190:193], v187 offset:17408
	ds_read_b128 v[194:197], v187 offset:18432
	ds_read_b128 v[198:201], v187 offset:19456
	ds_read_b128 v[202:205], v187 offset:20480
	ds_read_b128 v[206:209], v187 offset:21504
	ds_read_b128 v[210:213], v187 offset:22528
	ds_read_b128 v[214:217], v187 offset:23552
	global_load_lds_dwordx4 v[218:219], off
	s_add_i32 m0, s83, 0x2000
	s_add_u32 s86, s54, 0x80000
	v_lshl_add_u64 v[220:221], s[54:55], 0, v[134:135]
	s_addc_u32 s87, s55, 0
	s_add_i32 s83, s68, s60
	global_load_lds_dwordx4 v[220:221], off
	s_mov_b32 m0, s83
	v_lshl_add_u64 v[224:225], s[56:57], 0, v[132:133]
	global_load_lds_dwordx4 v130, s[86:87]
	s_add_i32 m0, s83, 0x2000
	s_nop 0
	global_load_lds_dwordx4 v134, s[86:87]
	v_lshl_add_u64 v[222:223], s[56:57], 0, v[128:129]
	s_mov_b32 m0, s61
	s_nop 0
	global_load_lds_dwordx4 v[222:223], off
	s_mov_b32 m0, s62
	s_nop 0
	global_load_lds_dwordx4 v[224:225], off
	s_waitcnt vmcnt(8)
	s_waitcnt lgkmcnt(0)
	s_barrier
; #define PG8_STAGE(bufoff, gbase, voff) do { _Pragma("unroll") for (int _i = 0; _i < 2; ++_i) \
;         __builtin_amdgcn_global_load_lds((const unsigned*)((const char*)(gbase) + (voff)[_i]), (PG8_LAS unsigned*)(lds + (bufoff) + ldsw + _i * 8192), 16, 0, 0); } while (0)
; #define PG8_LDA(dst, b, h) do { _Pragma("unroll") for (int m = 0; m < 4; ++m) _Pragma("unroll") for (int k = 0; k < 2; ++k) dst[m][k] = *(const PG8_LAS bf16x8*)(lds + PG8_SA(b, h) + aoff + m * 2048 + k * 1024); } while (0)
; #define PG8_LDB(dst, b, h) do { _Pragma("unroll") for (int n = 0; n < 2; ++n) _Pragma("unroll") for (int k = 0; k < 2; ++k) dst[n][k] = *(const PG8_LAS bf16x8*)(lds + PG8_SB(b, h) + boff + n * 2048 + k * 1024); } while (0)
; #define PG8_MMA(ai, bj, At, Bt) do { __builtin_amdgcn_s_setprio(1); _Pragma("unroll") for (int m = 0; m < 4; ++m) _Pragma("unroll") for (int n = 0; n < 2; ++n) _Pragma("unroll") for (int k = 0; k < 2; ++k) \
;         acc[ai][bj][m][n] = __builtin_amdgcn_mfma_f32_16x16x32_bf16(Bt[n][k], At[m][k], acc[ai][bj][m][n], 0, 0, 0); __builtin_amdgcn_s_setprio(0); } while (0)
; #define PG8_WAIT_V(n) asm volatile("s_waitcnt vmcnt(" #n ")" ::: "memory")
; #define PG8_WAIT_L(n) asm volatile("s_waitcnt lgkmcnt(" #n ")" ::: "memory")
; #define PG8_BAR __builtin_amdgcn_s_barrier()
; #define PG8_SCHED __builtin_amdgcn_sched_barrier(0)
; template <class Epi, class Sched, bool ALIGN_EPI = false, bool SP2 = false>
; __device__ __forceinline__ void gemm_phase(PG8_LAS unsigned char* lds, const Gemm g, const Sched& S, const Epi& E) {
;     ...
;             PG8_WAIT_V(8); PG8_WAIT_L(0); PG8_BAR; PG8_MMA(1, 0, At, B0); PG8_MMA(1, 1, At, B1); PG8_BAR; PG8_SCHED;
;             PG8_LDB(B0, 1, 0); PG8_LDB(B1, 1, 1); PG8_SCHED; PG8_LDA(At, 1, 0); PG8_STAGE(PG8_SA(0, 1), a2 + hstep, voffA);
;             PG8_WAIT_V(8); PG8_WAIT_L(0); PG8_BAR; PG8_MMA(0, 0, At, B0); PG8_MMA(0, 1, At, B1); PG8_BAR; PG8_SCHED;
	s_setprio 1
	s_waitcnt lgkmcnt(0)
	v_mfma_f32_16x16x32_bf16 v[60:63], v[150:153], v[182:185], v[60:63]
	v_mfma_f32_16x16x32_bf16 v[56:59], v[158:161], v[182:185], v[56:59]
	v_mfma_f32_16x16x32_bf16 v[52:55], v[150:153], v[194:197], v[52:55]
	v_mfma_f32_16x16x32_bf16 v[48:51], v[158:161], v[194:197], v[48:51]
	v_mfma_f32_16x16x32_bf16 v[44:47], v[150:153], v[202:205], v[44:47]
	v_mfma_f32_16x16x32_bf16 v[40:43], v[158:161], v[202:205], v[40:43]
	v_mfma_f32_16x16x32_bf16 v[36:39], v[150:153], v[210:213], v[36:39]
	v_mfma_f32_16x16x32_bf16 v[32:35], v[158:161], v[210:213], v[32:35]
	v_mfma_f32_16x16x32_bf16 v[60:63], v[154:157], v[190:193], v[60:63]
	v_mfma_f32_16x16x32_bf16 v[56:59], v[162:165], v[190:193], v[56:59]
	v_mfma_f32_16x16x32_bf16 v[52:55], v[154:157], v[198:201], v[52:55]
	v_mfma_f32_16x16x32_bf16 v[48:51], v[162:165], v[198:201], v[48:51]
	v_mfma_f32_16x16x32_bf16 v[44:47], v[154:157], v[206:209], v[44:47]
	v_mfma_f32_16x16x32_bf16 v[40:43], v[162:165], v[206:209], v[40:43]
	v_mfma_f32_16x16x32_bf16 v[36:39], v[154:157], v[214:217], v[36:39]
	v_mfma_f32_16x16x32_bf16 v[32:35], v[162:165], v[214:217], v[32:35]
	s_setprio 0
	s_setprio 1
	v_mfma_f32_16x16x32_bf16 v[28:31], v[166:169], v[182:185], v[28:31]
	v_mfma_f32_16x16x32_bf16 v[24:27], v[174:177], v[182:185], v[24:27]
	v_mfma_f32_16x16x32_bf16 v[20:23], v[166:169], v[194:197], v[20:23]
	v_mfma_f32_16x16x32_bf16 v[16:19], v[174:177], v[194:197], v[16:19]
	v_mfma_f32_16x16x32_bf16 v[12:15], v[166:169], v[202:205], v[12:15]
	v_mfma_f32_16x16x32_bf16 v[8:11], v[174:177], v[202:205], v[8:11]
	v_mfma_f32_16x16x32_bf16 v[4:7], v[166:169], v[210:213], v[4:7]
	v_mfma_f32_16x16x32_bf16 v[0:3], v[174:177], v[210:213], v[0:3]
	v_mfma_f32_16x16x32_bf16 v[28:31], v[170:173], v[190:193], v[28:31]
	v_mfma_f32_16x16x32_bf16 v[24:27], v[178:181], v[190:193], v[24:27]
	v_mfma_f32_16x16x32_bf16 v[20:23], v[170:173], v[198:201], v[20:23]
	v_mfma_f32_16x16x32_bf16 v[16:19], v[178:181], v[198:201], v[16:19]
	v_mfma_f32_16x16x32_bf16 v[12:15], v[170:173], v[206:209], v[12:15]
	v_mfma_f32_16x16x32_bf16 v[8:11], v[178:181], v[206:209], v[8:11]
	v_mfma_f32_16x16x32_bf16 v[4:7], v[170:173], v[214:217], v[4:7]
	v_mfma_f32_16x16x32_bf16 v[0:3], v[178:181], v[214:217], v[0:3]
	s_setprio 0
	s_barrier
	s_add_i32 s83, 0, 0x18000
	s_add_i32 s86, 0, 0x1c000
	v_add_u32_e32 v162, s83, v186
	v_add_u32_e32 v178, s86, v186
	ds_read_b128 v[150:153], v162
	ds_read_b128 v[154:157], v162 offset:1024
	ds_read_b128 v[158:161], v162 offset:2048
	ds_read_b128 v[162:165], v162 offset:3072
	ds_read_b128 v[166:169], v178
	ds_read_b128 v[170:173], v178 offset:1024
	ds_read_b128 v[174:177], v178 offset:2048
	ds_read_b128 v[178:181], v178 offset:3072
	s_add_u32 s56, s56, 0x80000
	s_addc_u32 s57, s57, 0
	s_mov_b32 m0, s63
	ds_read_b128 v[182:185], v187 offset:32768
	ds_read_b128 v[190:193], v187 offset:33792
	ds_read_b128 v[194:197], v187 offset:34816
	ds_read_b128 v[198:201], v187 offset:35840
	ds_read_b128 v[202:205], v187 offset:36864
	ds_read_b128 v[206:209], v187 offset:37888
	ds_read_b128 v[210:213], v187 offset:38912
	ds_read_b128 v[214:217], v187 offset:39936
	global_load_lds_dwordx4 v128, s[56:57]
	s_mov_b32 m0, s64
	s_nop 0
	global_load_lds_dwordx4 v132, s[56:57]
	s_waitcnt vmcnt(8)
	s_waitcnt lgkmcnt(0)
	s_barrier
	s_setprio 1
	s_waitcnt lgkmcnt(0)
	v_mfma_f32_16x16x32_bf16 v[124:127], v[150:153], v[182:185], v[124:127]
	v_mfma_f32_16x16x32_bf16 v[120:123], v[158:161], v[182:185], v[120:123]
	v_mfma_f32_16x16x32_bf16 v[116:119], v[150:153], v[194:197], v[116:119]
	v_mfma_f32_16x16x32_bf16 v[112:115], v[158:161], v[194:197], v[112:115]
	v_mfma_f32_16x16x32_bf16 v[108:111], v[150:153], v[202:205], v[108:111]
	v_mfma_f32_16x16x32_bf16 v[104:107], v[158:161], v[202:205], v[104:107]
	v_mfma_f32_16x16x32_bf16 v[100:103], v[150:153], v[210:213], v[100:103]
	v_mfma_f32_16x16x32_bf16 v[96:99], v[158:161], v[210:213], v[96:99]
	v_mfma_f32_16x16x32_bf16 v[124:127], v[154:157], v[190:193], v[124:127]
	v_mfma_f32_16x16x32_bf16 v[120:123], v[162:165], v[190:193], v[120:123]
	v_mfma_f32_16x16x32_bf16 v[116:119], v[154:157], v[198:201], v[116:119]
	v_mfma_f32_16x16x32_bf16 v[112:115], v[162:165], v[198:201], v[112:115]
	v_mfma_f32_16x16x32_bf16 v[108:111], v[154:157], v[206:209], v[108:111]
	v_mfma_f32_16x16x32_bf16 v[104:107], v[162:165], v[206:209], v[104:107]
	v_mfma_f32_16x16x32_bf16 v[100:103], v[154:157], v[214:217], v[100:103]
	v_mfma_f32_16x16x32_bf16 v[96:99], v[162:165], v[214:217], v[96:99]
	s_setprio 0
	s_setprio 1
	v_mfma_f32_16x16x32_bf16 v[92:95], v[166:169], v[182:185], v[92:95]
	v_mfma_f32_16x16x32_bf16 v[88:91], v[174:177], v[182:185], v[88:91]
	v_mfma_f32_16x16x32_bf16 v[84:87], v[166:169], v[194:197], v[84:87]
	v_mfma_f32_16x16x32_bf16 v[80:83], v[174:177], v[194:197], v[80:83]
	v_mfma_f32_16x16x32_bf16 v[76:79], v[166:169], v[202:205], v[76:79]
	v_mfma_f32_16x16x32_bf16 v[72:75], v[174:177], v[202:205], v[72:75]
	v_mfma_f32_16x16x32_bf16 v[68:71], v[166:169], v[210:213], v[68:71]
	v_mfma_f32_16x16x32_bf16 v[64:67], v[174:177], v[210:213], v[64:67]
	v_mfma_f32_16x16x32_bf16 v[92:95], v[170:173], v[190:193], v[92:95]
	v_mfma_f32_16x16x32_bf16 v[88:91], v[178:181], v[190:193], v[88:91]
	v_mfma_f32_16x16x32_bf16 v[84:87], v[170:173], v[198:201], v[84:87]
	v_mfma_f32_16x16x32_bf16 v[80:83], v[178:181], v[198:201], v[80:83]
	v_mfma_f32_16x16x32_bf16 v[76:79], v[170:173], v[206:209], v[76:79]
	v_mfma_f32_16x16x32_bf16 v[72:75], v[178:181], v[206:209], v[72:75]
	v_mfma_f32_16x16x32_bf16 v[68:71], v[170:173], v[214:217], v[68:71]
	v_mfma_f32_16x16x32_bf16 v[64:67], v[178:181], v[214:217], v[64:67]
	s_setprio 0
	s_barrier
; #define PG8_STAGE(bufoff, gbase, voff) do { _Pragma("unroll") for (int _i = 0; _i < 2; ++_i) \
;         __builtin_amdgcn_global_load_lds((const unsigned*)((const char*)(gbase) + (voff)[_i]), (PG8_LAS unsigned*)(lds + (bufoff) + ldsw + _i * 8192), 16, 0, 0); } while (0)
; #define PG8_LDA(dst, b, h) do { _Pragma("unroll") for (int m = 0; m < 4; ++m) _Pragma("unroll") for (int k = 0; k < 2; ++k) dst[m][k] = *(const PG8_LAS bf16x8*)(lds + PG8_SA(b, h) + aoff + m * 2048 + k * 1024); } while (0)
; #define PG8_MMA(ai, bj, At, Bt) do { __builtin_amdgcn_s_setprio(1); _Pragma("unroll") for (int m = 0; m < 4; ++m) _Pragma("unroll") for (int n = 0; n < 2; ++n) _Pragma("unroll") for (int k = 0; k < 2; ++k) \
;         acc[ai][bj][m][n] = __builtin_amdgcn_mfma_f32_16x16x32_bf16(Bt[n][k], At[m][k], acc[ai][bj][m][n], 0, 0, 0); __builtin_amdgcn_s_setprio(0); } while (0)
; #define PG8_WAIT_V(n) asm volatile("s_waitcnt vmcnt(" #n ")" ::: "memory")
; #define PG8_WAIT_L(n) asm volatile("s_waitcnt lgkmcnt(" #n ")" ::: "memory")
; #define PG8_BAR __builtin_amdgcn_s_barrier()
; #define PG8_SCHED __builtin_amdgcn_sched_barrier(0)
; template <class Epi, class Sched, bool ALIGN_EPI = false, bool SP2 = false>
; __device__ __forceinline__ void gemm_phase(PG8_LAS unsigned char* lds, const Gemm g, const Sched& S, const Epi& E) {
;     ...
;         for (int t = 0; t < nt; t += 2) {
;             const bool last = (t == nt - 2);
;             const char* a1 = cA + (size_t)(t + 1) * kstep;
;             const char* a2 = last ? nA : cA + (size_t)(t + 2) * kstep; const char* b2 = last ? nB : cB + (size_t)(t + 2) * kstep;
;             const char* a3 = a2 + kstep; const char* b3 = b2 + kstep;
;     ...
;             PG8_LDA(At, 1, 1); PG8_STAGE(PG8_SB(1, 0), b3, voffB); PG8_STAGE(PG8_SB(1, 1), b3 + hstep, voffB); PG8_STAGE(PG8_SA(1, 0), a3, voffA);
;             PG8_WAIT_V(8); PG8_WAIT_L(0); PG8_BAR; PG8_MMA(1, 0, At, B0); PG8_MMA(1, 1, At, B1); PG8_BAR; PG8_SCHED;
	s_add_i32 s56, s83, s60
	v_lshl_add_u64 v[218:219], v[218:219], 0, s[14:15]
	s_mov_b32 m0, s56
	ds_read_b128 v[182:185], v187 offset:49152
	ds_read_b128 v[190:193], v187 offset:50176
	ds_read_b128 v[194:197], v187 offset:51200
	ds_read_b128 v[198:201], v187 offset:52224
	ds_read_b128 v[202:205], v187 offset:53248
	ds_read_b128 v[206:209], v187 offset:54272
	ds_read_b128 v[210:213], v187 offset:55296
	ds_read_b128 v[214:217], v187 offset:56320
	global_load_lds_dwordx4 v[218:219], off
	s_add_i32 m0, s56, 0x2000
	s_add_u32 s54, s54, 0x80080
	v_lshl_add_u64 v[218:219], v[220:221], 0, s[14:15]
	s_addc_u32 s55, s55, 0
	s_add_i32 s56, s86, s60
	global_load_lds_dwordx4 v[218:219], off
	s_mov_b32 m0, s56
	s_nop 0
	global_load_lds_dwordx4 v130, s[54:55]
	s_add_i32 m0, s56, 0x2000
	s_nop 0
	global_load_lds_dwordx4 v134, s[54:55]
	v_lshl_add_u64 v[218:219], v[222:223], 0, s[14:15]
	s_mov_b32 m0, s65
	s_nop 0
	global_load_lds_dwordx4 v[218:219], off
	v_lshl_add_u64 v[218:219], v[224:225], 0, s[14:15]
	s_mov_b32 m0, s66
	s_nop 0
	global_load_lds_dwordx4 v[218:219], off
	s_waitcnt vmcnt(8)
	s_waitcnt lgkmcnt(0)
	s_barrier
	s_setprio 1
	s_waitcnt lgkmcnt(0)
	v_mfma_f32_16x16x32_bf16 v[60:63], v[150:153], v[182:185], v[60:63]
	v_mfma_f32_16x16x32_bf16 v[56:59], v[158:161], v[182:185], v[56:59]
	v_mfma_f32_16x16x32_bf16 v[52:55], v[150:153], v[194:197], v[52:55]
	v_mfma_f32_16x16x32_bf16 v[48:51], v[158:161], v[194:197], v[48:51]
	v_mfma_f32_16x16x32_bf16 v[44:47], v[150:153], v[202:205], v[44:47]
	v_mfma_f32_16x16x32_bf16 v[40:43], v[158:161], v[202:205], v[40:43]
	v_mfma_f32_16x16x32_bf16 v[36:39], v[150:153], v[210:213], v[36:39]
	v_mfma_f32_16x16x32_bf16 v[32:35], v[158:161], v[210:213], v[32:35]
	v_mfma_f32_16x16x32_bf16 v[60:63], v[154:157], v[190:193], v[60:63]
	v_mfma_f32_16x16x32_bf16 v[56:59], v[162:165], v[190:193], v[56:59]
	v_mfma_f32_16x16x32_bf16 v[52:55], v[154:157], v[198:201], v[52:55]
	v_mfma_f32_16x16x32_bf16 v[48:51], v[162:165], v[198:201], v[48:51]
	v_mfma_f32_16x16x32_bf16 v[44:47], v[154:157], v[206:209], v[44:47]
	v_mfma_f32_16x16x32_bf16 v[40:43], v[162:165], v[206:209], v[40:43]
	v_mfma_f32_16x16x32_bf16 v[36:39], v[154:157], v[214:217], v[36:39]
	v_mfma_f32_16x16x32_bf16 v[32:35], v[162:165], v[214:217], v[32:35]
	s_setprio 0
	s_setprio 1
	v_mfma_f32_16x16x32_bf16 v[28:31], v[166:169], v[182:185], v[28:31]
	v_mfma_f32_16x16x32_bf16 v[24:27], v[174:177], v[182:185], v[24:27]
	v_mfma_f32_16x16x32_bf16 v[20:23], v[166:169], v[194:197], v[20:23]
	v_mfma_f32_16x16x32_bf16 v[16:19], v[174:177], v[194:197], v[16:19]
	v_mfma_f32_16x16x32_bf16 v[12:15], v[166:169], v[202:205], v[12:15]
	v_mfma_f32_16x16x32_bf16 v[8:11], v[174:177], v[202:205], v[8:11]
	v_mfma_f32_16x16x32_bf16 v[4:7], v[166:169], v[210:213], v[4:7]
	v_mfma_f32_16x16x32_bf16 v[0:3], v[174:177], v[210:213], v[0:3]
	v_mfma_f32_16x16x32_bf16 v[28:31], v[170:173], v[190:193], v[28:31]
	v_mfma_f32_16x16x32_bf16 v[24:27], v[178:181], v[190:193], v[24:27]
	v_mfma_f32_16x16x32_bf16 v[20:23], v[170:173], v[198:201], v[20:23]
	v_mfma_f32_16x16x32_bf16 v[16:19], v[178:181], v[198:201], v[16:19]
	v_mfma_f32_16x16x32_bf16 v[12:15], v[170:173], v[206:209], v[12:15]
	v_mfma_f32_16x16x32_bf16 v[8:11], v[178:181], v[206:209], v[8:11]
	v_mfma_f32_16x16x32_bf16 v[4:7], v[170:173], v[214:217], v[4:7]
	v_mfma_f32_16x16x32_bf16 v[0:3], v[178:181], v[214:217], v[0:3]
	s_setprio 0
	s_barrier
	s_add_i32 s82, s82, 2
	s_add_u32 s46, s46, 0x100
	s_addc_u32 s47, s47, 0
	s_add_u32 s80, s80, 0x100
	s_addc_u32 s81, s81, 0
	s_cmp_gt_u32 s82, 13
	s_cbranch_scc0 .LBB0_795
	s_and_b64 vcc, exec, s[16:17]
	s_cbranch_vccz .LBB0_798
	s_barrier

; #define PG8_STAGE(bufoff, gbase, voff) do { _Pragma("unroll") for (int _i = 0; _i < 2; ++_i) \
;         __builtin_amdgcn_global_load_lds((const unsigned*)((const char*)(gbase) + (voff)[_i]), (PG8_LAS unsigned*)(lds + (bufoff) + ldsw + _i * 8192), 16, 0, 0); } while (0)
; #define PG8_LDA(dst, b, h) do { _Pragma("unroll") for (int m = 0; m < 4; ++m) _Pragma("unroll") for (int k = 0; k < 2; ++k) dst[m][k] = *(const PG8_LAS bf16x8*)(lds + PG8_SA(b, h) + aoff + m * 2048 + k * 1024); } while (0)
; #define PG8_LDB(dst, b, h) do { _Pragma("unroll") for (int n = 0; n < 2; ++n) _Pragma("unroll") for (int k = 0; k < 2; ++k) dst[n][k] = *(const PG8_LAS bf16x8*)(lds + PG8_SB(b, h) + boff + n * 2048 + k * 1024); } while (0)
; #define PG8_MMA(ai, bj, At, Bt) do { __builtin_amdgcn_s_setprio(1); _Pragma("unroll") for (int m = 0; m < 4; ++m) _Pragma("unroll") for (int n = 0; n < 2; ++n) _Pragma("unroll") for (int k = 0; k < 2; ++k) \
;         acc[ai][bj][m][n] = __builtin_amdgcn_mfma_f32_16x16x32_bf16(Bt[n][k], At[m][k], acc[ai][bj][m][n], 0, 0, 0); __builtin_amdgcn_s_setprio(0); } while (0)
; #define PG8_WAIT_V(n) asm volatile("s_waitcnt vmcnt(" #n ")" ::: "memory")
; #define PG8_WAIT_L(n) asm volatile("s_waitcnt lgkmcnt(" #n ")" ::: "memory")
; #define PG8_BAR __builtin_amdgcn_s_barrier()
; #define PG8_SCHED __builtin_amdgcn_sched_barrier(0)
; template <class Epi, class Sched, bool ALIGN_EPI = false, bool SP2 = false>
; __device__ __forceinline__ void gemm_phase(PG8_LAS unsigned char* lds, const Gemm g, const Sched& S, const Epi& E) {
;     ...
;             PG8_LDB(B0, 0, 0); PG8_LDB(B1, 0, 1); PG8_SCHED; PG8_LDA(At, 0, 0); PG8_STAGE(PG8_SA(1, 1), a1 + hstep, voffA);
;             PG8_WAIT_V(8); PG8_WAIT_L(0); PG8_BAR; PG8_MMA(0, 0, At, B0); PG8_MMA(0, 1, At, B1); PG8_BAR; PG8_SCHED;
;             PG8_LDA(At, 0, 1); PG8_STAGE(PG8_SB(0, 0), b2, voffB); PG8_STAGE(PG8_SB(0, 1), b2 + hstep, voffB); PG8_STAGE(PG8_SA(0, 0), a2, voffA);
;             PG8_WAIT_V(8); PG8_WAIT_L(0); PG8_BAR; PG8_MMA(1, 0, At, B0); PG8_MMA(1, 1, At, B1); PG8_BAR; PG8_SCHED;
.LBB0_882:
	ds_read_b128 v[128:131], v173
	ds_read_b128 v[132:135], v173 offset:1024
	ds_read_b128 v[136:139], v173 offset:2048
	ds_read_b128 v[140:143], v173 offset:3072
	ds_read_b128 v[164:167], v174
	ds_read_b128 v[168:171], v174 offset:1024
	ds_read_b128 v[178:181], v174 offset:2048
	ds_read_b128 v[182:185], v174 offset:3072
	s_add_u32 s34, s30, 0xfffc0080
	s_addc_u32 s35, s31, -1
	s_cmp_eq_u32 s61, 12
	s_cselect_b32 s37, s23, s35
	s_cselect_b32 s36, s29, s34
	s_cselect_b32 s35, s21, s60
	s_cselect_b32 s34, s58, s59
	s_add_i32 m0, s43, 0xc000
	ds_read_b128 v[190:193], v175
	ds_read_b128 v[194:197], v175 offset:1024
	ds_read_b128 v[198:201], v175 offset:2048
	ds_read_b128 v[202:205], v175 offset:3072
	ds_read_b128 v[206:209], v175 offset:4096
	ds_read_b128 v[210:213], v175 offset:5120
	ds_read_b128 v[214:217], v175 offset:6144
	ds_read_b128 v[218:221], v175 offset:7168
	global_load_lds_dwordx4 v156, s[30:31]
	s_add_i32 m0, s43, 0xe000
	s_nop 0
	global_load_lds_dwordx4 v158, s[30:31]
	s_waitcnt vmcnt(8)
	s_waitcnt lgkmcnt(0)
	s_barrier
	s_setprio 1
	s_waitcnt lgkmcnt(0)
	v_mfma_f32_16x16x32_bf16 v[124:127], v[128:131], v[190:193], v[124:127]
	v_mfma_f32_16x16x32_bf16 v[120:123], v[136:139], v[190:193], v[120:123]
	v_mfma_f32_16x16x32_bf16 v[108:111], v[128:131], v[198:201], v[108:111]
	v_mfma_f32_16x16x32_bf16 v[104:107], v[136:139], v[198:201], v[104:107]
	v_mfma_f32_16x16x32_bf16 v[92:95], v[128:131], v[206:209], v[92:95]
	v_mfma_f32_16x16x32_bf16 v[88:91], v[136:139], v[206:209], v[88:91]
	v_mfma_f32_16x16x32_bf16 v[76:79], v[128:131], v[214:217], v[76:79]
	v_mfma_f32_16x16x32_bf16 v[72:75], v[136:139], v[214:217], v[72:75]
	v_mfma_f32_16x16x32_bf16 v[124:127], v[132:135], v[194:197], v[124:127]
	v_mfma_f32_16x16x32_bf16 v[120:123], v[140:143], v[194:197], v[120:123]
	v_mfma_f32_16x16x32_bf16 v[108:111], v[132:135], v[202:205], v[108:111]
	v_mfma_f32_16x16x32_bf16 v[104:107], v[140:143], v[202:205], v[104:107]
	v_mfma_f32_16x16x32_bf16 v[92:95], v[132:135], v[210:213], v[92:95]
	v_mfma_f32_16x16x32_bf16 v[88:91], v[140:143], v[210:213], v[88:91]
	v_mfma_f32_16x16x32_bf16 v[76:79], v[132:135], v[218:221], v[76:79]
	v_mfma_f32_16x16x32_bf16 v[72:75], v[140:143], v[218:221], v[72:75]
	s_setprio 0
	s_setprio 1
	v_mfma_f32_16x16x32_bf16 v[116:119], v[164:167], v[190:193], v[116:119]
	v_mfma_f32_16x16x32_bf16 v[112:115], v[178:181], v[190:193], v[112:115]
	v_mfma_f32_16x16x32_bf16 v[100:103], v[164:167], v[198:201], v[100:103]
	v_mfma_f32_16x16x32_bf16 v[96:99], v[178:181], v[198:201], v[96:99]
	v_mfma_f32_16x16x32_bf16 v[84:87], v[164:167], v[206:209], v[84:87]
	v_mfma_f32_16x16x32_bf16 v[80:83], v[178:181], v[206:209], v[80:83]
	v_mfma_f32_16x16x32_bf16 v[68:71], v[164:167], v[214:217], v[68:71]
	v_mfma_f32_16x16x32_bf16 v[64:67], v[178:181], v[214:217], v[64:67]
	v_mfma_f32_16x16x32_bf16 v[116:119], v[168:171], v[194:197], v[116:119]
	v_mfma_f32_16x16x32_bf16 v[112:115], v[182:185], v[194:197], v[112:115]
	v_mfma_f32_16x16x32_bf16 v[100:103], v[168:171], v[202:205], v[100:103]
	v_mfma_f32_16x16x32_bf16 v[96:99], v[182:185], v[202:205], v[96:99]
	v_mfma_f32_16x16x32_bf16 v[84:87], v[168:171], v[210:213], v[84:87]
	v_mfma_f32_16x16x32_bf16 v[80:83], v[182:185], v[210:213], v[80:83]
	v_mfma_f32_16x16x32_bf16 v[68:71], v[168:171], v[218:221], v[68:71]
	v_mfma_f32_16x16x32_bf16 v[64:67], v[182:185], v[218:221], v[64:67]
	s_setprio 0
	s_barrier
	s_add_i32 s62, s55, s42
	v_lshl_add_u64 v[186:187], s[34:35], 0, v[146:147]
	s_mov_b32 m0, s62
	ds_read_b128 v[190:193], v175 offset:16384
	ds_read_b128 v[194:197], v175 offset:17408
	ds_read_b128 v[198:201], v175 offset:18432
	ds_read_b128 v[202:205], v175 offset:19456
	ds_read_b128 v[206:209], v175 offset:20480
	ds_read_b128 v[210:213], v175 offset:21504
	ds_read_b128 v[214:217], v175 offset:22528
	ds_read_b128 v[218:221], v175 offset:23552
	global_load_lds_dwordx4 v[186:187], off
	s_add_i32 m0, s62, 0x2000
	s_add_u32 s62, s34, 0x40000
	v_lshl_add_u64 v[222:223], s[34:35], 0, v[150:151]
	s_addc_u32 s63, s35, 0
	s_add_i32 s64, s56, s42
	global_load_lds_dwordx4 v[222:223], off
	s_mov_b32 m0, s64
	v_lshl_add_u64 v[226:227], s[36:37], 0, v[148:149]
	global_load_lds_dwordx4 v146, s[62:63]
	s_add_i32 m0, s64, 0x2000
	s_nop 0
	global_load_lds_dwordx4 v150, s[62:63]
	v_lshl_add_u64 v[224:225], s[36:37], 0, v[144:145]
	s_mov_b32 m0, s43
	s_nop 0
	global_load_lds_dwordx4 v[224:225], off
	s_mov_b32 m0, s44
	s_nop 0
	global_load_lds_dwordx4 v[226:227], off
	s_waitcnt vmcnt(8)
	s_waitcnt lgkmcnt(0)
	s_barrier
; #define PG8_STAGE(bufoff, gbase, voff) do { _Pragma("unroll") for (int _i = 0; _i < 2; ++_i) \
;         __builtin_amdgcn_global_load_lds((const unsigned*)((const char*)(gbase) + (voff)[_i]), (PG8_LAS unsigned*)(lds + (bufoff) + ldsw + _i * 8192), 16, 0, 0); } while (0)
; #define PG8_LDA(dst, b, h) do { _Pragma("unroll") for (int m = 0; m < 4; ++m) _Pragma("unroll") for (int k = 0; k < 2; ++k) dst[m][k] = *(const PG8_LAS bf16x8*)(lds + PG8_SA(b, h) + aoff + m * 2048 + k * 1024); } while (0)
; #define PG8_LDB(dst, b, h) do { _Pragma("unroll") for (int n = 0; n < 2; ++n) _Pragma("unroll") for (int k = 0; k < 2; ++k) dst[n][k] = *(const PG8_LAS bf16x8*)(lds + PG8_SB(b, h) + boff + n * 2048 + k * 1024); } while (0)
; #define PG8_MMA(ai, bj, At, Bt) do { __builtin_amdgcn_s_setprio(1); _Pragma("unroll") for (int m = 0; m < 4; ++m) _Pragma("unroll") for (int n = 0; n < 2; ++n) _Pragma("unroll") for (int k = 0; k < 2; ++k) \
;         acc[ai][bj][m][n] = __builtin_amdgcn_mfma_f32_16x16x32_bf16(Bt[n][k], At[m][k], acc[ai][bj][m][n], 0, 0, 0); __builtin_amdgcn_s_setprio(0); } while (0)
; #define PG8_WAIT_V(n) asm volatile("s_waitcnt vmcnt(" #n ")" ::: "memory")
; #define PG8_WAIT_L(n) asm volatile("s_waitcnt lgkmcnt(" #n ")" ::: "memory")
; #define PG8_BAR __builtin_amdgcn_s_barrier()
; #define PG8_SCHED __builtin_amdgcn_sched_barrier(0)
; template <class Epi, class Sched, bool ALIGN_EPI = false, bool SP2 = false>
; __device__ __forceinline__ void gemm_phase(PG8_LAS unsigned char* lds, const Gemm g, const Sched& S, const Epi& E) {
;     ...
;             PG8_WAIT_V(8); PG8_WAIT_L(0); PG8_BAR; PG8_MMA(1, 0, At, B0); PG8_MMA(1, 1, At, B1); PG8_BAR; PG8_SCHED;
;             PG8_LDB(B0, 1, 0); PG8_LDB(B1, 1, 1); PG8_SCHED; PG8_LDA(At, 1, 0); PG8_STAGE(PG8_SA(0, 1), a2 + hstep, voffA);
;             PG8_WAIT_V(8); PG8_WAIT_L(0); PG8_BAR; PG8_MMA(0, 0, At, B0); PG8_MMA(0, 1, At, B1); PG8_BAR; PG8_SCHED;
;             PG8_LDA(At, 1, 1); PG8_STAGE(PG8_SB(1, 0), b3, voffB); PG8_STAGE(PG8_SB(1, 1), b3 + hstep, voffB); PG8_STAGE(PG8_SA(1, 0), a3, voffA);
	s_setprio 1
	s_waitcnt lgkmcnt(0)
	v_mfma_f32_16x16x32_bf16 v[60:63], v[128:131], v[190:193], v[60:63]
	v_mfma_f32_16x16x32_bf16 v[56:59], v[136:139], v[190:193], v[56:59]
	v_mfma_f32_16x16x32_bf16 v[44:47], v[128:131], v[198:201], v[44:47]
	v_mfma_f32_16x16x32_bf16 v[40:43], v[136:139], v[198:201], v[40:43]
	v_mfma_f32_16x16x32_bf16 v[28:31], v[128:131], v[206:209], v[28:31]
	v_mfma_f32_16x16x32_bf16 v[24:27], v[136:139], v[206:209], v[24:27]
	v_mfma_f32_16x16x32_bf16 v[12:15], v[128:131], v[214:217], v[12:15]
	v_mfma_f32_16x16x32_bf16 v[8:11], v[136:139], v[214:217], v[8:11]
	v_mfma_f32_16x16x32_bf16 v[60:63], v[132:135], v[194:197], v[60:63]
	v_mfma_f32_16x16x32_bf16 v[56:59], v[140:143], v[194:197], v[56:59]
	v_mfma_f32_16x16x32_bf16 v[44:47], v[132:135], v[202:205], v[44:47]
	v_mfma_f32_16x16x32_bf16 v[40:43], v[140:143], v[202:205], v[40:43]
	v_mfma_f32_16x16x32_bf16 v[28:31], v[132:135], v[210:213], v[28:31]
	v_mfma_f32_16x16x32_bf16 v[24:27], v[140:143], v[210:213], v[24:27]
	v_mfma_f32_16x16x32_bf16 v[12:15], v[132:135], v[218:221], v[12:15]
	v_mfma_f32_16x16x32_bf16 v[8:11], v[140:143], v[218:221], v[8:11]
	s_setprio 0
	s_setprio 1
	v_mfma_f32_16x16x32_bf16 v[52:55], v[164:167], v[190:193], v[52:55]
	v_mfma_f32_16x16x32_bf16 v[48:51], v[178:181], v[190:193], v[48:51]
	v_mfma_f32_16x16x32_bf16 v[36:39], v[164:167], v[198:201], v[36:39]
	v_mfma_f32_16x16x32_bf16 v[32:35], v[178:181], v[198:201], v[32:35]
	v_mfma_f32_16x16x32_bf16 v[20:23], v[164:167], v[206:209], v[20:23]
	v_mfma_f32_16x16x32_bf16 v[16:19], v[178:181], v[206:209], v[16:19]
	v_mfma_f32_16x16x32_bf16 v[4:7], v[164:167], v[214:217], v[4:7]
	v_mfma_f32_16x16x32_bf16 v[0:3], v[178:181], v[214:217], v[0:3]
	v_mfma_f32_16x16x32_bf16 v[52:55], v[168:171], v[194:197], v[52:55]
	v_mfma_f32_16x16x32_bf16 v[48:51], v[182:185], v[194:197], v[48:51]
	v_mfma_f32_16x16x32_bf16 v[36:39], v[168:171], v[202:205], v[36:39]
	v_mfma_f32_16x16x32_bf16 v[32:35], v[182:185], v[202:205], v[32:35]
	v_mfma_f32_16x16x32_bf16 v[20:23], v[168:171], v[210:213], v[20:23]
	v_mfma_f32_16x16x32_bf16 v[16:19], v[182:185], v[210:213], v[16:19]
	v_mfma_f32_16x16x32_bf16 v[4:7], v[168:171], v[218:221], v[4:7]
	v_mfma_f32_16x16x32_bf16 v[0:3], v[182:185], v[218:221], v[0:3]
	s_setprio 0
	s_barrier
	s_add_i32 s62, 0, 0x18000
	s_add_i32 s63, 0, 0x1c000
	v_add_u32_e32 v140, s62, v172
	v_add_u32_e32 v177, s63, v172
	ds_read_b128 v[128:131], v140
	ds_read_b128 v[132:135], v140 offset:1024
	ds_read_b128 v[136:139], v140 offset:2048
	ds_read_b128 v[140:143], v140 offset:3072
	ds_read_b128 v[164:167], v177
	ds_read_b128 v[168:171], v177 offset:1024
	ds_read_b128 v[178:181], v177 offset:2048
	ds_read_b128 v[182:185], v177 offset:3072
	s_add_u32 s36, s36, 0x40000
	s_addc_u32 s37, s37, 0
	s_mov_b32 m0, s45
	ds_read_b128 v[190:193], v175 offset:32768
	ds_read_b128 v[194:197], v175 offset:33792
	ds_read_b128 v[198:201], v175 offset:34816
	ds_read_b128 v[202:205], v175 offset:35840
	ds_read_b128 v[206:209], v175 offset:36864
	ds_read_b128 v[210:213], v175 offset:37888
	ds_read_b128 v[214:217], v175 offset:38912
	ds_read_b128 v[218:221], v175 offset:39936
	global_load_lds_dwordx4 v144, s[36:37]
	s_mov_b32 m0, s46
	s_nop 0
	global_load_lds_dwordx4 v148, s[36:37]
	s_waitcnt vmcnt(8)
	s_waitcnt lgkmcnt(0)
	s_barrier
	s_setprio 1
	s_waitcnt lgkmcnt(0)
	v_mfma_f32_16x16x32_bf16 v[124:127], v[128:131], v[190:193], v[124:127]
	v_mfma_f32_16x16x32_bf16 v[120:123], v[136:139], v[190:193], v[120:123]
	v_mfma_f32_16x16x32_bf16 v[108:111], v[128:131], v[198:201], v[108:111]
	v_mfma_f32_16x16x32_bf16 v[104:107], v[136:139], v[198:201], v[104:107]
	v_mfma_f32_16x16x32_bf16 v[92:95], v[128:131], v[206:209], v[92:95]
	v_mfma_f32_16x16x32_bf16 v[88:91], v[136:139], v[206:209], v[88:91]
	v_mfma_f32_16x16x32_bf16 v[76:79], v[128:131], v[214:217], v[76:79]
	v_mfma_f32_16x16x32_bf16 v[72:75], v[136:139], v[214:217], v[72:75]
	v_mfma_f32_16x16x32_bf16 v[124:127], v[132:135], v[194:197], v[124:127]
	v_mfma_f32_16x16x32_bf16 v[120:123], v[140:143], v[194:197], v[120:123]
	v_mfma_f32_16x16x32_bf16 v[108:111], v[132:135], v[202:205], v[108:111]
	v_mfma_f32_16x16x32_bf16 v[104:107], v[140:143], v[202:205], v[104:107]
	v_mfma_f32_16x16x32_bf16 v[92:95], v[132:135], v[210:213], v[92:95]
	v_mfma_f32_16x16x32_bf16 v[88:91], v[140:143], v[210:213], v[88:91]
	v_mfma_f32_16x16x32_bf16 v[76:79], v[132:135], v[218:221], v[76:79]
	v_mfma_f32_16x16x32_bf16 v[72:75], v[140:143], v[218:221], v[72:75]
	s_setprio 0
	s_setprio 1
	v_mfma_f32_16x16x32_bf16 v[116:119], v[164:167], v[190:193], v[116:119]
	v_mfma_f32_16x16x32_bf16 v[112:115], v[178:181], v[190:193], v[112:115]
	v_mfma_f32_16x16x32_bf16 v[100:103], v[164:167], v[198:201], v[100:103]
	v_mfma_f32_16x16x32_bf16 v[96:99], v[178:181], v[198:201], v[96:99]
	v_mfma_f32_16x16x32_bf16 v[84:87], v[164:167], v[206:209], v[84:87]
	v_mfma_f32_16x16x32_bf16 v[80:83], v[178:181], v[206:209], v[80:83]
	v_mfma_f32_16x16x32_bf16 v[68:71], v[164:167], v[214:217], v[68:71]
	v_mfma_f32_16x16x32_bf16 v[64:67], v[178:181], v[214:217], v[64:67]
	v_mfma_f32_16x16x32_bf16 v[116:119], v[168:171], v[194:197], v[116:119]
	v_mfma_f32_16x16x32_bf16 v[112:115], v[182:185], v[194:197], v[112:115]
	v_mfma_f32_16x16x32_bf16 v[100:103], v[168:171], v[202:205], v[100:103]
	v_mfma_f32_16x16x32_bf16 v[96:99], v[182:185], v[202:205], v[96:99]
	v_mfma_f32_16x16x32_bf16 v[84:87], v[168:171], v[210:213], v[84:87]
	v_mfma_f32_16x16x32_bf16 v[80:83], v[182:185], v[210:213], v[80:83]
	v_mfma_f32_16x16x32_bf16 v[68:71], v[168:171], v[218:221], v[68:71]
	v_mfma_f32_16x16x32_bf16 v[64:67], v[182:185], v[218:221], v[64:67]
	s_setprio 0
	s_barrier
; #define PG8_STAGE(bufoff, gbase, voff) do { _Pragma("unroll") for (int _i = 0; _i < 2; ++_i) \
;         __builtin_amdgcn_global_load_lds((const unsigned*)((const char*)(gbase) + (voff)[_i]), (PG8_LAS unsigned*)(lds + (bufoff) + ldsw + _i * 8192), 16, 0, 0); } while (0)
; #define PG8_LDA(dst, b, h) do { _Pragma("unroll") for (int m = 0; m < 4; ++m) _Pragma("unroll") for (int k = 0; k < 2; ++k) dst[m][k] = *(const PG8_LAS bf16x8*)(lds + PG8_SA(b, h) + aoff + m * 2048 + k * 1024); } while (0)
; #define PG8_MMA(ai, bj, At, Bt) do { __builtin_amdgcn_s_setprio(1); _Pragma("unroll") for (int m = 0; m < 4; ++m) _Pragma("unroll") for (int n = 0; n < 2; ++n) _Pragma("unroll") for (int k = 0; k < 2; ++k) \
;         acc[ai][bj][m][n] = __builtin_amdgcn_mfma_f32_16x16x32_bf16(Bt[n][k], At[m][k], acc[ai][bj][m][n], 0, 0, 0); __builtin_amdgcn_s_setprio(0); } while (0)
; #define PG8_WAIT_V(n) asm volatile("s_waitcnt vmcnt(" #n ")" ::: "memory")
; #define PG8_WAIT_L(n) asm volatile("s_waitcnt lgkmcnt(" #n ")" ::: "memory")
; #define PG8_BAR __builtin_amdgcn_s_barrier()
; #define PG8_SCHED __builtin_amdgcn_sched_barrier(0)
; template <class Epi, class Sched, bool ALIGN_EPI = false, bool SP2 = false>
; __device__ __forceinline__ void gemm_phase(PG8_LAS unsigned char* lds, const Gemm g, const Sched& S, const Epi& E) {
;     ...
;             PG8_LDA(At, 1, 1); PG8_STAGE(PG8_SB(1, 0), b3, voffB); PG8_STAGE(PG8_SB(1, 1), b3 + hstep, voffB); PG8_STAGE(PG8_SA(1, 0), a3, voffA);
;             PG8_WAIT_V(8); PG8_WAIT_L(0); PG8_BAR; PG8_MMA(1, 0, At, B0); PG8_MMA(1, 1, At, B1); PG8_BAR; PG8_SCHED;
	s_add_i32 s36, s62, s42
	v_lshl_add_u64 v[186:187], v[186:187], 0, s[16:17]
	s_mov_b32 m0, s36
	ds_read_b128 v[190:193], v175 offset:49152
	ds_read_b128 v[194:197], v175 offset:50176
	ds_read_b128 v[198:201], v175 offset:51200
	ds_read_b128 v[202:205], v175 offset:52224
	ds_read_b128 v[206:209], v175 offset:53248
	ds_read_b128 v[210:213], v175 offset:54272
	ds_read_b128 v[214:217], v175 offset:55296
	ds_read_b128 v[218:221], v175 offset:56320
	global_load_lds_dwordx4 v[186:187], off
	s_add_i32 m0, s36, 0x2000
	s_add_u32 s34, s34, 0x40080
	v_lshl_add_u64 v[186:187], v[222:223], 0, s[16:17]
	s_addc_u32 s35, s35, 0
	s_add_i32 s36, s63, s42
	global_load_lds_dwordx4 v[186:187], off
	s_mov_b32 m0, s36
	s_nop 0
	global_load_lds_dwordx4 v146, s[34:35]
	s_add_i32 m0, s36, 0x2000
	s_nop 0
	global_load_lds_dwordx4 v150, s[34:35]
	v_lshl_add_u64 v[186:187], v[224:225], 0, s[16:17]
	s_mov_b32 m0, s48
	s_nop 0
	global_load_lds_dwordx4 v[186:187], off
	v_lshl_add_u64 v[186:187], v[226:227], 0, s[16:17]
	s_mov_b32 m0, s49
	s_nop 0
	global_load_lds_dwordx4 v[186:187], off
	s_waitcnt vmcnt(8)
	s_waitcnt lgkmcnt(0)
	s_barrier
	s_setprio 1
	s_waitcnt lgkmcnt(0)
	v_mfma_f32_16x16x32_bf16 v[60:63], v[128:131], v[190:193], v[60:63]
	v_mfma_f32_16x16x32_bf16 v[56:59], v[136:139], v[190:193], v[56:59]
	v_mfma_f32_16x16x32_bf16 v[44:47], v[128:131], v[198:201], v[44:47]
	v_mfma_f32_16x16x32_bf16 v[40:43], v[136:139], v[198:201], v[40:43]
	v_mfma_f32_16x16x32_bf16 v[28:31], v[128:131], v[206:209], v[28:31]
	v_mfma_f32_16x16x32_bf16 v[24:27], v[136:139], v[206:209], v[24:27]
	v_mfma_f32_16x16x32_bf16 v[12:15], v[128:131], v[214:217], v[12:15]
	v_mfma_f32_16x16x32_bf16 v[8:11], v[136:139], v[214:217], v[8:11]
	v_mfma_f32_16x16x32_bf16 v[60:63], v[132:135], v[194:197], v[60:63]
	v_mfma_f32_16x16x32_bf16 v[56:59], v[140:143], v[194:197], v[56:59]
	v_mfma_f32_16x16x32_bf16 v[44:47], v[132:135], v[202:205], v[44:47]
	v_mfma_f32_16x16x32_bf16 v[40:43], v[140:143], v[202:205], v[40:43]
	v_mfma_f32_16x16x32_bf16 v[28:31], v[132:135], v[210:213], v[28:31]
	v_mfma_f32_16x16x32_bf16 v[24:27], v[140:143], v[210:213], v[24:27]
	v_mfma_f32_16x16x32_bf16 v[12:15], v[132:135], v[218:221], v[12:15]
	v_mfma_f32_16x16x32_bf16 v[8:11], v[140:143], v[218:221], v[8:11]
	s_setprio 0
	s_setprio 1
	v_mfma_f32_16x16x32_bf16 v[52:55], v[164:167], v[190:193], v[52:55]
	v_mfma_f32_16x16x32_bf16 v[48:51], v[178:181], v[190:193], v[48:51]
	v_mfma_f32_16x16x32_bf16 v[36:39], v[164:167], v[198:201], v[36:39]
	v_mfma_f32_16x16x32_bf16 v[32:35], v[178:181], v[198:201], v[32:35]
	v_mfma_f32_16x16x32_bf16 v[20:23], v[164:167], v[206:209], v[20:23]
	v_mfma_f32_16x16x32_bf16 v[16:19], v[178:181], v[206:209], v[16:19]
	v_mfma_f32_16x16x32_bf16 v[4:7], v[164:167], v[214:217], v[4:7]
	v_mfma_f32_16x16x32_bf16 v[0:3], v[178:181], v[214:217], v[0:3]
	v_mfma_f32_16x16x32_bf16 v[52:55], v[168:171], v[194:197], v[52:55]
	v_mfma_f32_16x16x32_bf16 v[48:51], v[182:185], v[194:197], v[48:51]
	v_mfma_f32_16x16x32_bf16 v[36:39], v[168:171], v[202:205], v[36:39]
	v_mfma_f32_16x16x32_bf16 v[32:35], v[182:185], v[202:205], v[32:35]
	v_mfma_f32_16x16x32_bf16 v[20:23], v[168:171], v[210:213], v[20:23]
	v_mfma_f32_16x16x32_bf16 v[16:19], v[182:185], v[210:213], v[16:19]
	v_mfma_f32_16x16x32_bf16 v[4:7], v[168:171], v[218:221], v[4:7]
	v_mfma_f32_16x16x32_bf16 v[0:3], v[182:185], v[218:221], v[0:3]
	s_setprio 0
	s_barrier
	s_add_i32 s61, s61, 2
	s_add_u32 s30, s30, 0x100
	s_addc_u32 s31, s31, 0
	s_add_u32 s59, s59, 0x100
	s_addc_u32 s60, s60, 0
	s_cmp_gt_u32 s61, 13
	s_cbranch_scc0 .LBB0_882
	s_and_b64 vcc, exec, s[18:19]
	s_cbranch_vccz .LBB0_885
	s_barrier

; #define PG8_STAGE(bufoff, gbase, voff) do { _Pragma("unroll") for (int _i = 0; _i < 2; ++_i) \
;         __builtin_amdgcn_global_load_lds((const unsigned*)((const char*)(gbase) + (voff)[_i]), (PG8_LAS unsigned*)(lds + (bufoff) + ldsw + _i * 8192), 16, 0, 0); } while (0)
; #define PG8_LDA(dst, b, h) do { _Pragma("unroll") for (int m = 0; m < 4; ++m) _Pragma("unroll") for (int k = 0; k < 2; ++k) dst[m][k] = *(const PG8_LAS bf16x8*)(lds + PG8_SA(b, h) + aoff + m * 2048 + k * 1024); } while (0)
; #define PG8_LDB(dst, b, h) do { _Pragma("unroll") for (int n = 0; n < 2; ++n) _Pragma("unroll") for (int k = 0; k < 2; ++k) dst[n][k] = *(const PG8_LAS bf16x8*)(lds + PG8_SB(b, h) + boff + n * 2048 + k * 1024); } while (0)
; #define PG8_MMA(ai, bj, At, Bt) do { __builtin_amdgcn_s_setprio(1); _Pragma("unroll") for (int m = 0; m < 4; ++m) _Pragma("unroll") for (int n = 0; n < 2; ++n) _Pragma("unroll") for (int k = 0; k < 2; ++k) \
;         acc[ai][bj][m][n] = __builtin_amdgcn_mfma_f32_16x16x32_bf16(Bt[n][k], At[m][k], acc[ai][bj][m][n], 0, 0, 0); __builtin_amdgcn_s_setprio(0); } while (0)
; #define PG8_WAIT_V(n) asm volatile("s_waitcnt vmcnt(" #n ")" ::: "memory")
; #define PG8_WAIT_L(n) asm volatile("s_waitcnt lgkmcnt(" #n ")" ::: "memory")
; #define PG8_BAR __builtin_amdgcn_s_barrier()
; #define PG8_SCHED __builtin_amdgcn_sched_barrier(0)
; template <class Epi, class Sched, bool ALIGN_EPI = false, bool SP2 = false>
; __device__ __forceinline__ void gemm_phase(PG8_LAS unsigned char* lds, const Gemm g, const Sched& S, const Epi& E) {
;     ...
;             PG8_LDB(B0, 0, 0); PG8_LDB(B1, 0, 1); PG8_SCHED; PG8_LDA(At, 0, 0); PG8_STAGE(PG8_SA(1, 1), a1 + hstep, voffA);
;             PG8_WAIT_V(8); PG8_WAIT_L(0); PG8_BAR; PG8_MMA(0, 0, At, B0); PG8_MMA(0, 1, At, B1); PG8_BAR; PG8_SCHED;
;             PG8_LDA(At, 0, 1); PG8_STAGE(PG8_SB(0, 0), b2, voffB); PG8_STAGE(PG8_SB(0, 1), b2 + hstep, voffB); PG8_STAGE(PG8_SA(0, 0), a2, voffA);
;             PG8_WAIT_V(8); PG8_WAIT_L(0); PG8_BAR; PG8_MMA(1, 0, At, B0); PG8_MMA(1, 1, At, B1); PG8_BAR; PG8_SCHED;
.LBB0_969:
	ds_read_b128 v[128:131], v191
	ds_read_b128 v[132:135], v191 offset:1024
	ds_read_b128 v[136:139], v191 offset:2048
	ds_read_b128 v[140:143], v191 offset:3072
	ds_read_b128 v[144:147], v192
	ds_read_b128 v[148:151], v192 offset:1024
	ds_read_b128 v[172:175], v192 offset:2048
	ds_read_b128 v[176:179], v192 offset:3072
	s_add_u32 s26, s24, 0xfffc0080
	s_addc_u32 s27, s25, -1
	s_cmp_eq_u32 s57, 12
	s_cselect_b32 s29, s17, s27
	s_cselect_b32 s28, s51, s26
	s_cselect_b32 s27, s15, s56
	s_cselect_b32 s26, s54, s55
	s_add_i32 m0, s39, 0xc000
	ds_read_b128 v[180:183], v193
	ds_read_b128 v[184:187], v193 offset:1024
	ds_read_b128 v[196:199], v193 offset:2048
	ds_read_b128 v[200:203], v193 offset:3072
	ds_read_b128 v[204:207], v193 offset:4096
	ds_read_b128 v[208:211], v193 offset:5120
	ds_read_b128 v[212:215], v193 offset:6144
	ds_read_b128 v[216:219], v193 offset:7168
	global_load_lds_dwordx4 v164, s[24:25]
	s_add_i32 m0, s39, 0xe000
	s_nop 0
	global_load_lds_dwordx4 v166, s[24:25]
	s_waitcnt vmcnt(8)
	s_waitcnt lgkmcnt(0)
	s_barrier
	s_setprio 1
	s_waitcnt lgkmcnt(0)
	v_mfma_f32_16x16x32_bf16 v[124:127], v[128:131], v[180:183], v[124:127]
	v_mfma_f32_16x16x32_bf16 v[120:123], v[136:139], v[180:183], v[120:123]
	v_mfma_f32_16x16x32_bf16 v[108:111], v[128:131], v[196:199], v[108:111]
	v_mfma_f32_16x16x32_bf16 v[104:107], v[136:139], v[196:199], v[104:107]
	v_mfma_f32_16x16x32_bf16 v[92:95], v[128:131], v[204:207], v[92:95]
	v_mfma_f32_16x16x32_bf16 v[84:87], v[136:139], v[204:207], v[84:87]
	v_mfma_f32_16x16x32_bf16 v[76:79], v[128:131], v[212:215], v[76:79]
	v_mfma_f32_16x16x32_bf16 v[72:75], v[136:139], v[212:215], v[72:75]
	v_mfma_f32_16x16x32_bf16 v[124:127], v[132:135], v[184:187], v[124:127]
	v_mfma_f32_16x16x32_bf16 v[120:123], v[140:143], v[184:187], v[120:123]
	v_mfma_f32_16x16x32_bf16 v[108:111], v[132:135], v[200:203], v[108:111]
	v_mfma_f32_16x16x32_bf16 v[104:107], v[140:143], v[200:203], v[104:107]
	v_mfma_f32_16x16x32_bf16 v[92:95], v[132:135], v[208:211], v[92:95]
	v_mfma_f32_16x16x32_bf16 v[84:87], v[140:143], v[208:211], v[84:87]
	v_mfma_f32_16x16x32_bf16 v[76:79], v[132:135], v[216:219], v[76:79]
	v_mfma_f32_16x16x32_bf16 v[72:75], v[140:143], v[216:219], v[72:75]
	s_setprio 0
	s_setprio 1
	v_mfma_f32_16x16x32_bf16 v[116:119], v[144:147], v[180:183], v[116:119]
	v_mfma_f32_16x16x32_bf16 v[112:115], v[172:175], v[180:183], v[112:115]
	v_mfma_f32_16x16x32_bf16 v[100:103], v[144:147], v[196:199], v[100:103]
	v_mfma_f32_16x16x32_bf16 v[96:99], v[172:175], v[196:199], v[96:99]
	v_mfma_f32_16x16x32_bf16 v[88:91], v[144:147], v[204:207], v[88:91]
	v_mfma_f32_16x16x32_bf16 v[80:83], v[172:175], v[204:207], v[80:83]
	v_mfma_f32_16x16x32_bf16 v[68:71], v[144:147], v[212:215], v[68:71]
	v_mfma_f32_16x16x32_bf16 v[64:67], v[172:175], v[212:215], v[64:67]
	v_mfma_f32_16x16x32_bf16 v[116:119], v[148:151], v[184:187], v[116:119]
	v_mfma_f32_16x16x32_bf16 v[112:115], v[176:179], v[184:187], v[112:115]
	v_mfma_f32_16x16x32_bf16 v[100:103], v[148:151], v[200:203], v[100:103]
	v_mfma_f32_16x16x32_bf16 v[96:99], v[176:179], v[200:203], v[96:99]
	v_mfma_f32_16x16x32_bf16 v[88:91], v[148:151], v[208:211], v[88:91]
	v_mfma_f32_16x16x32_bf16 v[80:83], v[176:179], v[208:211], v[80:83]
	v_mfma_f32_16x16x32_bf16 v[68:71], v[148:151], v[216:219], v[68:71]
	v_mfma_f32_16x16x32_bf16 v[64:67], v[176:179], v[216:219], v[64:67]
	s_setprio 0
	s_barrier
	s_add_i32 s58, s47, s36
	v_lshl_add_u64 v[220:221], s[26:27], 0, v[156:157]
	s_mov_b32 m0, s58
	ds_read_b128 v[180:183], v193 offset:16384
	ds_read_b128 v[184:187], v193 offset:17408
	ds_read_b128 v[196:199], v193 offset:18432
	ds_read_b128 v[200:203], v193 offset:19456
	ds_read_b128 v[204:207], v193 offset:20480
	ds_read_b128 v[208:211], v193 offset:21504
	ds_read_b128 v[212:215], v193 offset:22528
	ds_read_b128 v[216:219], v193 offset:23552
	global_load_lds_dwordx4 v[220:221], off
	s_add_i32 m0, s58, 0x2000
	s_add_u32 s58, s26, 0x40000
	v_lshl_add_u64 v[222:223], s[26:27], 0, v[152:153]
	s_addc_u32 s59, s27, 0
	s_add_i32 s60, s48, s36
	global_load_lds_dwordx4 v[222:223], off
	s_mov_b32 m0, s60
	v_lshl_add_u64 v[226:227], s[28:29], 0, v[154:155]
	global_load_lds_dwordx4 v156, s[58:59]
	s_add_i32 m0, s60, 0x2000
	s_nop 0
	global_load_lds_dwordx4 v152, s[58:59]
	v_lshl_add_u64 v[224:225], s[28:29], 0, v[158:159]
	s_mov_b32 m0, s39
	s_nop 0
	global_load_lds_dwordx4 v[224:225], off
	s_mov_b32 m0, s40
	s_nop 0
	global_load_lds_dwordx4 v[226:227], off
	s_waitcnt vmcnt(8)
	s_waitcnt lgkmcnt(0)
	s_barrier
; #define PG8_STAGE(bufoff, gbase, voff) do { _Pragma("unroll") for (int _i = 0; _i < 2; ++_i) \
;         __builtin_amdgcn_global_load_lds((const unsigned*)((const char*)(gbase) + (voff)[_i]), (PG8_LAS unsigned*)(lds + (bufoff) + ldsw + _i * 8192), 16, 0, 0); } while (0)
; #define PG8_LDA(dst, b, h) do { _Pragma("unroll") for (int m = 0; m < 4; ++m) _Pragma("unroll") for (int k = 0; k < 2; ++k) dst[m][k] = *(const PG8_LAS bf16x8*)(lds + PG8_SA(b, h) + aoff + m * 2048 + k * 1024); } while (0)
; #define PG8_LDB(dst, b, h) do { _Pragma("unroll") for (int n = 0; n < 2; ++n) _Pragma("unroll") for (int k = 0; k < 2; ++k) dst[n][k] = *(const PG8_LAS bf16x8*)(lds + PG8_SB(b, h) + boff + n * 2048 + k * 1024); } while (0)
; #define PG8_MMA(ai, bj, At, Bt) do { __builtin_amdgcn_s_setprio(1); _Pragma("unroll") for (int m = 0; m < 4; ++m) _Pragma("unroll") for (int n = 0; n < 2; ++n) _Pragma("unroll") for (int k = 0; k < 2; ++k) \
;         acc[ai][bj][m][n] = __builtin_amdgcn_mfma_f32_16x16x32_bf16(Bt[n][k], At[m][k], acc[ai][bj][m][n], 0, 0, 0); __builtin_amdgcn_s_setprio(0); } while (0)
; #define PG8_WAIT_V(n) asm volatile("s_waitcnt vmcnt(" #n ")" ::: "memory")
; #define PG8_WAIT_L(n) asm volatile("s_waitcnt lgkmcnt(" #n ")" ::: "memory")
; #define PG8_BAR __builtin_amdgcn_s_barrier()
; #define PG8_SCHED __builtin_amdgcn_sched_barrier(0)
; template <class Epi, class Sched, bool ALIGN_EPI = false, bool SP2 = false>
; __device__ __forceinline__ void gemm_phase(PG8_LAS unsigned char* lds, const Gemm g, const Sched& S, const Epi& E) {
;     ...
;             PG8_WAIT_V(8); PG8_WAIT_L(0); PG8_BAR; PG8_MMA(1, 0, At, B0); PG8_MMA(1, 1, At, B1); PG8_BAR; PG8_SCHED;
;             PG8_LDB(B0, 1, 0); PG8_LDB(B1, 1, 1); PG8_SCHED; PG8_LDA(At, 1, 0); PG8_STAGE(PG8_SA(0, 1), a2 + hstep, voffA);
;             PG8_WAIT_V(8); PG8_WAIT_L(0); PG8_BAR; PG8_MMA(0, 0, At, B0); PG8_MMA(0, 1, At, B1); PG8_BAR; PG8_SCHED;
;             PG8_LDA(At, 1, 1); PG8_STAGE(PG8_SB(1, 0), b3, voffB); PG8_STAGE(PG8_SB(1, 1), b3 + hstep, voffB); PG8_STAGE(PG8_SA(1, 0), a3, voffA);
	s_setprio 1
	s_waitcnt lgkmcnt(0)
	v_mfma_f32_16x16x32_bf16 v[60:63], v[128:131], v[180:183], v[60:63]
	v_mfma_f32_16x16x32_bf16 v[52:55], v[136:139], v[180:183], v[52:55]
	v_mfma_f32_16x16x32_bf16 v[44:47], v[128:131], v[196:199], v[44:47]
	v_mfma_f32_16x16x32_bf16 v[40:43], v[136:139], v[196:199], v[40:43]
	v_mfma_f32_16x16x32_bf16 v[28:31], v[128:131], v[204:207], v[28:31]
	v_mfma_f32_16x16x32_bf16 v[20:23], v[136:139], v[204:207], v[20:23]
	v_mfma_f32_16x16x32_bf16 v[12:15], v[128:131], v[212:215], v[12:15]
	v_mfma_f32_16x16x32_bf16 v[8:11], v[136:139], v[212:215], v[8:11]
	v_mfma_f32_16x16x32_bf16 v[60:63], v[132:135], v[184:187], v[60:63]
	v_mfma_f32_16x16x32_bf16 v[52:55], v[140:143], v[184:187], v[52:55]
	v_mfma_f32_16x16x32_bf16 v[44:47], v[132:135], v[200:203], v[44:47]
	v_mfma_f32_16x16x32_bf16 v[40:43], v[140:143], v[200:203], v[40:43]
	v_mfma_f32_16x16x32_bf16 v[28:31], v[132:135], v[208:211], v[28:31]
	v_mfma_f32_16x16x32_bf16 v[20:23], v[140:143], v[208:211], v[20:23]
	v_mfma_f32_16x16x32_bf16 v[12:15], v[132:135], v[216:219], v[12:15]
	v_mfma_f32_16x16x32_bf16 v[8:11], v[140:143], v[216:219], v[8:11]
	s_setprio 0
	s_setprio 1
	v_mfma_f32_16x16x32_bf16 v[56:59], v[144:147], v[180:183], v[56:59]
	v_mfma_f32_16x16x32_bf16 v[48:51], v[172:175], v[180:183], v[48:51]
	v_mfma_f32_16x16x32_bf16 v[36:39], v[144:147], v[196:199], v[36:39]
	v_mfma_f32_16x16x32_bf16 v[32:35], v[172:175], v[196:199], v[32:35]
	v_mfma_f32_16x16x32_bf16 v[24:27], v[144:147], v[204:207], v[24:27]
	v_mfma_f32_16x16x32_bf16 v[16:19], v[172:175], v[204:207], v[16:19]
	v_mfma_f32_16x16x32_bf16 v[4:7], v[144:147], v[212:215], v[4:7]
	v_mfma_f32_16x16x32_bf16 v[0:3], v[172:175], v[212:215], v[0:3]
	v_mfma_f32_16x16x32_bf16 v[56:59], v[148:151], v[184:187], v[56:59]
	v_mfma_f32_16x16x32_bf16 v[48:51], v[176:179], v[184:187], v[48:51]
	v_mfma_f32_16x16x32_bf16 v[36:39], v[148:151], v[200:203], v[36:39]
	v_mfma_f32_16x16x32_bf16 v[32:35], v[176:179], v[200:203], v[32:35]
	v_mfma_f32_16x16x32_bf16 v[24:27], v[148:151], v[208:211], v[24:27]
	v_mfma_f32_16x16x32_bf16 v[16:19], v[176:179], v[208:211], v[16:19]
	v_mfma_f32_16x16x32_bf16 v[4:7], v[148:151], v[216:219], v[4:7]
	v_mfma_f32_16x16x32_bf16 v[0:3], v[176:179], v[216:219], v[0:3]
	s_setprio 0
	s_barrier
	s_add_i32 s58, 0, 0x18000
	s_add_i32 s59, 0, 0x1c000
	v_add_u32_e32 v140, s58, v190
	v_add_u32_e32 v176, s59, v190
	ds_read_b128 v[128:131], v140
	ds_read_b128 v[132:135], v140 offset:1024
	ds_read_b128 v[136:139], v140 offset:2048
	ds_read_b128 v[140:143], v140 offset:3072
	ds_read_b128 v[144:147], v176
	ds_read_b128 v[148:151], v176 offset:1024
	ds_read_b128 v[172:175], v176 offset:2048
	ds_read_b128 v[176:179], v176 offset:3072
	s_add_u32 s28, s28, 0x40000
	s_addc_u32 s29, s29, 0
	s_mov_b32 m0, s41
	ds_read_b128 v[180:183], v193 offset:32768
	ds_read_b128 v[184:187], v193 offset:33792
	ds_read_b128 v[196:199], v193 offset:34816
	ds_read_b128 v[200:203], v193 offset:35840
	ds_read_b128 v[204:207], v193 offset:36864
	ds_read_b128 v[208:211], v193 offset:37888
	ds_read_b128 v[212:215], v193 offset:38912
	ds_read_b128 v[216:219], v193 offset:39936
	global_load_lds_dwordx4 v158, s[28:29]
	s_mov_b32 m0, s42
	s_nop 0
	global_load_lds_dwordx4 v154, s[28:29]
	s_waitcnt vmcnt(8)
	s_waitcnt lgkmcnt(0)
	s_barrier
	s_setprio 1
	s_waitcnt lgkmcnt(0)
	v_mfma_f32_16x16x32_bf16 v[124:127], v[128:131], v[180:183], v[124:127]
	v_mfma_f32_16x16x32_bf16 v[120:123], v[136:139], v[180:183], v[120:123]
	v_mfma_f32_16x16x32_bf16 v[108:111], v[128:131], v[196:199], v[108:111]
	v_mfma_f32_16x16x32_bf16 v[104:107], v[136:139], v[196:199], v[104:107]
	v_mfma_f32_16x16x32_bf16 v[92:95], v[128:131], v[204:207], v[92:95]
	v_mfma_f32_16x16x32_bf16 v[84:87], v[136:139], v[204:207], v[84:87]
	v_mfma_f32_16x16x32_bf16 v[76:79], v[128:131], v[212:215], v[76:79]
	v_mfma_f32_16x16x32_bf16 v[72:75], v[136:139], v[212:215], v[72:75]
	v_mfma_f32_16x16x32_bf16 v[124:127], v[132:135], v[184:187], v[124:127]
	v_mfma_f32_16x16x32_bf16 v[120:123], v[140:143], v[184:187], v[120:123]
	v_mfma_f32_16x16x32_bf16 v[108:111], v[132:135], v[200:203], v[108:111]
	v_mfma_f32_16x16x32_bf16 v[104:107], v[140:143], v[200:203], v[104:107]
	v_mfma_f32_16x16x32_bf16 v[92:95], v[132:135], v[208:211], v[92:95]
	v_mfma_f32_16x16x32_bf16 v[84:87], v[140:143], v[208:211], v[84:87]
	v_mfma_f32_16x16x32_bf16 v[76:79], v[132:135], v[216:219], v[76:79]
	v_mfma_f32_16x16x32_bf16 v[72:75], v[140:143], v[216:219], v[72:75]
	s_setprio 0
	s_setprio 1
	v_mfma_f32_16x16x32_bf16 v[116:119], v[144:147], v[180:183], v[116:119]
	v_mfma_f32_16x16x32_bf16 v[112:115], v[172:175], v[180:183], v[112:115]
	v_mfma_f32_16x16x32_bf16 v[100:103], v[144:147], v[196:199], v[100:103]
	v_mfma_f32_16x16x32_bf16 v[96:99], v[172:175], v[196:199], v[96:99]
	v_mfma_f32_16x16x32_bf16 v[88:91], v[144:147], v[204:207], v[88:91]
	v_mfma_f32_16x16x32_bf16 v[80:83], v[172:175], v[204:207], v[80:83]
	v_mfma_f32_16x16x32_bf16 v[68:71], v[144:147], v[212:215], v[68:71]
	v_mfma_f32_16x16x32_bf16 v[64:67], v[172:175], v[212:215], v[64:67]
	v_mfma_f32_16x16x32_bf16 v[116:119], v[148:151], v[184:187], v[116:119]
	v_mfma_f32_16x16x32_bf16 v[112:115], v[176:179], v[184:187], v[112:115]
	v_mfma_f32_16x16x32_bf16 v[100:103], v[148:151], v[200:203], v[100:103]
	v_mfma_f32_16x16x32_bf16 v[96:99], v[176:179], v[200:203], v[96:99]
	v_mfma_f32_16x16x32_bf16 v[88:91], v[148:151], v[208:211], v[88:91]
	v_mfma_f32_16x16x32_bf16 v[80:83], v[176:179], v[208:211], v[80:83]
	v_mfma_f32_16x16x32_bf16 v[68:71], v[148:151], v[216:219], v[68:71]
	v_mfma_f32_16x16x32_bf16 v[64:67], v[176:179], v[216:219], v[64:67]
	s_setprio 0
	s_barrier
; #define PG8_STAGE(bufoff, gbase, voff) do { _Pragma("unroll") for (int _i = 0; _i < 2; ++_i) \
;         __builtin_amdgcn_global_load_lds((const unsigned*)((const char*)(gbase) + (voff)[_i]), (PG8_LAS unsigned*)(lds + (bufoff) + ldsw + _i * 8192), 16, 0, 0); } while (0)
; #define PG8_LDA(dst, b, h) do { _Pragma("unroll") for (int m = 0; m < 4; ++m) _Pragma("unroll") for (int k = 0; k < 2; ++k) dst[m][k] = *(const PG8_LAS bf16x8*)(lds + PG8_SA(b, h) + aoff + m * 2048 + k * 1024); } while (0)
; #define PG8_MMA(ai, bj, At, Bt) do { __builtin_amdgcn_s_setprio(1); _Pragma("unroll") for (int m = 0; m < 4; ++m) _Pragma("unroll") for (int n = 0; n < 2; ++n) _Pragma("unroll") for (int k = 0; k < 2; ++k) \
;         acc[ai][bj][m][n] = __builtin_amdgcn_mfma_f32_16x16x32_bf16(Bt[n][k], At[m][k], acc[ai][bj][m][n], 0, 0, 0); __builtin_amdgcn_s_setprio(0); } while (0)
; #define PG8_WAIT_V(n) asm volatile("s_waitcnt vmcnt(" #n ")" ::: "memory")
; #define PG8_WAIT_L(n) asm volatile("s_waitcnt lgkmcnt(" #n ")" ::: "memory")
; #define PG8_BAR __builtin_amdgcn_s_barrier()
; #define PG8_SCHED __builtin_amdgcn_sched_barrier(0)
; template <class Epi, class Sched, bool ALIGN_EPI = false, bool SP2 = false>
; __device__ __forceinline__ void gemm_phase(PG8_LAS unsigned char* lds, const Gemm g, const Sched& S, const Epi& E) {
;     ...
;             PG8_LDA(At, 1, 1); PG8_STAGE(PG8_SB(1, 0), b3, voffB); PG8_STAGE(PG8_SB(1, 1), b3 + hstep, voffB); PG8_STAGE(PG8_SA(1, 0), a3, voffA);
;             PG8_WAIT_V(8); PG8_WAIT_L(0); PG8_BAR; PG8_MMA(1, 0, At, B0); PG8_MMA(1, 1, At, B1); PG8_BAR; PG8_SCHED;
	s_add_i32 s28, s58, s36
	v_lshl_add_u64 v[220:221], v[220:221], 0, s[10:11]
	s_mov_b32 m0, s28
	ds_read_b128 v[180:183], v193 offset:49152
	ds_read_b128 v[184:187], v193 offset:50176
	ds_read_b128 v[196:199], v193 offset:51200
	ds_read_b128 v[200:203], v193 offset:52224
	ds_read_b128 v[204:207], v193 offset:53248
	ds_read_b128 v[208:211], v193 offset:54272
	ds_read_b128 v[212:215], v193 offset:55296
	ds_read_b128 v[216:219], v193 offset:56320
	global_load_lds_dwordx4 v[220:221], off
	s_add_i32 m0, s28, 0x2000
	s_add_u32 s26, s26, 0x40080
	v_lshl_add_u64 v[220:221], v[222:223], 0, s[10:11]
	s_addc_u32 s27, s27, 0
	s_add_i32 s28, s59, s36
	global_load_lds_dwordx4 v[220:221], off
	s_mov_b32 m0, s28
	s_nop 0
	global_load_lds_dwordx4 v156, s[26:27]
	s_add_i32 m0, s28, 0x2000
	s_nop 0
	global_load_lds_dwordx4 v152, s[26:27]
	v_lshl_add_u64 v[220:221], v[224:225], 0, s[10:11]
	s_mov_b32 m0, s43
	s_nop 0
	global_load_lds_dwordx4 v[220:221], off
	v_lshl_add_u64 v[220:221], v[226:227], 0, s[10:11]
	s_mov_b32 m0, s44
	s_nop 0
	global_load_lds_dwordx4 v[220:221], off
	s_waitcnt vmcnt(8)
	s_waitcnt lgkmcnt(0)
	s_barrier
	s_setprio 1
	s_waitcnt lgkmcnt(0)
	v_mfma_f32_16x16x32_bf16 v[60:63], v[128:131], v[180:183], v[60:63]
	v_mfma_f32_16x16x32_bf16 v[52:55], v[136:139], v[180:183], v[52:55]
	v_mfma_f32_16x16x32_bf16 v[44:47], v[128:131], v[196:199], v[44:47]
	v_mfma_f32_16x16x32_bf16 v[40:43], v[136:139], v[196:199], v[40:43]
	v_mfma_f32_16x16x32_bf16 v[28:31], v[128:131], v[204:207], v[28:31]
	v_mfma_f32_16x16x32_bf16 v[20:23], v[136:139], v[204:207], v[20:23]
	v_mfma_f32_16x16x32_bf16 v[12:15], v[128:131], v[212:215], v[12:15]
	v_mfma_f32_16x16x32_bf16 v[8:11], v[136:139], v[212:215], v[8:11]
	v_mfma_f32_16x16x32_bf16 v[60:63], v[132:135], v[184:187], v[60:63]
	v_mfma_f32_16x16x32_bf16 v[52:55], v[140:143], v[184:187], v[52:55]
	v_mfma_f32_16x16x32_bf16 v[44:47], v[132:135], v[200:203], v[44:47]
	v_mfma_f32_16x16x32_bf16 v[40:43], v[140:143], v[200:203], v[40:43]
	v_mfma_f32_16x16x32_bf16 v[28:31], v[132:135], v[208:211], v[28:31]
	v_mfma_f32_16x16x32_bf16 v[20:23], v[140:143], v[208:211], v[20:23]
	v_mfma_f32_16x16x32_bf16 v[12:15], v[132:135], v[216:219], v[12:15]
	v_mfma_f32_16x16x32_bf16 v[8:11], v[140:143], v[216:219], v[8:11]
	s_setprio 0
	s_setprio 1
	v_mfma_f32_16x16x32_bf16 v[56:59], v[144:147], v[180:183], v[56:59]
	v_mfma_f32_16x16x32_bf16 v[48:51], v[172:175], v[180:183], v[48:51]
	v_mfma_f32_16x16x32_bf16 v[36:39], v[144:147], v[196:199], v[36:39]
	v_mfma_f32_16x16x32_bf16 v[32:35], v[172:175], v[196:199], v[32:35]
	v_mfma_f32_16x16x32_bf16 v[24:27], v[144:147], v[204:207], v[24:27]
	v_mfma_f32_16x16x32_bf16 v[16:19], v[172:175], v[204:207], v[16:19]
	v_mfma_f32_16x16x32_bf16 v[4:7], v[144:147], v[212:215], v[4:7]
	v_mfma_f32_16x16x32_bf16 v[0:3], v[172:175], v[212:215], v[0:3]
	v_mfma_f32_16x16x32_bf16 v[56:59], v[148:151], v[184:187], v[56:59]
	v_mfma_f32_16x16x32_bf16 v[48:51], v[176:179], v[184:187], v[48:51]
	v_mfma_f32_16x16x32_bf16 v[36:39], v[148:151], v[200:203], v[36:39]
	v_mfma_f32_16x16x32_bf16 v[32:35], v[176:179], v[200:203], v[32:35]
	v_mfma_f32_16x16x32_bf16 v[24:27], v[148:151], v[208:211], v[24:27]
	v_mfma_f32_16x16x32_bf16 v[16:19], v[176:179], v[208:211], v[16:19]
	v_mfma_f32_16x16x32_bf16 v[4:7], v[148:151], v[216:219], v[4:7]
	v_mfma_f32_16x16x32_bf16 v[0:3], v[176:179], v[216:219], v[0:3]
	s_setprio 0
	s_barrier
	s_add_i32 s57, s57, 2
	s_add_u32 s24, s24, 0x100
	s_addc_u32 s25, s25, 0
	s_add_u32 s55, s55, 0x100
	s_addc_u32 s56, s56, 0
	s_cmp_gt_u32 s57, 13
	s_cbranch_scc0 .LBB0_969
	s_and_b64 vcc, exec, s[12:13]
	s_cbranch_vccz .LBB0_972
	s_barrier

; #define PG8_STAGE(bufoff, gbase, voff) do { _Pragma("unroll") for (int _i = 0; _i < 2; ++_i) \
;         __builtin_amdgcn_global_load_lds((const unsigned*)((const char*)(gbase) + (voff)[_i]), (PG8_LAS unsigned*)(lds + (bufoff) + ldsw + _i * 8192), 16, 0, 0); } while (0)
; #define PG8_LDA(dst, b, h) do { _Pragma("unroll") for (int m = 0; m < 4; ++m) _Pragma("unroll") for (int k = 0; k < 2; ++k) dst[m][k] = *(const PG8_LAS bf16x8*)(lds + PG8_SA(b, h) + aoff + m * 2048 + k * 1024); } while (0)
; #define PG8_LDB(dst, b, h) do { _Pragma("unroll") for (int n = 0; n < 2; ++n) _Pragma("unroll") for (int k = 0; k < 2; ++k) dst[n][k] = *(const PG8_LAS bf16x8*)(lds + PG8_SB(b, h) + boff + n * 2048 + k * 1024); } while (0)
; #define PG8_MMA(ai, bj, At, Bt) do { __builtin_amdgcn_s_setprio(1); _Pragma("unroll") for (int m = 0; m < 4; ++m) _Pragma("unroll") for (int n = 0; n < 2; ++n) _Pragma("unroll") for (int k = 0; k < 2; ++k) \
;         acc[ai][bj][m][n] = __builtin_amdgcn_mfma_f32_16x16x32_bf16(Bt[n][k], At[m][k], acc[ai][bj][m][n], 0, 0, 0); __builtin_amdgcn_s_setprio(0); } while (0)
; #define PG8_WAIT_V(n) asm volatile("s_waitcnt vmcnt(" #n ")" ::: "memory")
; #define PG8_WAIT_L(n) asm volatile("s_waitcnt lgkmcnt(" #n ")" ::: "memory")
; #define PG8_BAR __builtin_amdgcn_s_barrier()
; #define PG8_SCHED __builtin_amdgcn_sched_barrier(0)
; template <class Epi, class Sched, bool ALIGN_EPI = false, bool SP2 = false>
; __device__ __forceinline__ void gemm_phase(PG8_LAS unsigned char* lds, const Gemm g, const Sched& S, const Epi& E) {
;     ...
;             PG8_LDB(B0, 0, 0); PG8_LDB(B1, 0, 1); PG8_SCHED; PG8_LDA(At, 0, 0); PG8_STAGE(PG8_SA(1, 1), a1 + hstep, voffA);
;             PG8_WAIT_V(8); PG8_WAIT_L(0); PG8_BAR; PG8_MMA(0, 0, At, B0); PG8_MMA(0, 1, At, B1); PG8_BAR; PG8_SCHED;
;             PG8_LDA(At, 0, 1); PG8_STAGE(PG8_SB(0, 0), b2, voffB); PG8_STAGE(PG8_SB(0, 1), b2 + hstep, voffB); PG8_STAGE(PG8_SA(0, 0), a2, voffA);
;             PG8_WAIT_V(8); PG8_WAIT_L(0); PG8_BAR; PG8_MMA(1, 0, At, B0); PG8_MMA(1, 1, At, B1); PG8_BAR; PG8_SCHED;
.LBB0_1052:
	ds_read_b128 v[146:149], v153
	ds_read_b128 v[156:159], v153 offset:1024
	ds_read_b128 v[160:163], v153 offset:2048
	ds_read_b128 v[164:167], v153 offset:3072
	ds_read_b128 v[168:171], v154
	ds_read_b128 v[172:175], v154 offset:1024
	ds_read_b128 v[176:179], v154 offset:2048
	ds_read_b128 v[180:183], v154 offset:3072
	s_add_u32 s24, s22, 0x100
	s_addc_u32 s25, s23, 0
	s_cmp_eq_u32 s56, 40
	s_cselect_b32 s29, s3, s25
	s_cselect_b32 s28, s2, s24
	s_cselect_b32 s27, s21, s55
	s_cselect_b32 s26, s20, s54
	s_add_i32 m0, s38, 0xc000
	ds_read_b128 v[184:187], v155
	ds_read_b128 v[188:191], v155 offset:1024
	ds_read_b128 v[192:195], v155 offset:2048
	ds_read_b128 v[196:199], v155 offset:3072
	ds_read_b128 v[200:203], v155 offset:4096
	ds_read_b128 v[204:207], v155 offset:5120
	ds_read_b128 v[208:211], v155 offset:6144
	ds_read_b128 v[212:215], v155 offset:7168
	global_load_lds_dwordx4 v138, s[22:23]
	s_add_i32 m0, s38, 0xe000
	s_nop 0
	global_load_lds_dwordx4 v140, s[22:23]
	s_waitcnt vmcnt(8)
	s_waitcnt lgkmcnt(0)
	s_barrier
	s_setprio 1
	s_waitcnt lgkmcnt(0)
	v_mfma_f32_16x16x32_bf16 v[124:127], v[146:149], v[184:187], v[124:127]
	v_mfma_f32_16x16x32_bf16 v[120:123], v[160:163], v[184:187], v[120:123]
	v_mfma_f32_16x16x32_bf16 v[116:119], v[146:149], v[192:195], v[116:119]
	v_mfma_f32_16x16x32_bf16 v[112:115], v[160:163], v[192:195], v[112:115]
	v_mfma_f32_16x16x32_bf16 v[92:95], v[146:149], v[200:203], v[92:95]
	v_mfma_f32_16x16x32_bf16 v[88:91], v[160:163], v[200:203], v[88:91]
	v_mfma_f32_16x16x32_bf16 v[76:79], v[146:149], v[208:211], v[76:79]
	v_mfma_f32_16x16x32_bf16 v[72:75], v[160:163], v[208:211], v[72:75]
	v_mfma_f32_16x16x32_bf16 v[124:127], v[156:159], v[188:191], v[124:127]
	v_mfma_f32_16x16x32_bf16 v[120:123], v[164:167], v[188:191], v[120:123]
	v_mfma_f32_16x16x32_bf16 v[116:119], v[156:159], v[196:199], v[116:119]
	v_mfma_f32_16x16x32_bf16 v[112:115], v[164:167], v[196:199], v[112:115]
	v_mfma_f32_16x16x32_bf16 v[92:95], v[156:159], v[204:207], v[92:95]
	v_mfma_f32_16x16x32_bf16 v[88:91], v[164:167], v[204:207], v[88:91]
	v_mfma_f32_16x16x32_bf16 v[76:79], v[156:159], v[212:215], v[76:79]
	v_mfma_f32_16x16x32_bf16 v[72:75], v[164:167], v[212:215], v[72:75]
	s_setprio 0
	s_setprio 1
	v_mfma_f32_16x16x32_bf16 v[108:111], v[168:171], v[184:187], v[108:111]
	v_mfma_f32_16x16x32_bf16 v[104:107], v[176:179], v[184:187], v[104:107]
	v_mfma_f32_16x16x32_bf16 v[100:103], v[168:171], v[192:195], v[100:103]
	v_mfma_f32_16x16x32_bf16 v[96:99], v[176:179], v[192:195], v[96:99]
	v_mfma_f32_16x16x32_bf16 v[84:87], v[168:171], v[200:203], v[84:87]
	v_mfma_f32_16x16x32_bf16 v[80:83], v[176:179], v[200:203], v[80:83]
	v_mfma_f32_16x16x32_bf16 v[68:71], v[168:171], v[208:211], v[68:71]
	v_mfma_f32_16x16x32_bf16 v[64:67], v[176:179], v[208:211], v[64:67]
	v_mfma_f32_16x16x32_bf16 v[108:111], v[172:175], v[188:191], v[108:111]
	v_mfma_f32_16x16x32_bf16 v[104:107], v[180:183], v[188:191], v[104:107]
	v_mfma_f32_16x16x32_bf16 v[100:103], v[172:175], v[196:199], v[100:103]
	v_mfma_f32_16x16x32_bf16 v[96:99], v[180:183], v[196:199], v[96:99]
	v_mfma_f32_16x16x32_bf16 v[84:87], v[172:175], v[204:207], v[84:87]
	v_mfma_f32_16x16x32_bf16 v[80:83], v[180:183], v[204:207], v[80:83]
	v_mfma_f32_16x16x32_bf16 v[68:71], v[172:175], v[212:215], v[68:71]
	v_mfma_f32_16x16x32_bf16 v[64:67], v[180:183], v[212:215], v[64:67]
	s_setprio 0
	s_barrier
	s_add_i32 s22, s46, s37
	v_lshl_add_u64 v[150:151], s[26:27], 0, v[130:131]
	s_mov_b32 m0, s22
	ds_read_b128 v[184:187], v155 offset:16384
	ds_read_b128 v[188:191], v155 offset:17408
	ds_read_b128 v[192:195], v155 offset:18432
	ds_read_b128 v[196:199], v155 offset:19456
	ds_read_b128 v[200:203], v155 offset:20480
	ds_read_b128 v[204:207], v155 offset:21504
	ds_read_b128 v[208:211], v155 offset:22528
	ds_read_b128 v[212:215], v155 offset:23552
	global_load_lds_dwordx4 v[150:151], off
	s_add_i32 m0, s22, 0x2000
	s_add_u32 s22, s26, 0xb0000
	v_lshl_add_u64 v[216:217], s[26:27], 0, v[134:135]
	s_addc_u32 s23, s27, 0
	s_add_i32 s57, s47, s37
	global_load_lds_dwordx4 v[216:217], off
	s_mov_b32 m0, s57
	v_lshl_add_u64 v[220:221], s[28:29], 0, v[132:133]
	global_load_lds_dwordx4 v130, s[22:23]
	s_add_i32 m0, s57, 0x2000
	s_nop 0
	global_load_lds_dwordx4 v134, s[22:23]
	v_lshl_add_u64 v[218:219], s[28:29], 0, v[128:129]
	s_mov_b32 m0, s38
	s_nop 0
	global_load_lds_dwordx4 v[218:219], off
	s_mov_b32 m0, s39
	s_nop 0
	global_load_lds_dwordx4 v[220:221], off
	s_waitcnt vmcnt(8)
	s_waitcnt lgkmcnt(0)
	s_barrier
; #define PG8_STAGE(bufoff, gbase, voff) do { _Pragma("unroll") for (int _i = 0; _i < 2; ++_i) \
;         __builtin_amdgcn_global_load_lds((const unsigned*)((const char*)(gbase) + (voff)[_i]), (PG8_LAS unsigned*)(lds + (bufoff) + ldsw + _i * 8192), 16, 0, 0); } while (0)
; #define PG8_LDA(dst, b, h) do { _Pragma("unroll") for (int m = 0; m < 4; ++m) _Pragma("unroll") for (int k = 0; k < 2; ++k) dst[m][k] = *(const PG8_LAS bf16x8*)(lds + PG8_SA(b, h) + aoff + m * 2048 + k * 1024); } while (0)
; #define PG8_LDB(dst, b, h) do { _Pragma("unroll") for (int n = 0; n < 2; ++n) _Pragma("unroll") for (int k = 0; k < 2; ++k) dst[n][k] = *(const PG8_LAS bf16x8*)(lds + PG8_SB(b, h) + boff + n * 2048 + k * 1024); } while (0)
; #define PG8_MMA(ai, bj, At, Bt) do { __builtin_amdgcn_s_setprio(1); _Pragma("unroll") for (int m = 0; m < 4; ++m) _Pragma("unroll") for (int n = 0; n < 2; ++n) _Pragma("unroll") for (int k = 0; k < 2; ++k) \
;         acc[ai][bj][m][n] = __builtin_amdgcn_mfma_f32_16x16x32_bf16(Bt[n][k], At[m][k], acc[ai][bj][m][n], 0, 0, 0); __builtin_amdgcn_s_setprio(0); } while (0)
; #define PG8_WAIT_V(n) asm volatile("s_waitcnt vmcnt(" #n ")" ::: "memory")
; #define PG8_WAIT_L(n) asm volatile("s_waitcnt lgkmcnt(" #n ")" ::: "memory")
; #define PG8_BAR __builtin_amdgcn_s_barrier()
; #define PG8_SCHED __builtin_amdgcn_sched_barrier(0)
; template <class Epi, class Sched, bool ALIGN_EPI = false, bool SP2 = false>
; __device__ __forceinline__ void gemm_phase(PG8_LAS unsigned char* lds, const Gemm g, const Sched& S, const Epi& E) {
;     ...
;             PG8_WAIT_V(8); PG8_WAIT_L(0); PG8_BAR; PG8_MMA(1, 0, At, B0); PG8_MMA(1, 1, At, B1); PG8_BAR; PG8_SCHED;
;             PG8_LDB(B0, 1, 0); PG8_LDB(B1, 1, 1); PG8_SCHED; PG8_LDA(At, 1, 0); PG8_STAGE(PG8_SA(0, 1), a2 + hstep, voffA);
;             PG8_WAIT_V(8); PG8_WAIT_L(0); PG8_BAR; PG8_MMA(0, 0, At, B0); PG8_MMA(0, 1, At, B1); PG8_BAR; PG8_SCHED;
;             PG8_LDA(At, 1, 1); PG8_STAGE(PG8_SB(1, 0), b3, voffB); PG8_STAGE(PG8_SB(1, 1), b3 + hstep, voffB); PG8_STAGE(PG8_SA(1, 0), a3, voffA);
	s_setprio 1
	s_waitcnt lgkmcnt(0)
	v_mfma_f32_16x16x32_bf16 v[60:63], v[146:149], v[184:187], v[60:63]
	v_mfma_f32_16x16x32_bf16 v[56:59], v[160:163], v[184:187], v[56:59]
	v_mfma_f32_16x16x32_bf16 v[44:47], v[146:149], v[192:195], v[44:47]
	v_mfma_f32_16x16x32_bf16 v[40:43], v[160:163], v[192:195], v[40:43]
	v_mfma_f32_16x16x32_bf16 v[28:31], v[146:149], v[200:203], v[28:31]
	v_mfma_f32_16x16x32_bf16 v[24:27], v[160:163], v[200:203], v[24:27]
	v_mfma_f32_16x16x32_bf16 v[12:15], v[146:149], v[208:211], v[12:15]
	v_mfma_f32_16x16x32_bf16 v[8:11], v[160:163], v[208:211], v[8:11]
	v_mfma_f32_16x16x32_bf16 v[60:63], v[156:159], v[188:191], v[60:63]
	v_mfma_f32_16x16x32_bf16 v[56:59], v[164:167], v[188:191], v[56:59]
	v_mfma_f32_16x16x32_bf16 v[44:47], v[156:159], v[196:199], v[44:47]
	v_mfma_f32_16x16x32_bf16 v[40:43], v[164:167], v[196:199], v[40:43]
	v_mfma_f32_16x16x32_bf16 v[28:31], v[156:159], v[204:207], v[28:31]
	v_mfma_f32_16x16x32_bf16 v[24:27], v[164:167], v[204:207], v[24:27]
	v_mfma_f32_16x16x32_bf16 v[12:15], v[156:159], v[212:215], v[12:15]
	v_mfma_f32_16x16x32_bf16 v[8:11], v[164:167], v[212:215], v[8:11]
	s_setprio 0
	s_setprio 1
	v_mfma_f32_16x16x32_bf16 v[52:55], v[168:171], v[184:187], v[52:55]
	v_mfma_f32_16x16x32_bf16 v[48:51], v[176:179], v[184:187], v[48:51]
	v_mfma_f32_16x16x32_bf16 v[36:39], v[168:171], v[192:195], v[36:39]
	v_mfma_f32_16x16x32_bf16 v[32:35], v[176:179], v[192:195], v[32:35]
	v_mfma_f32_16x16x32_bf16 v[20:23], v[168:171], v[200:203], v[20:23]
	v_mfma_f32_16x16x32_bf16 v[16:19], v[176:179], v[200:203], v[16:19]
	v_mfma_f32_16x16x32_bf16 v[4:7], v[168:171], v[208:211], v[4:7]
	v_mfma_f32_16x16x32_bf16 v[0:3], v[176:179], v[208:211], v[0:3]
	v_mfma_f32_16x16x32_bf16 v[52:55], v[172:175], v[188:191], v[52:55]
	v_mfma_f32_16x16x32_bf16 v[48:51], v[180:183], v[188:191], v[48:51]
	v_mfma_f32_16x16x32_bf16 v[36:39], v[172:175], v[196:199], v[36:39]
	v_mfma_f32_16x16x32_bf16 v[32:35], v[180:183], v[196:199], v[32:35]
	v_mfma_f32_16x16x32_bf16 v[20:23], v[172:175], v[204:207], v[20:23]
	v_mfma_f32_16x16x32_bf16 v[16:19], v[180:183], v[204:207], v[16:19]
	v_mfma_f32_16x16x32_bf16 v[4:7], v[172:175], v[212:215], v[4:7]
	v_mfma_f32_16x16x32_bf16 v[0:3], v[180:183], v[212:215], v[0:3]
	s_setprio 0
	s_barrier
	s_add_i32 s57, 0, 0x18000
	s_add_i32 s58, 0, 0x1c000
	v_add_u32_e32 v164, s57, v152
	v_add_u32_e32 v180, s58, v152
	ds_read_b128 v[146:149], v164
	ds_read_b128 v[156:159], v164 offset:1024
	ds_read_b128 v[160:163], v164 offset:2048
	ds_read_b128 v[164:167], v164 offset:3072
	ds_read_b128 v[168:171], v180
	ds_read_b128 v[172:175], v180 offset:1024
	ds_read_b128 v[176:179], v180 offset:2048
	ds_read_b128 v[180:183], v180 offset:3072
	s_add_u32 s22, s28, 0xb0000
	s_addc_u32 s23, s29, 0
	s_mov_b32 m0, s40
	ds_read_b128 v[184:187], v155 offset:32768
	ds_read_b128 v[188:191], v155 offset:33792
	ds_read_b128 v[192:195], v155 offset:34816
	ds_read_b128 v[196:199], v155 offset:35840
	ds_read_b128 v[200:203], v155 offset:36864
	ds_read_b128 v[204:207], v155 offset:37888
	ds_read_b128 v[208:211], v155 offset:38912
	ds_read_b128 v[212:215], v155 offset:39936
	global_load_lds_dwordx4 v128, s[22:23]
	s_mov_b32 m0, s41
	s_nop 0
	global_load_lds_dwordx4 v132, s[22:23]
	s_waitcnt vmcnt(8)
	s_waitcnt lgkmcnt(0)
	s_barrier
	s_setprio 1
	s_waitcnt lgkmcnt(0)
	v_mfma_f32_16x16x32_bf16 v[124:127], v[146:149], v[184:187], v[124:127]
	v_mfma_f32_16x16x32_bf16 v[120:123], v[160:163], v[184:187], v[120:123]
	v_mfma_f32_16x16x32_bf16 v[116:119], v[146:149], v[192:195], v[116:119]
	v_mfma_f32_16x16x32_bf16 v[112:115], v[160:163], v[192:195], v[112:115]
	v_mfma_f32_16x16x32_bf16 v[92:95], v[146:149], v[200:203], v[92:95]
	v_mfma_f32_16x16x32_bf16 v[88:91], v[160:163], v[200:203], v[88:91]
	v_mfma_f32_16x16x32_bf16 v[76:79], v[146:149], v[208:211], v[76:79]
	v_mfma_f32_16x16x32_bf16 v[72:75], v[160:163], v[208:211], v[72:75]
	v_mfma_f32_16x16x32_bf16 v[124:127], v[156:159], v[188:191], v[124:127]
	v_mfma_f32_16x16x32_bf16 v[120:123], v[164:167], v[188:191], v[120:123]
	v_mfma_f32_16x16x32_bf16 v[116:119], v[156:159], v[196:199], v[116:119]
	v_mfma_f32_16x16x32_bf16 v[112:115], v[164:167], v[196:199], v[112:115]
	v_mfma_f32_16x16x32_bf16 v[92:95], v[156:159], v[204:207], v[92:95]
	v_mfma_f32_16x16x32_bf16 v[88:91], v[164:167], v[204:207], v[88:91]
	v_mfma_f32_16x16x32_bf16 v[76:79], v[156:159], v[212:215], v[76:79]
	v_mfma_f32_16x16x32_bf16 v[72:75], v[164:167], v[212:215], v[72:75]
	s_setprio 0
	s_setprio 1
	v_mfma_f32_16x16x32_bf16 v[108:111], v[168:171], v[184:187], v[108:111]
	v_mfma_f32_16x16x32_bf16 v[104:107], v[176:179], v[184:187], v[104:107]
	v_mfma_f32_16x16x32_bf16 v[100:103], v[168:171], v[192:195], v[100:103]
	v_mfma_f32_16x16x32_bf16 v[96:99], v[176:179], v[192:195], v[96:99]
	v_mfma_f32_16x16x32_bf16 v[84:87], v[168:171], v[200:203], v[84:87]
	v_mfma_f32_16x16x32_bf16 v[80:83], v[176:179], v[200:203], v[80:83]
	v_mfma_f32_16x16x32_bf16 v[68:71], v[168:171], v[208:211], v[68:71]
	v_mfma_f32_16x16x32_bf16 v[64:67], v[176:179], v[208:211], v[64:67]
	v_mfma_f32_16x16x32_bf16 v[108:111], v[172:175], v[188:191], v[108:111]
	v_mfma_f32_16x16x32_bf16 v[104:107], v[180:183], v[188:191], v[104:107]
	v_mfma_f32_16x16x32_bf16 v[100:103], v[172:175], v[196:199], v[100:103]
	v_mfma_f32_16x16x32_bf16 v[96:99], v[180:183], v[196:199], v[96:99]
	v_mfma_f32_16x16x32_bf16 v[84:87], v[172:175], v[204:207], v[84:87]
	v_mfma_f32_16x16x32_bf16 v[80:83], v[180:183], v[204:207], v[80:83]
	v_mfma_f32_16x16x32_bf16 v[68:71], v[172:175], v[212:215], v[68:71]
	v_mfma_f32_16x16x32_bf16 v[64:67], v[180:183], v[212:215], v[64:67]
	s_setprio 0
	s_barrier
; #define PG8_STAGE(bufoff, gbase, voff) do { _Pragma("unroll") for (int _i = 0; _i < 2; ++_i) \
;         __builtin_amdgcn_global_load_lds((const unsigned*)((const char*)(gbase) + (voff)[_i]), (PG8_LAS unsigned*)(lds + (bufoff) + ldsw + _i * 8192), 16, 0, 0); } while (0)
; #define PG8_LDA(dst, b, h) do { _Pragma("unroll") for (int m = 0; m < 4; ++m) _Pragma("unroll") for (int k = 0; k < 2; ++k) dst[m][k] = *(const PG8_LAS bf16x8*)(lds + PG8_SA(b, h) + aoff + m * 2048 + k * 1024); } while (0)
; #define PG8_MMA(ai, bj, At, Bt) do { __builtin_amdgcn_s_setprio(1); _Pragma("unroll") for (int m = 0; m < 4; ++m) _Pragma("unroll") for (int n = 0; n < 2; ++n) _Pragma("unroll") for (int k = 0; k < 2; ++k) \
;         acc[ai][bj][m][n] = __builtin_amdgcn_mfma_f32_16x16x32_bf16(Bt[n][k], At[m][k], acc[ai][bj][m][n], 0, 0, 0); __builtin_amdgcn_s_setprio(0); } while (0)
; #define PG8_WAIT_V(n) asm volatile("s_waitcnt vmcnt(" #n ")" ::: "memory")
; #define PG8_WAIT_L(n) asm volatile("s_waitcnt lgkmcnt(" #n ")" ::: "memory")
; #define PG8_BAR __builtin_amdgcn_s_barrier()
; #define PG8_SCHED __builtin_amdgcn_sched_barrier(0)
; template <class Epi, class Sched, bool ALIGN_EPI = false, bool SP2 = false>
; __device__ __forceinline__ void gemm_phase(PG8_LAS unsigned char* lds, const Gemm g, const Sched& S, const Epi& E) {
;     ...
;             PG8_LDA(At, 1, 1); PG8_STAGE(PG8_SB(1, 0), b3, voffB); PG8_STAGE(PG8_SB(1, 1), b3 + hstep, voffB); PG8_STAGE(PG8_SA(1, 0), a3, voffA);
;             PG8_WAIT_V(8); PG8_WAIT_L(0); PG8_BAR; PG8_MMA(1, 0, At, B0); PG8_MMA(1, 1, At, B1); PG8_BAR; PG8_SCHED;
	s_add_i32 s22, s57, s37
	v_lshl_add_u64 v[150:151], v[150:151], 0, s[8:9]
	s_mov_b32 m0, s22
	ds_read_b128 v[184:187], v155 offset:49152
	ds_read_b128 v[188:191], v155 offset:50176
	ds_read_b128 v[192:195], v155 offset:51200
	ds_read_b128 v[196:199], v155 offset:52224
	ds_read_b128 v[200:203], v155 offset:53248
	ds_read_b128 v[204:207], v155 offset:54272
	ds_read_b128 v[208:211], v155 offset:55296
	ds_read_b128 v[212:215], v155 offset:56320
	global_load_lds_dwordx4 v[150:151], off
	s_add_i32 m0, s22, 0x2000
	s_add_u32 s22, s26, 0xb0080
	v_lshl_add_u64 v[150:151], v[216:217], 0, s[8:9]
	s_addc_u32 s23, s27, 0
	s_add_i32 s26, s58, s37
	global_load_lds_dwordx4 v[150:151], off
	s_mov_b32 m0, s26
	s_nop 0
	global_load_lds_dwordx4 v130, s[22:23]
	s_add_i32 m0, s26, 0x2000
	s_nop 0
	global_load_lds_dwordx4 v134, s[22:23]
	v_lshl_add_u64 v[150:151], v[218:219], 0, s[8:9]
	s_mov_b32 m0, s43
	s_nop 0
	global_load_lds_dwordx4 v[150:151], off
	v_lshl_add_u64 v[150:151], v[220:221], 0, s[8:9]
	s_mov_b32 m0, s44
	s_nop 0
	global_load_lds_dwordx4 v[150:151], off
	s_waitcnt vmcnt(8)
	s_waitcnt lgkmcnt(0)
	s_barrier
	s_setprio 1
	s_waitcnt lgkmcnt(0)
	v_mfma_f32_16x16x32_bf16 v[60:63], v[146:149], v[184:187], v[60:63]
	v_mfma_f32_16x16x32_bf16 v[56:59], v[160:163], v[184:187], v[56:59]
	v_mfma_f32_16x16x32_bf16 v[44:47], v[146:149], v[192:195], v[44:47]
	v_mfma_f32_16x16x32_bf16 v[40:43], v[160:163], v[192:195], v[40:43]
	v_mfma_f32_16x16x32_bf16 v[28:31], v[146:149], v[200:203], v[28:31]
	v_mfma_f32_16x16x32_bf16 v[24:27], v[160:163], v[200:203], v[24:27]
	v_mfma_f32_16x16x32_bf16 v[12:15], v[146:149], v[208:211], v[12:15]
	v_mfma_f32_16x16x32_bf16 v[8:11], v[160:163], v[208:211], v[8:11]
	v_mfma_f32_16x16x32_bf16 v[60:63], v[156:159], v[188:191], v[60:63]
	v_mfma_f32_16x16x32_bf16 v[56:59], v[164:167], v[188:191], v[56:59]
	v_mfma_f32_16x16x32_bf16 v[44:47], v[156:159], v[196:199], v[44:47]
	v_mfma_f32_16x16x32_bf16 v[40:43], v[164:167], v[196:199], v[40:43]
	v_mfma_f32_16x16x32_bf16 v[28:31], v[156:159], v[204:207], v[28:31]
	v_mfma_f32_16x16x32_bf16 v[24:27], v[164:167], v[204:207], v[24:27]
	v_mfma_f32_16x16x32_bf16 v[12:15], v[156:159], v[212:215], v[12:15]
	v_mfma_f32_16x16x32_bf16 v[8:11], v[164:167], v[212:215], v[8:11]
	s_setprio 0
	s_setprio 1
	v_mfma_f32_16x16x32_bf16 v[52:55], v[168:171], v[184:187], v[52:55]
	v_mfma_f32_16x16x32_bf16 v[48:51], v[176:179], v[184:187], v[48:51]
	v_mfma_f32_16x16x32_bf16 v[36:39], v[168:171], v[192:195], v[36:39]
	v_mfma_f32_16x16x32_bf16 v[32:35], v[176:179], v[192:195], v[32:35]
	v_mfma_f32_16x16x32_bf16 v[20:23], v[168:171], v[200:203], v[20:23]
	v_mfma_f32_16x16x32_bf16 v[16:19], v[176:179], v[200:203], v[16:19]
	v_mfma_f32_16x16x32_bf16 v[4:7], v[168:171], v[208:211], v[4:7]
	v_mfma_f32_16x16x32_bf16 v[0:3], v[176:179], v[208:211], v[0:3]
	v_mfma_f32_16x16x32_bf16 v[52:55], v[172:175], v[188:191], v[52:55]
	v_mfma_f32_16x16x32_bf16 v[48:51], v[180:183], v[188:191], v[48:51]
	v_mfma_f32_16x16x32_bf16 v[36:39], v[172:175], v[196:199], v[36:39]
	v_mfma_f32_16x16x32_bf16 v[32:35], v[180:183], v[196:199], v[32:35]
	v_mfma_f32_16x16x32_bf16 v[20:23], v[172:175], v[204:207], v[20:23]
	v_mfma_f32_16x16x32_bf16 v[16:19], v[180:183], v[204:207], v[16:19]
	v_mfma_f32_16x16x32_bf16 v[4:7], v[172:175], v[212:215], v[4:7]
	v_mfma_f32_16x16x32_bf16 v[0:3], v[180:183], v[212:215], v[0:3]
	s_setprio 0
	s_barrier
	s_add_i32 s56, s56, 2
	s_add_u32 s54, s54, 0x100
	s_addc_u32 s55, s55, 0
	s_cmp_gt_u32 s56, 41
	s_mov_b64 s[22:23], s[24:25]
	s_cbranch_scc0 .LBB0_1052
	s_and_b64 vcc, exec, s[10:11]
	s_cbranch_vccz .LBB0_1055
	s_barrier
